# GEMM K-loops: removed the s_setprio 0 / s_setprio 1 pair between the two 16-MFMA groups of each phase (priority stays raised through all 32 MFMAs)
# speedup vs baseline: 1.0062x; 1.0051x over previous
; #define PG8_STAGE(bufoff, gbase, voff) do { _Pragma("unroll") for (int _i = 0; _i < 2; ++_i) \
;         __builtin_amdgcn_global_load_lds((const unsigned*)((const char*)(gbase) + (voff)[_i]), (PG8_LAS unsigned*)(lds + (bufoff) + ldsw + _i * 8192), 16, 0, 0); } while (0)
; #define PG8_LDA(dst, b, h) do { _Pragma("unroll") for (int m = 0; m < 4; ++m) _Pragma("unroll") for (int k = 0; k < 2; ++k) dst[m][k] = *(const PG8_LAS bf16x8*)(lds + PG8_SA(b, h) + aoff + m * 2048 + k * 1024); } while (0)
; #define PG8_LDB(dst, b, h) do { _Pragma("unroll") for (int n = 0; n < 2; ++n) _Pragma("unroll") for (int k = 0; k < 2; ++k) dst[n][k] = *(const PG8_LAS bf16x8*)(lds + PG8_SB(b, h) + boff + n * 2048 + k * 1024); } while (0)
; #define PG8_WAIT_V(n) asm volatile("s_waitcnt vmcnt(" #n ")" ::: "memory")
; #define PG8_WAIT_L(n) asm volatile("s_waitcnt lgkmcnt(" #n ")" ::: "memory")
; #define PG8_BAR __builtin_amdgcn_s_barrier()
; #define PG8_SCHED __builtin_amdgcn_sched_barrier(0)
; template <class Epi, bool ALIGN_EPI = true>
; __device__ __forceinline__ void gemm_phase(PG8_LAS unsigned char* lds, const Gemm g, const StaticOrder& S, const Epi& E) {
;     ...
;             PG8_LDB(B0, 0, 0); PG8_LDB(B1, 0, 1); PG8_SCHED; PG8_LDA(At, 0, 0); PG8_STAGE(PG8_SA(1, 1), a1 + hstepA, voffA);
;             PG8_WAIT_V(8); PG8_WAIT_L(0); PG8_BAR; PG8_MMA(0, 0, At, B0); PG8_MMA(0, 1, At, B1); PG8_BAR; PG8_SCHED;
;             PG8_LDA(At, 0, 1); PG8_STAGE(PG8_SB(0, 0), b2, voffB); PG8_STAGE(PG8_SB(0, 1), b2 + hstepB, voffB); PG8_STAGE(PG8_SA(0, 0), a2, voffA);
.Lrot_439:
	ds_read_b128 v[142:145], v32
	ds_read_b128 v[148:151], v32 offset:1024
	ds_read_b128 v[158:161], v32 offset:2048
	ds_read_b128 v[168:171], v32 offset:3072
	v_add_u32_e32 v32, s56, v164
	ds_read_b128 v[172:175], v32
	ds_read_b128 v[176:179], v32 offset:1024
	ds_read_b128 v[180:183], v32 offset:2048
	ds_read_b128 v[184:187], v32 offset:3072
	v_lshl_add_u64 v[146:147], s[8:9], 0, v[138:139]
	s_add_i32 m0, s41, 0xc000
	ds_read_b128 v[188:191], v166
	ds_read_b128 v[192:195], v166 offset:1024
	ds_read_b128 v[196:199], v166 offset:2048
	ds_read_b128 v[208:211], v166 offset:3072
	ds_read_b128 v[216:219], v166 offset:4096
	ds_read_b128 v[220:223], v166 offset:5120
	ds_read_b128 v[224:227], v166 offset:6144
	ds_read_b128 v[228:231], v166 offset:7168
	global_load_lds_dwordx4 v[146:147], off
	v_lshl_add_u64 v[146:147], s[8:9], 0, v[140:141]
	s_add_i32 m0, s41, 0xe000
	s_nop 0
	global_load_lds_dwordx4 v[146:147], off
	s_waitcnt vmcnt(8)
	s_waitcnt lgkmcnt(0)
	s_barrier
	s_setprio 1
	s_waitcnt lgkmcnt(0)
	v_mfma_f32_16x16x32_bf16 v[126:129], v[142:145], v[188:191], v[126:129]
	v_mfma_f32_16x16x32_bf16 v[122:125], v[158:161], v[188:191], v[122:125]
	v_mfma_f32_16x16x32_bf16 v[110:113], v[142:145], v[196:199], v[110:113]
	v_mfma_f32_16x16x32_bf16 v[106:109], v[158:161], v[196:199], v[106:109]
	v_mfma_f32_16x16x32_bf16 v[94:97], v[142:145], v[216:219], v[94:97]
	v_mfma_f32_16x16x32_bf16 v[90:93], v[158:161], v[216:219], v[90:93]
	v_mfma_f32_16x16x32_bf16 v[78:81], v[142:145], v[224:227], v[78:81]
	v_mfma_f32_16x16x32_bf16 v[74:77], v[158:161], v[224:227], v[74:77]
	v_mfma_f32_16x16x32_bf16 v[126:129], v[148:151], v[192:195], v[126:129]
	v_mfma_f32_16x16x32_bf16 v[122:125], v[168:171], v[192:195], v[122:125]
	v_mfma_f32_16x16x32_bf16 v[110:113], v[148:151], v[208:211], v[110:113]
	v_mfma_f32_16x16x32_bf16 v[106:109], v[168:171], v[208:211], v[106:109]
	v_mfma_f32_16x16x32_bf16 v[94:97], v[148:151], v[220:223], v[94:97]
	v_mfma_f32_16x16x32_bf16 v[90:93], v[168:171], v[220:223], v[90:93]
	v_mfma_f32_16x16x32_bf16 v[78:81], v[148:151], v[228:231], v[78:81]
	v_mfma_f32_16x16x32_bf16 v[74:77], v[168:171], v[228:231], v[74:77]
	v_mfma_f32_16x16x32_bf16 v[118:121], v[172:175], v[188:191], v[118:121]
	v_mfma_f32_16x16x32_bf16 v[114:117], v[180:183], v[188:191], v[114:117]
	v_mfma_f32_16x16x32_bf16 v[102:105], v[172:175], v[196:199], v[102:105]
	v_mfma_f32_16x16x32_bf16 v[98:101], v[180:183], v[196:199], v[98:101]
	v_mfma_f32_16x16x32_bf16 v[86:89], v[172:175], v[216:219], v[86:89]
	v_mfma_f32_16x16x32_bf16 v[82:85], v[180:183], v[216:219], v[82:85]
	v_mfma_f32_16x16x32_bf16 v[70:73], v[172:175], v[224:227], v[70:73]
	v_mfma_f32_16x16x32_bf16 v[66:69], v[180:183], v[224:227], v[66:69]
	v_mfma_f32_16x16x32_bf16 v[118:121], v[176:179], v[192:195], v[118:121]
	v_mfma_f32_16x16x32_bf16 v[114:117], v[184:187], v[192:195], v[114:117]
	v_mfma_f32_16x16x32_bf16 v[102:105], v[176:179], v[208:211], v[102:105]
	v_mfma_f32_16x16x32_bf16 v[98:101], v[184:187], v[208:211], v[98:101]
	v_mfma_f32_16x16x32_bf16 v[86:89], v[176:179], v[220:223], v[86:89]
	v_mfma_f32_16x16x32_bf16 v[82:85], v[184:187], v[220:223], v[82:85]
	v_mfma_f32_16x16x32_bf16 v[70:73], v[176:179], v[228:231], v[70:73]
	v_mfma_f32_16x16x32_bf16 v[66:69], v[184:187], v[228:231], v[66:69]
	s_setprio 0
	s_barrier
	s_add_i32 s53, s53, s40
	v_lshl_add_u64 v[146:147], s[28:29], 0, v[132:133]
	s_mov_b32 m0, s53
	ds_read_b128 v[188:191], v166 offset:16384
	ds_read_b128 v[192:195], v166 offset:17408
	ds_read_b128 v[196:199], v166 offset:18432
	ds_read_b128 v[208:211], v166 offset:19456
	ds_read_b128 v[216:219], v166 offset:20480
	ds_read_b128 v[220:223], v166 offset:21504
	ds_read_b128 v[224:227], v166 offset:22528
	ds_read_b128 v[228:231], v166 offset:23552
	global_load_lds_dwordx4 v[146:147], off
	s_add_i32 m0, s53, 0x2000
	s_add_u32 s58, s28, 0x40000
	v_lshl_add_u64 v[200:201], s[28:29], 0, v[136:137]
	s_addc_u32 s59, s29, 0
	s_add_i32 s53, s56, s40
	global_load_lds_dwordx4 v[200:201], off
	v_lshl_add_u64 v[204:205], s[58:59], 0, v[132:133]
	s_mov_b32 m0, s53
	v_lshl_add_u64 v[206:207], s[30:31], 0, v[134:135]
	global_load_lds_dwordx4 v[204:205], off
	v_lshl_add_u64 v[204:205], s[58:59], 0, v[136:137]
	s_add_i32 m0, s53, 0x2000
	s_nop 0
	global_load_lds_dwordx4 v[204:205], off
	v_lshl_add_u64 v[204:205], s[30:31], 0, v[130:131]
	s_mov_b32 m0, s41
	s_nop 0
	global_load_lds_dwordx4 v[204:205], off
	s_mov_b32 m0, s42
	s_nop 0
	global_load_lds_dwordx4 v[206:207], off
	s_waitcnt vmcnt(8)
	s_waitcnt lgkmcnt(0)
	s_barrier
; #define PG8_STAGE(bufoff, gbase, voff) do { _Pragma("unroll") for (int _i = 0; _i < 2; ++_i) \
;         __builtin_amdgcn_global_load_lds((const unsigned*)((const char*)(gbase) + (voff)[_i]), (PG8_LAS unsigned*)(lds + (bufoff) + ldsw + _i * 8192), 16, 0, 0); } while (0)
; #define PG8_LDA(dst, b, h) do { _Pragma("unroll") for (int m = 0; m < 4; ++m) _Pragma("unroll") for (int k = 0; k < 2; ++k) dst[m][k] = *(const PG8_LAS bf16x8*)(lds + PG8_SA(b, h) + aoff + m * 2048 + k * 1024); } while (0)
; #define PG8_LDB(dst, b, h) do { _Pragma("unroll") for (int n = 0; n < 2; ++n) _Pragma("unroll") for (int k = 0; k < 2; ++k) dst[n][k] = *(const PG8_LAS bf16x8*)(lds + PG8_SB(b, h) + boff + n * 2048 + k * 1024); } while (0)
; #define PG8_WAIT_V(n) asm volatile("s_waitcnt vmcnt(" #n ")" ::: "memory")
; #define PG8_WAIT_L(n) asm volatile("s_waitcnt lgkmcnt(" #n ")" ::: "memory")
; #define PG8_BAR __builtin_amdgcn_s_barrier()
; #define PG8_SCHED __builtin_amdgcn_sched_barrier(0)
; template <class Epi, bool ALIGN_EPI = true>
; __device__ __forceinline__ void gemm_phase(PG8_LAS unsigned char* lds, const Gemm g, const StaticOrder& S, const Epi& E) {
;     ...
;             PG8_WAIT_V(8); PG8_WAIT_L(0); PG8_BAR; PG8_MMA(1, 0, At, B0); PG8_MMA(1, 1, At, B1); PG8_BAR; PG8_SCHED;
;             PG8_LDB(B0, 1, 0); PG8_LDB(B1, 1, 1); PG8_SCHED; PG8_LDA(At, 1, 0); PG8_STAGE(PG8_SA(0, 1), a2 + hstepA, voffA);
;             PG8_WAIT_V(8); PG8_WAIT_L(0); PG8_BAR; PG8_MMA(0, 0, At, B0); PG8_MMA(0, 1, At, B1); PG8_BAR; PG8_SCHED;
	s_setprio 1
	s_waitcnt lgkmcnt(0)
	v_mfma_f32_16x16x32_bf16 v[62:65], v[142:145], v[188:191], v[62:65]
	v_mfma_f32_16x16x32_bf16 v[58:61], v[158:161], v[188:191], v[58:61]
	v_mfma_f32_16x16x32_bf16 v[46:49], v[142:145], v[196:199], v[46:49]
	v_mfma_f32_16x16x32_bf16 v[42:45], v[158:161], v[196:199], v[42:45]
	v_mfma_f32_16x16x32_bf16 v[28:31], v[142:145], v[216:219], v[28:31]
	v_mfma_f32_16x16x32_bf16 v[24:27], v[158:161], v[216:219], v[24:27]
	v_mfma_f32_16x16x32_bf16 v[12:15], v[142:145], v[224:227], v[12:15]
	v_mfma_f32_16x16x32_bf16 v[8:11], v[158:161], v[224:227], v[8:11]
	v_mfma_f32_16x16x32_bf16 v[62:65], v[148:151], v[192:195], v[62:65]
	v_mfma_f32_16x16x32_bf16 v[58:61], v[168:171], v[192:195], v[58:61]
	v_mfma_f32_16x16x32_bf16 v[46:49], v[148:151], v[208:211], v[46:49]
	v_mfma_f32_16x16x32_bf16 v[42:45], v[168:171], v[208:211], v[42:45]
	v_mfma_f32_16x16x32_bf16 v[28:31], v[148:151], v[220:223], v[28:31]
	v_mfma_f32_16x16x32_bf16 v[24:27], v[168:171], v[220:223], v[24:27]
	v_mfma_f32_16x16x32_bf16 v[12:15], v[148:151], v[228:231], v[12:15]
	v_mfma_f32_16x16x32_bf16 v[8:11], v[168:171], v[228:231], v[8:11]
	v_mfma_f32_16x16x32_bf16 v[54:57], v[172:175], v[188:191], v[54:57]
	v_mfma_f32_16x16x32_bf16 v[50:53], v[180:183], v[188:191], v[50:53]
	v_mfma_f32_16x16x32_bf16 v[38:41], v[172:175], v[196:199], v[38:41]
	v_mfma_f32_16x16x32_bf16 v[34:37], v[180:183], v[196:199], v[34:37]
	v_mfma_f32_16x16x32_bf16 v[20:23], v[172:175], v[216:219], v[20:23]
	v_mfma_f32_16x16x32_bf16 v[16:19], v[180:183], v[216:219], v[16:19]
	v_mfma_f32_16x16x32_bf16 v[4:7], v[172:175], v[224:227], v[4:7]
	v_mfma_f32_16x16x32_bf16 v[0:3], v[180:183], v[224:227], v[0:3]
	v_mfma_f32_16x16x32_bf16 v[54:57], v[176:179], v[192:195], v[54:57]
	v_mfma_f32_16x16x32_bf16 v[50:53], v[184:187], v[192:195], v[50:53]
	v_mfma_f32_16x16x32_bf16 v[38:41], v[176:179], v[208:211], v[38:41]
	v_mfma_f32_16x16x32_bf16 v[34:37], v[184:187], v[208:211], v[34:37]
	v_mfma_f32_16x16x32_bf16 v[20:23], v[176:179], v[220:223], v[20:23]
	v_mfma_f32_16x16x32_bf16 v[16:19], v[184:187], v[220:223], v[16:19]
	v_mfma_f32_16x16x32_bf16 v[4:7], v[176:179], v[228:231], v[4:7]
	v_mfma_f32_16x16x32_bf16 v[0:3], v[184:187], v[228:231], v[0:3]
	s_setprio 0
	s_barrier
	s_add_i32 s53, 0, 0x18000
	v_add_u32_e32 v32, s53, v164
	s_add_i32 s56, 0, 0x1c000
	ds_read_b128 v[142:145], v32
	ds_read_b128 v[148:151], v32 offset:1024
	ds_read_b128 v[158:161], v32 offset:2048
	ds_read_b128 v[168:171], v32 offset:3072
	v_add_u32_e32 v32, s56, v164
	ds_read_b128 v[172:175], v32
	ds_read_b128 v[176:179], v32 offset:1024
	ds_read_b128 v[180:183], v32 offset:2048
	ds_read_b128 v[184:187], v32 offset:3072
	s_add_u32 s30, s30, 0x40000
	s_addc_u32 s31, s31, 0
	s_mov_b32 m0, s43
	v_lshl_add_u64 v[232:233], s[30:31], 0, v[130:131]
	ds_read_b128 v[188:191], v166 offset:32768
	ds_read_b128 v[192:195], v166 offset:33792
	ds_read_b128 v[196:199], v166 offset:34816
	ds_read_b128 v[208:211], v166 offset:35840
	ds_read_b128 v[216:219], v166 offset:36864
	ds_read_b128 v[220:223], v166 offset:37888
	ds_read_b128 v[224:227], v166 offset:38912
	ds_read_b128 v[228:231], v166 offset:39936
	global_load_lds_dwordx4 v[232:233], off
	v_lshl_add_u64 v[232:233], s[30:31], 0, v[134:135]
	s_mov_b32 m0, s44
	s_nop 0
	global_load_lds_dwordx4 v[232:233], off
	s_waitcnt vmcnt(8)
	s_waitcnt lgkmcnt(0)
	s_barrier
	s_setprio 1
	s_waitcnt lgkmcnt(0)
	v_mfma_f32_16x16x32_bf16 v[126:129], v[142:145], v[188:191], v[126:129]
	v_mfma_f32_16x16x32_bf16 v[122:125], v[158:161], v[188:191], v[122:125]
	v_mfma_f32_16x16x32_bf16 v[110:113], v[142:145], v[196:199], v[110:113]
	v_mfma_f32_16x16x32_bf16 v[106:109], v[158:161], v[196:199], v[106:109]
	v_mfma_f32_16x16x32_bf16 v[94:97], v[142:145], v[216:219], v[94:97]
	v_mfma_f32_16x16x32_bf16 v[90:93], v[158:161], v[216:219], v[90:93]
	v_mfma_f32_16x16x32_bf16 v[78:81], v[142:145], v[224:227], v[78:81]
	v_mfma_f32_16x16x32_bf16 v[74:77], v[158:161], v[224:227], v[74:77]
	v_mfma_f32_16x16x32_bf16 v[126:129], v[148:151], v[192:195], v[126:129]
	v_mfma_f32_16x16x32_bf16 v[122:125], v[168:171], v[192:195], v[122:125]
	v_mfma_f32_16x16x32_bf16 v[110:113], v[148:151], v[208:211], v[110:113]
	v_mfma_f32_16x16x32_bf16 v[106:109], v[168:171], v[208:211], v[106:109]
	v_mfma_f32_16x16x32_bf16 v[94:97], v[148:151], v[220:223], v[94:97]
	v_mfma_f32_16x16x32_bf16 v[90:93], v[168:171], v[220:223], v[90:93]
	v_mfma_f32_16x16x32_bf16 v[78:81], v[148:151], v[228:231], v[78:81]
	v_mfma_f32_16x16x32_bf16 v[74:77], v[168:171], v[228:231], v[74:77]
	v_mfma_f32_16x16x32_bf16 v[118:121], v[172:175], v[188:191], v[118:121]
	v_mfma_f32_16x16x32_bf16 v[114:117], v[180:183], v[188:191], v[114:117]
	v_mfma_f32_16x16x32_bf16 v[102:105], v[172:175], v[196:199], v[102:105]
	v_mfma_f32_16x16x32_bf16 v[98:101], v[180:183], v[196:199], v[98:101]
	v_mfma_f32_16x16x32_bf16 v[86:89], v[172:175], v[216:219], v[86:89]
	v_mfma_f32_16x16x32_bf16 v[82:85], v[180:183], v[216:219], v[82:85]
	v_mfma_f32_16x16x32_bf16 v[70:73], v[172:175], v[224:227], v[70:73]
	v_mfma_f32_16x16x32_bf16 v[66:69], v[180:183], v[224:227], v[66:69]
	v_mfma_f32_16x16x32_bf16 v[118:121], v[176:179], v[192:195], v[118:121]
	v_mfma_f32_16x16x32_bf16 v[114:117], v[184:187], v[192:195], v[114:117]
	v_mfma_f32_16x16x32_bf16 v[102:105], v[176:179], v[208:211], v[102:105]
	v_mfma_f32_16x16x32_bf16 v[98:101], v[184:187], v[208:211], v[98:101]
	v_mfma_f32_16x16x32_bf16 v[86:89], v[176:179], v[220:223], v[86:89]
	v_mfma_f32_16x16x32_bf16 v[82:85], v[184:187], v[220:223], v[82:85]
	v_mfma_f32_16x16x32_bf16 v[70:73], v[176:179], v[228:231], v[70:73]
	v_mfma_f32_16x16x32_bf16 v[66:69], v[184:187], v[228:231], v[66:69]
	s_setprio 0
	s_barrier
; #define PG8_STAGE(bufoff, gbase, voff) do { _Pragma("unroll") for (int _i = 0; _i < 2; ++_i) \
;         __builtin_amdgcn_global_load_lds((const unsigned*)((const char*)(gbase) + (voff)[_i]), (PG8_LAS unsigned*)(lds + (bufoff) + ldsw + _i * 8192), 16, 0, 0); } while (0)
; #define PG8_LDA(dst, b, h) do { _Pragma("unroll") for (int m = 0; m < 4; ++m) _Pragma("unroll") for (int k = 0; k < 2; ++k) dst[m][k] = *(const PG8_LAS bf16x8*)(lds + PG8_SA(b, h) + aoff + m * 2048 + k * 1024); } while (0)
; #define PG8_WAIT_V(n) asm volatile("s_waitcnt vmcnt(" #n ")" ::: "memory")
; #define PG8_WAIT_L(n) asm volatile("s_waitcnt lgkmcnt(" #n ")" ::: "memory")
; #define PG8_BAR __builtin_amdgcn_s_barrier()
; #define PG8_SCHED __builtin_amdgcn_sched_barrier(0)
; template <class Epi, bool ALIGN_EPI = true>
; __device__ __forceinline__ void gemm_phase(PG8_LAS unsigned char* lds, const Gemm g, const StaticOrder& S, const Epi& E) {
;     ...
;             PG8_LDA(At, 1, 1); PG8_STAGE(PG8_SB(1, 0), b3, voffB); PG8_STAGE(PG8_SB(1, 1), b3 + hstepB, voffB); PG8_STAGE(PG8_SA(1, 0), a3, voffA);
;             PG8_WAIT_V(8); PG8_WAIT_L(0); PG8_BAR; PG8_MMA(1, 0, At, B0); PG8_MMA(1, 1, At, B1); PG8_BAR; PG8_SCHED;
	s_add_i32 s30, s53, s40
	v_lshl_add_u64 v[146:147], v[146:147], 0, s[60:61]
	s_mov_b32 m0, s30
	ds_read_b128 v[188:191], v166 offset:49152
	ds_read_b128 v[192:195], v166 offset:50176
	ds_read_b128 v[196:199], v166 offset:51200
	ds_read_b128 v[208:211], v166 offset:52224
	ds_read_b128 v[216:219], v166 offset:53248
	ds_read_b128 v[220:223], v166 offset:54272
	ds_read_b128 v[224:227], v166 offset:55296
	ds_read_b128 v[228:231], v166 offset:56320
	global_load_lds_dwordx4 v[146:147], off
	s_add_i32 m0, s30, 0x2000
	s_add_u32 s28, s28, 0x40080
	v_lshl_add_u64 v[146:147], v[200:201], 0, s[60:61]
	s_addc_u32 s29, s29, 0
	s_add_i32 s30, s56, s40
	global_load_lds_dwordx4 v[146:147], off
	v_lshl_add_u64 v[146:147], s[28:29], 0, v[132:133]
	s_mov_b32 m0, s30
	s_nop 0
	global_load_lds_dwordx4 v[146:147], off
	v_lshl_add_u64 v[146:147], s[28:29], 0, v[136:137]
	s_add_i32 m0, s30, 0x2000
	s_nop 0
	global_load_lds_dwordx4 v[146:147], off
	v_lshl_add_u64 v[146:147], v[204:205], 0, s[60:61]
	s_mov_b32 m0, s45
	s_nop 0
	global_load_lds_dwordx4 v[146:147], off
	v_lshl_add_u64 v[146:147], v[206:207], 0, s[60:61]
	s_mov_b32 m0, s46
	s_nop 0
	global_load_lds_dwordx4 v[146:147], off
	s_add_i32 s52, s52, 2
	s_add_u32 s8, s8, 0x100
	s_addc_u32 s9, s9, 0
	s_add_u32 s50, s50, 0x100
	s_addc_u32 s51, s51, 0
	s_add_u32 s28, s8, 0xfffc0080
	s_addc_u32 s29, s9, -1
	s_add_i32 s53, 0, 0x10000
	s_cmp_eq_u32 s52, 12
	s_cselect_b32 s31, s3, s29
	s_cselect_b32 s30, s7, s28
	v_add_u32_e32 v32, s53, v164
	s_cselect_b32 s29, s21, s51
	s_cselect_b32 s28, s23, s50
	s_add_i32 s56, 0, 0x14000
	s_cmp_gt_u32 s52, 13
	s_waitcnt vmcnt(8)
	s_waitcnt lgkmcnt(0)
	s_barrier
	s_setprio 1
	s_waitcnt lgkmcnt(0)
	v_mfma_f32_16x16x32_bf16 v[62:65], v[142:145], v[188:191], v[62:65]
	v_mfma_f32_16x16x32_bf16 v[58:61], v[158:161], v[188:191], v[58:61]
	v_mfma_f32_16x16x32_bf16 v[46:49], v[142:145], v[196:199], v[46:49]
	v_mfma_f32_16x16x32_bf16 v[42:45], v[158:161], v[196:199], v[42:45]
	v_mfma_f32_16x16x32_bf16 v[28:31], v[142:145], v[216:219], v[28:31]
	v_mfma_f32_16x16x32_bf16 v[24:27], v[158:161], v[216:219], v[24:27]
	v_mfma_f32_16x16x32_bf16 v[12:15], v[142:145], v[224:227], v[12:15]
	v_mfma_f32_16x16x32_bf16 v[8:11], v[158:161], v[224:227], v[8:11]
	v_mfma_f32_16x16x32_bf16 v[62:65], v[148:151], v[192:195], v[62:65]
	v_mfma_f32_16x16x32_bf16 v[58:61], v[168:171], v[192:195], v[58:61]
	v_mfma_f32_16x16x32_bf16 v[46:49], v[148:151], v[208:211], v[46:49]
	v_mfma_f32_16x16x32_bf16 v[42:45], v[168:171], v[208:211], v[42:45]
	v_mfma_f32_16x16x32_bf16 v[28:31], v[148:151], v[220:223], v[28:31]
	v_mfma_f32_16x16x32_bf16 v[24:27], v[168:171], v[220:223], v[24:27]
	v_mfma_f32_16x16x32_bf16 v[12:15], v[148:151], v[228:231], v[12:15]
	v_mfma_f32_16x16x32_bf16 v[8:11], v[168:171], v[228:231], v[8:11]
	v_mfma_f32_16x16x32_bf16 v[54:57], v[172:175], v[188:191], v[54:57]
	v_mfma_f32_16x16x32_bf16 v[50:53], v[180:183], v[188:191], v[50:53]
	v_mfma_f32_16x16x32_bf16 v[38:41], v[172:175], v[196:199], v[38:41]
	v_mfma_f32_16x16x32_bf16 v[34:37], v[180:183], v[196:199], v[34:37]
	v_mfma_f32_16x16x32_bf16 v[20:23], v[172:175], v[216:219], v[20:23]
	v_mfma_f32_16x16x32_bf16 v[16:19], v[180:183], v[216:219], v[16:19]
	v_mfma_f32_16x16x32_bf16 v[4:7], v[172:175], v[224:227], v[4:7]
	v_mfma_f32_16x16x32_bf16 v[0:3], v[180:183], v[224:227], v[0:3]
	v_mfma_f32_16x16x32_bf16 v[54:57], v[176:179], v[192:195], v[54:57]
	v_mfma_f32_16x16x32_bf16 v[50:53], v[184:187], v[192:195], v[50:53]
	v_mfma_f32_16x16x32_bf16 v[38:41], v[176:179], v[208:211], v[38:41]
	v_mfma_f32_16x16x32_bf16 v[34:37], v[184:187], v[208:211], v[34:37]
	v_mfma_f32_16x16x32_bf16 v[20:23], v[176:179], v[220:223], v[20:23]
	v_mfma_f32_16x16x32_bf16 v[16:19], v[184:187], v[220:223], v[16:19]
	v_mfma_f32_16x16x32_bf16 v[4:7], v[176:179], v[228:231], v[4:7]
	v_mfma_f32_16x16x32_bf16 v[0:3], v[184:187], v[228:231], v[0:3]
	s_setprio 0
	s_barrier
	s_cbranch_scc0 .Lrot_439
	s_and_b64 vcc, exec, s[18:19]
	s_cbranch_vccz .LBB0_442
	s_barrier

; #define PG8_STAGE(bufoff, gbase, voff) do { _Pragma("unroll") for (int _i = 0; _i < 2; ++_i) \
;         __builtin_amdgcn_global_load_lds((const unsigned*)((const char*)(gbase) + (voff)[_i]), (PG8_LAS unsigned*)(lds + (bufoff) + ldsw + _i * 8192), 16, 0, 0); } while (0)
; #define PG8_LDA(dst, b, h) do { _Pragma("unroll") for (int m = 0; m < 4; ++m) _Pragma("unroll") for (int k = 0; k < 2; ++k) dst[m][k] = *(const PG8_LAS bf16x8*)(lds + PG8_SA(b, h) + aoff + m * 2048 + k * 1024); } while (0)
; #define PG8_LDB(dst, b, h) do { _Pragma("unroll") for (int n = 0; n < 2; ++n) _Pragma("unroll") for (int k = 0; k < 2; ++k) dst[n][k] = *(const PG8_LAS bf16x8*)(lds + PG8_SB(b, h) + boff + n * 2048 + k * 1024); } while (0)
; #define PG8_WAIT_V(n) asm volatile("s_waitcnt vmcnt(" #n ")" ::: "memory")
; #define PG8_WAIT_L(n) asm volatile("s_waitcnt lgkmcnt(" #n ")" ::: "memory")
; #define PG8_BAR __builtin_amdgcn_s_barrier()
; #define PG8_SCHED __builtin_amdgcn_sched_barrier(0)
; template <class Epi, bool ALIGN_EPI = true>
; __device__ __forceinline__ void gemm_phase(PG8_LAS unsigned char* lds, const Gemm g, const StaticOrder& S, const Epi& E) {
;     ...
;             PG8_LDB(B0, 0, 0); PG8_LDB(B1, 0, 1); PG8_SCHED; PG8_LDA(At, 0, 0); PG8_STAGE(PG8_SA(1, 1), a1 + hstepA, voffA);
;             PG8_WAIT_V(8); PG8_WAIT_L(0); PG8_BAR; PG8_MMA(0, 0, At, B0); PG8_MMA(0, 1, At, B1); PG8_BAR; PG8_SCHED;
;             PG8_LDA(At, 0, 1); PG8_STAGE(PG8_SB(0, 0), b2, voffB); PG8_STAGE(PG8_SB(0, 1), b2 + hstepB, voffB); PG8_STAGE(PG8_SA(0, 0), a2, voffA);
.Lrot_795:
	ds_read_b128 v[142:145], v32
	ds_read_b128 v[148:151], v32 offset:1024
	ds_read_b128 v[158:161], v32 offset:2048
	ds_read_b128 v[168:171], v32 offset:3072
	v_add_u32_e32 v32, s43, v165
	ds_read_b128 v[172:175], v32
	ds_read_b128 v[176:179], v32 offset:1024
	ds_read_b128 v[180:183], v32 offset:2048
	ds_read_b128 v[184:187], v32 offset:3072
	v_lshl_add_u64 v[146:147], s[6:7], 0, v[138:139]
	s_add_i32 m0, s59, 0xc000
	ds_read_b128 v[188:191], v167
	ds_read_b128 v[192:195], v167 offset:1024
	ds_read_b128 v[196:199], v167 offset:2048
	ds_read_b128 v[208:211], v167 offset:3072
	ds_read_b128 v[216:219], v167 offset:4096
	ds_read_b128 v[220:223], v167 offset:5120
	ds_read_b128 v[224:227], v167 offset:6144
	ds_read_b128 v[228:231], v167 offset:7168
	global_load_lds_dwordx4 v[146:147], off
	v_lshl_add_u64 v[146:147], s[6:7], 0, v[140:141]
	s_add_i32 m0, s59, 0xe000
	s_nop 0
	global_load_lds_dwordx4 v[146:147], off
	s_waitcnt vmcnt(8)
	s_waitcnt lgkmcnt(0)
	s_barrier
	s_setprio 1
	s_waitcnt lgkmcnt(0)
	v_mfma_f32_16x16x32_bf16 v[126:129], v[142:145], v[188:191], v[126:129]
	v_mfma_f32_16x16x32_bf16 v[122:125], v[158:161], v[188:191], v[122:125]
	v_mfma_f32_16x16x32_bf16 v[110:113], v[142:145], v[196:199], v[110:113]
	v_mfma_f32_16x16x32_bf16 v[106:109], v[158:161], v[196:199], v[106:109]
	v_mfma_f32_16x16x32_bf16 v[94:97], v[142:145], v[216:219], v[94:97]
	v_mfma_f32_16x16x32_bf16 v[90:93], v[158:161], v[216:219], v[90:93]
	v_mfma_f32_16x16x32_bf16 v[78:81], v[142:145], v[224:227], v[78:81]
	v_mfma_f32_16x16x32_bf16 v[74:77], v[158:161], v[224:227], v[74:77]
	v_mfma_f32_16x16x32_bf16 v[126:129], v[148:151], v[192:195], v[126:129]
	v_mfma_f32_16x16x32_bf16 v[122:125], v[168:171], v[192:195], v[122:125]
	v_mfma_f32_16x16x32_bf16 v[110:113], v[148:151], v[208:211], v[110:113]
	v_mfma_f32_16x16x32_bf16 v[106:109], v[168:171], v[208:211], v[106:109]
	v_mfma_f32_16x16x32_bf16 v[94:97], v[148:151], v[220:223], v[94:97]
	v_mfma_f32_16x16x32_bf16 v[90:93], v[168:171], v[220:223], v[90:93]
	v_mfma_f32_16x16x32_bf16 v[78:81], v[148:151], v[228:231], v[78:81]
	v_mfma_f32_16x16x32_bf16 v[74:77], v[168:171], v[228:231], v[74:77]
	v_mfma_f32_16x16x32_bf16 v[118:121], v[172:175], v[188:191], v[118:121]
	v_mfma_f32_16x16x32_bf16 v[114:117], v[180:183], v[188:191], v[114:117]
	v_mfma_f32_16x16x32_bf16 v[102:105], v[172:175], v[196:199], v[102:105]
	v_mfma_f32_16x16x32_bf16 v[98:101], v[180:183], v[196:199], v[98:101]
	v_mfma_f32_16x16x32_bf16 v[86:89], v[172:175], v[216:219], v[86:89]
	v_mfma_f32_16x16x32_bf16 v[82:85], v[180:183], v[216:219], v[82:85]
	v_mfma_f32_16x16x32_bf16 v[70:73], v[172:175], v[224:227], v[70:73]
	v_mfma_f32_16x16x32_bf16 v[66:69], v[180:183], v[224:227], v[66:69]
	v_mfma_f32_16x16x32_bf16 v[118:121], v[176:179], v[192:195], v[118:121]
	v_mfma_f32_16x16x32_bf16 v[114:117], v[184:187], v[192:195], v[114:117]
	v_mfma_f32_16x16x32_bf16 v[102:105], v[176:179], v[208:211], v[102:105]
	v_mfma_f32_16x16x32_bf16 v[98:101], v[184:187], v[208:211], v[98:101]
	v_mfma_f32_16x16x32_bf16 v[86:89], v[176:179], v[220:223], v[86:89]
	v_mfma_f32_16x16x32_bf16 v[82:85], v[184:187], v[220:223], v[82:85]
	v_mfma_f32_16x16x32_bf16 v[70:73], v[176:179], v[228:231], v[70:73]
	v_mfma_f32_16x16x32_bf16 v[66:69], v[184:187], v[228:231], v[66:69]
	s_setprio 0
	s_barrier
	s_add_i32 s75, s75, s51
	v_lshl_add_u64 v[146:147], s[44:45], 0, v[132:133]
	s_mov_b32 m0, s75
	ds_read_b128 v[188:191], v167 offset:16384
	ds_read_b128 v[192:195], v167 offset:17408
	ds_read_b128 v[196:199], v167 offset:18432
	ds_read_b128 v[208:211], v167 offset:19456
	ds_read_b128 v[216:219], v167 offset:20480
	ds_read_b128 v[220:223], v167 offset:21504
	ds_read_b128 v[224:227], v167 offset:22528
	ds_read_b128 v[228:231], v167 offset:23552
	global_load_lds_dwordx4 v[146:147], off
	s_add_i32 m0, s75, 0x2000
	s_add_u32 s76, s44, 0x40000
	v_lshl_add_u64 v[162:163], s[44:45], 0, v[136:137]
	s_addc_u32 s77, s45, 0
	s_add_i32 s43, s43, s51
	global_load_lds_dwordx4 v[162:163], off
	v_lshl_add_u64 v[200:201], s[76:77], 0, v[132:133]
	s_mov_b32 m0, s43
	v_lshl_add_u64 v[204:205], s[46:47], 0, v[134:135]
	global_load_lds_dwordx4 v[200:201], off
	v_lshl_add_u64 v[200:201], s[76:77], 0, v[136:137]
	s_add_i32 m0, s43, 0x2000
	s_nop 0
	global_load_lds_dwordx4 v[200:201], off
	v_lshl_add_u64 v[200:201], s[46:47], 0, v[130:131]
	s_mov_b32 m0, s59
	s_nop 0
	global_load_lds_dwordx4 v[200:201], off
	s_mov_b32 m0, s62
	s_nop 0
	global_load_lds_dwordx4 v[204:205], off
	s_waitcnt vmcnt(8)
	s_waitcnt lgkmcnt(0)
	s_barrier
; #define PG8_STAGE(bufoff, gbase, voff) do { _Pragma("unroll") for (int _i = 0; _i < 2; ++_i) \
;         __builtin_amdgcn_global_load_lds((const unsigned*)((const char*)(gbase) + (voff)[_i]), (PG8_LAS unsigned*)(lds + (bufoff) + ldsw + _i * 8192), 16, 0, 0); } while (0)
; #define PG8_LDA(dst, b, h) do { _Pragma("unroll") for (int m = 0; m < 4; ++m) _Pragma("unroll") for (int k = 0; k < 2; ++k) dst[m][k] = *(const PG8_LAS bf16x8*)(lds + PG8_SA(b, h) + aoff + m * 2048 + k * 1024); } while (0)
; #define PG8_LDB(dst, b, h) do { _Pragma("unroll") for (int n = 0; n < 2; ++n) _Pragma("unroll") for (int k = 0; k < 2; ++k) dst[n][k] = *(const PG8_LAS bf16x8*)(lds + PG8_SB(b, h) + boff + n * 2048 + k * 1024); } while (0)
; #define PG8_WAIT_V(n) asm volatile("s_waitcnt vmcnt(" #n ")" ::: "memory")
; #define PG8_WAIT_L(n) asm volatile("s_waitcnt lgkmcnt(" #n ")" ::: "memory")
; #define PG8_BAR __builtin_amdgcn_s_barrier()
; #define PG8_SCHED __builtin_amdgcn_sched_barrier(0)
; template <class Epi, bool ALIGN_EPI = true>
; __device__ __forceinline__ void gemm_phase(PG8_LAS unsigned char* lds, const Gemm g, const StaticOrder& S, const Epi& E) {
;     ...
;             PG8_WAIT_V(8); PG8_WAIT_L(0); PG8_BAR; PG8_MMA(1, 0, At, B0); PG8_MMA(1, 1, At, B1); PG8_BAR; PG8_SCHED;
;             PG8_LDB(B0, 1, 0); PG8_LDB(B1, 1, 1); PG8_SCHED; PG8_LDA(At, 1, 0); PG8_STAGE(PG8_SA(0, 1), a2 + hstepA, voffA);
;             PG8_WAIT_V(8); PG8_WAIT_L(0); PG8_BAR; PG8_MMA(0, 0, At, B0); PG8_MMA(0, 1, At, B1); PG8_BAR; PG8_SCHED;
	s_setprio 1
	s_waitcnt lgkmcnt(0)
	v_mfma_f32_16x16x32_bf16 v[62:65], v[142:145], v[188:191], v[62:65]
	v_mfma_f32_16x16x32_bf16 v[58:61], v[158:161], v[188:191], v[58:61]
	v_mfma_f32_16x16x32_bf16 v[46:49], v[142:145], v[196:199], v[46:49]
	v_mfma_f32_16x16x32_bf16 v[42:45], v[158:161], v[196:199], v[42:45]
	v_mfma_f32_16x16x32_bf16 v[28:31], v[142:145], v[216:219], v[28:31]
	v_mfma_f32_16x16x32_bf16 v[24:27], v[158:161], v[216:219], v[24:27]
	v_mfma_f32_16x16x32_bf16 v[12:15], v[142:145], v[224:227], v[12:15]
	v_mfma_f32_16x16x32_bf16 v[8:11], v[158:161], v[224:227], v[8:11]
	v_mfma_f32_16x16x32_bf16 v[62:65], v[148:151], v[192:195], v[62:65]
	v_mfma_f32_16x16x32_bf16 v[58:61], v[168:171], v[192:195], v[58:61]
	v_mfma_f32_16x16x32_bf16 v[46:49], v[148:151], v[208:211], v[46:49]
	v_mfma_f32_16x16x32_bf16 v[42:45], v[168:171], v[208:211], v[42:45]
	v_mfma_f32_16x16x32_bf16 v[28:31], v[148:151], v[220:223], v[28:31]
	v_mfma_f32_16x16x32_bf16 v[24:27], v[168:171], v[220:223], v[24:27]
	v_mfma_f32_16x16x32_bf16 v[12:15], v[148:151], v[228:231], v[12:15]
	v_mfma_f32_16x16x32_bf16 v[8:11], v[168:171], v[228:231], v[8:11]
	v_mfma_f32_16x16x32_bf16 v[54:57], v[172:175], v[188:191], v[54:57]
	v_mfma_f32_16x16x32_bf16 v[50:53], v[180:183], v[188:191], v[50:53]
	v_mfma_f32_16x16x32_bf16 v[38:41], v[172:175], v[196:199], v[38:41]
	v_mfma_f32_16x16x32_bf16 v[34:37], v[180:183], v[196:199], v[34:37]
	v_mfma_f32_16x16x32_bf16 v[20:23], v[172:175], v[216:219], v[20:23]
	v_mfma_f32_16x16x32_bf16 v[16:19], v[180:183], v[216:219], v[16:19]
	v_mfma_f32_16x16x32_bf16 v[4:7], v[172:175], v[224:227], v[4:7]
	v_mfma_f32_16x16x32_bf16 v[0:3], v[180:183], v[224:227], v[0:3]
	v_mfma_f32_16x16x32_bf16 v[54:57], v[176:179], v[192:195], v[54:57]
	v_mfma_f32_16x16x32_bf16 v[50:53], v[184:187], v[192:195], v[50:53]
	v_mfma_f32_16x16x32_bf16 v[38:41], v[176:179], v[208:211], v[38:41]
	v_mfma_f32_16x16x32_bf16 v[34:37], v[184:187], v[208:211], v[34:37]
	v_mfma_f32_16x16x32_bf16 v[20:23], v[176:179], v[220:223], v[20:23]
	v_mfma_f32_16x16x32_bf16 v[16:19], v[184:187], v[220:223], v[16:19]
	v_mfma_f32_16x16x32_bf16 v[4:7], v[176:179], v[228:231], v[4:7]
	v_mfma_f32_16x16x32_bf16 v[0:3], v[184:187], v[228:231], v[0:3]
	s_setprio 0
	s_barrier
	s_add_i32 s43, 0, 0x18000
	v_add_u32_e32 v32, s43, v165
	s_add_i32 s75, 0, 0x1c000
	ds_read_b128 v[142:145], v32
	ds_read_b128 v[148:151], v32 offset:1024
	ds_read_b128 v[158:161], v32 offset:2048
	ds_read_b128 v[168:171], v32 offset:3072
	v_add_u32_e32 v32, s75, v165
	ds_read_b128 v[172:175], v32
	ds_read_b128 v[176:179], v32 offset:1024
	ds_read_b128 v[180:183], v32 offset:2048
	ds_read_b128 v[184:187], v32 offset:3072
	s_add_u32 s46, s46, 0x40000
	s_addc_u32 s47, s47, 0
	s_mov_b32 m0, s63
	v_lshl_add_u64 v[206:207], s[46:47], 0, v[130:131]
	ds_read_b128 v[188:191], v167 offset:32768
	ds_read_b128 v[192:195], v167 offset:33792
	ds_read_b128 v[196:199], v167 offset:34816
	ds_read_b128 v[208:211], v167 offset:35840
	ds_read_b128 v[216:219], v167 offset:36864
	ds_read_b128 v[220:223], v167 offset:37888
	ds_read_b128 v[224:227], v167 offset:38912
	ds_read_b128 v[228:231], v167 offset:39936
	global_load_lds_dwordx4 v[206:207], off
	v_lshl_add_u64 v[206:207], s[46:47], 0, v[134:135]
	s_mov_b32 m0, s66
	s_nop 0
	global_load_lds_dwordx4 v[206:207], off
	s_waitcnt vmcnt(8)
	s_waitcnt lgkmcnt(0)
	s_barrier
	s_setprio 1
	s_waitcnt lgkmcnt(0)
	v_mfma_f32_16x16x32_bf16 v[126:129], v[142:145], v[188:191], v[126:129]
	v_mfma_f32_16x16x32_bf16 v[122:125], v[158:161], v[188:191], v[122:125]
	v_mfma_f32_16x16x32_bf16 v[110:113], v[142:145], v[196:199], v[110:113]
	v_mfma_f32_16x16x32_bf16 v[106:109], v[158:161], v[196:199], v[106:109]
	v_mfma_f32_16x16x32_bf16 v[94:97], v[142:145], v[216:219], v[94:97]
	v_mfma_f32_16x16x32_bf16 v[90:93], v[158:161], v[216:219], v[90:93]
	v_mfma_f32_16x16x32_bf16 v[78:81], v[142:145], v[224:227], v[78:81]
	v_mfma_f32_16x16x32_bf16 v[74:77], v[158:161], v[224:227], v[74:77]
	v_mfma_f32_16x16x32_bf16 v[126:129], v[148:151], v[192:195], v[126:129]
	v_mfma_f32_16x16x32_bf16 v[122:125], v[168:171], v[192:195], v[122:125]
	v_mfma_f32_16x16x32_bf16 v[110:113], v[148:151], v[208:211], v[110:113]
	v_mfma_f32_16x16x32_bf16 v[106:109], v[168:171], v[208:211], v[106:109]
	v_mfma_f32_16x16x32_bf16 v[94:97], v[148:151], v[220:223], v[94:97]
	v_mfma_f32_16x16x32_bf16 v[90:93], v[168:171], v[220:223], v[90:93]
	v_mfma_f32_16x16x32_bf16 v[78:81], v[148:151], v[228:231], v[78:81]
	v_mfma_f32_16x16x32_bf16 v[74:77], v[168:171], v[228:231], v[74:77]
	v_mfma_f32_16x16x32_bf16 v[118:121], v[172:175], v[188:191], v[118:121]
	v_mfma_f32_16x16x32_bf16 v[114:117], v[180:183], v[188:191], v[114:117]
	v_mfma_f32_16x16x32_bf16 v[102:105], v[172:175], v[196:199], v[102:105]
	v_mfma_f32_16x16x32_bf16 v[98:101], v[180:183], v[196:199], v[98:101]
	v_mfma_f32_16x16x32_bf16 v[86:89], v[172:175], v[216:219], v[86:89]
	v_mfma_f32_16x16x32_bf16 v[82:85], v[180:183], v[216:219], v[82:85]
	v_mfma_f32_16x16x32_bf16 v[70:73], v[172:175], v[224:227], v[70:73]
	v_mfma_f32_16x16x32_bf16 v[66:69], v[180:183], v[224:227], v[66:69]
	v_mfma_f32_16x16x32_bf16 v[118:121], v[176:179], v[192:195], v[118:121]
	v_mfma_f32_16x16x32_bf16 v[114:117], v[184:187], v[192:195], v[114:117]
	v_mfma_f32_16x16x32_bf16 v[102:105], v[176:179], v[208:211], v[102:105]
	v_mfma_f32_16x16x32_bf16 v[98:101], v[184:187], v[208:211], v[98:101]
	v_mfma_f32_16x16x32_bf16 v[86:89], v[176:179], v[220:223], v[86:89]
	v_mfma_f32_16x16x32_bf16 v[82:85], v[184:187], v[220:223], v[82:85]
	v_mfma_f32_16x16x32_bf16 v[70:73], v[176:179], v[228:231], v[70:73]
	v_mfma_f32_16x16x32_bf16 v[66:69], v[184:187], v[228:231], v[66:69]
	s_setprio 0
	s_barrier
; #define PG8_STAGE(bufoff, gbase, voff) do { _Pragma("unroll") for (int _i = 0; _i < 2; ++_i) \
;         __builtin_amdgcn_global_load_lds((const unsigned*)((const char*)(gbase) + (voff)[_i]), (PG8_LAS unsigned*)(lds + (bufoff) + ldsw + _i * 8192), 16, 0, 0); } while (0)
; #define PG8_LDA(dst, b, h) do { _Pragma("unroll") for (int m = 0; m < 4; ++m) _Pragma("unroll") for (int k = 0; k < 2; ++k) dst[m][k] = *(const PG8_LAS bf16x8*)(lds + PG8_SA(b, h) + aoff + m * 2048 + k * 1024); } while (0)
; #define PG8_WAIT_V(n) asm volatile("s_waitcnt vmcnt(" #n ")" ::: "memory")
; #define PG8_WAIT_L(n) asm volatile("s_waitcnt lgkmcnt(" #n ")" ::: "memory")
; #define PG8_BAR __builtin_amdgcn_s_barrier()
; #define PG8_SCHED __builtin_amdgcn_sched_barrier(0)
; template <class Epi, bool ALIGN_EPI = true>
; __device__ __forceinline__ void gemm_phase(PG8_LAS unsigned char* lds, const Gemm g, const StaticOrder& S, const Epi& E) {
;     ...
;             PG8_LDA(At, 1, 1); PG8_STAGE(PG8_SB(1, 0), b3, voffB); PG8_STAGE(PG8_SB(1, 1), b3 + hstepB, voffB); PG8_STAGE(PG8_SA(1, 0), a3, voffA);
;             PG8_WAIT_V(8); PG8_WAIT_L(0); PG8_BAR; PG8_MMA(1, 0, At, B0); PG8_MMA(1, 1, At, B1); PG8_BAR; PG8_SCHED;
	s_add_i32 s43, s43, s51
	v_lshl_add_u64 v[146:147], v[146:147], 0, s[60:61]
	s_mov_b32 m0, s43
	ds_read_b128 v[188:191], v167 offset:49152
	ds_read_b128 v[192:195], v167 offset:50176
	ds_read_b128 v[196:199], v167 offset:51200
	ds_read_b128 v[208:211], v167 offset:52224
	ds_read_b128 v[216:219], v167 offset:53248
	ds_read_b128 v[220:223], v167 offset:54272
	ds_read_b128 v[224:227], v167 offset:55296
	ds_read_b128 v[228:231], v167 offset:56320
	global_load_lds_dwordx4 v[146:147], off
	s_add_i32 m0, s43, 0x2000
	s_add_u32 s44, s44, 0x40080
	v_lshl_add_u64 v[146:147], v[162:163], 0, s[60:61]
	s_addc_u32 s45, s45, 0
	s_add_i32 s43, s75, s51
	global_load_lds_dwordx4 v[146:147], off
	v_lshl_add_u64 v[146:147], s[44:45], 0, v[132:133]
	s_mov_b32 m0, s43
	s_nop 0
	global_load_lds_dwordx4 v[146:147], off
	v_lshl_add_u64 v[146:147], s[44:45], 0, v[136:137]
	s_add_i32 m0, s43, 0x2000
	s_nop 0
	global_load_lds_dwordx4 v[146:147], off
	v_lshl_add_u64 v[146:147], v[200:201], 0, s[60:61]
	s_mov_b32 m0, s70
	s_nop 0
	global_load_lds_dwordx4 v[146:147], off
	v_lshl_add_u64 v[146:147], v[204:205], 0, s[60:61]
	s_mov_b32 m0, s71
	s_nop 0
	global_load_lds_dwordx4 v[146:147], off
	s_add_i32 s37, s37, 2
	s_add_u32 s6, s6, 0x100
	s_addc_u32 s7, s7, 0
	s_add_u32 s9, s9, 0x100
	s_addc_u32 s35, s35, 0
	s_add_u32 s43, s6, 0xfffc0080
	s_addc_u32 s44, s7, -1
	s_add_i32 s75, 0, 0x10000
	s_cmp_eq_u32 s37, 12
	s_cselect_b32 s47, s39, s44
	s_cselect_b32 s46, s38, s43
	v_add_u32_e32 v32, s75, v165
	s_cselect_b32 s45, s41, s35
	s_cselect_b32 s44, s40, s9
	s_add_i32 s43, 0, 0x14000
	s_cmp_gt_u32 s37, 13
	s_waitcnt vmcnt(8)
	s_waitcnt lgkmcnt(0)
	s_barrier
	s_setprio 1
	s_waitcnt lgkmcnt(0)
	v_mfma_f32_16x16x32_bf16 v[62:65], v[142:145], v[188:191], v[62:65]
	v_mfma_f32_16x16x32_bf16 v[58:61], v[158:161], v[188:191], v[58:61]
	v_mfma_f32_16x16x32_bf16 v[46:49], v[142:145], v[196:199], v[46:49]
	v_mfma_f32_16x16x32_bf16 v[42:45], v[158:161], v[196:199], v[42:45]
	v_mfma_f32_16x16x32_bf16 v[28:31], v[142:145], v[216:219], v[28:31]
	v_mfma_f32_16x16x32_bf16 v[24:27], v[158:161], v[216:219], v[24:27]
	v_mfma_f32_16x16x32_bf16 v[12:15], v[142:145], v[224:227], v[12:15]
	v_mfma_f32_16x16x32_bf16 v[8:11], v[158:161], v[224:227], v[8:11]
	v_mfma_f32_16x16x32_bf16 v[62:65], v[148:151], v[192:195], v[62:65]
	v_mfma_f32_16x16x32_bf16 v[58:61], v[168:171], v[192:195], v[58:61]
	v_mfma_f32_16x16x32_bf16 v[46:49], v[148:151], v[208:211], v[46:49]
	v_mfma_f32_16x16x32_bf16 v[42:45], v[168:171], v[208:211], v[42:45]
	v_mfma_f32_16x16x32_bf16 v[28:31], v[148:151], v[220:223], v[28:31]
	v_mfma_f32_16x16x32_bf16 v[24:27], v[168:171], v[220:223], v[24:27]
	v_mfma_f32_16x16x32_bf16 v[12:15], v[148:151], v[228:231], v[12:15]
	v_mfma_f32_16x16x32_bf16 v[8:11], v[168:171], v[228:231], v[8:11]
	v_mfma_f32_16x16x32_bf16 v[54:57], v[172:175], v[188:191], v[54:57]
	v_mfma_f32_16x16x32_bf16 v[50:53], v[180:183], v[188:191], v[50:53]
	v_mfma_f32_16x16x32_bf16 v[38:41], v[172:175], v[196:199], v[38:41]
	v_mfma_f32_16x16x32_bf16 v[34:37], v[180:183], v[196:199], v[34:37]
	v_mfma_f32_16x16x32_bf16 v[20:23], v[172:175], v[216:219], v[20:23]
	v_mfma_f32_16x16x32_bf16 v[16:19], v[180:183], v[216:219], v[16:19]
	v_mfma_f32_16x16x32_bf16 v[4:7], v[172:175], v[224:227], v[4:7]
	v_mfma_f32_16x16x32_bf16 v[0:3], v[180:183], v[224:227], v[0:3]
	v_mfma_f32_16x16x32_bf16 v[54:57], v[176:179], v[192:195], v[54:57]
	v_mfma_f32_16x16x32_bf16 v[50:53], v[184:187], v[192:195], v[50:53]
	v_mfma_f32_16x16x32_bf16 v[38:41], v[176:179], v[208:211], v[38:41]
	v_mfma_f32_16x16x32_bf16 v[34:37], v[184:187], v[208:211], v[34:37]
	v_mfma_f32_16x16x32_bf16 v[20:23], v[176:179], v[220:223], v[20:23]
	v_mfma_f32_16x16x32_bf16 v[16:19], v[184:187], v[220:223], v[16:19]
	v_mfma_f32_16x16x32_bf16 v[4:7], v[176:179], v[228:231], v[4:7]
	v_mfma_f32_16x16x32_bf16 v[0:3], v[184:187], v[228:231], v[0:3]
	s_setprio 0
	s_barrier
	s_cbranch_scc0 .Lrot_795
	s_and_b64 vcc, exec, s[26:27]
	s_cbranch_vccz .LBB0_798
	s_barrier

; #define PG8_STAGE(bufoff, gbase, voff) do { _Pragma("unroll") for (int _i = 0; _i < 2; ++_i) \
;         __builtin_amdgcn_global_load_lds((const unsigned*)((const char*)(gbase) + (voff)[_i]), (PG8_LAS unsigned*)(lds + (bufoff) + ldsw + _i * 8192), 16, 0, 0); } while (0)
; #define PG8_LDA(dst, b, h) do { _Pragma("unroll") for (int m = 0; m < 4; ++m) _Pragma("unroll") for (int k = 0; k < 2; ++k) dst[m][k] = *(const PG8_LAS bf16x8*)(lds + PG8_SA(b, h) + aoff + m * 2048 + k * 1024); } while (0)
; #define PG8_LDB(dst, b, h) do { _Pragma("unroll") for (int n = 0; n < 2; ++n) _Pragma("unroll") for (int k = 0; k < 2; ++k) dst[n][k] = *(const PG8_LAS bf16x8*)(lds + PG8_SB(b, h) + boff + n * 2048 + k * 1024); } while (0)
; #define PG8_WAIT_V(n) asm volatile("s_waitcnt vmcnt(" #n ")" ::: "memory")
; #define PG8_WAIT_L(n) asm volatile("s_waitcnt lgkmcnt(" #n ")" ::: "memory")
; #define PG8_BAR __builtin_amdgcn_s_barrier()
; #define PG8_SCHED __builtin_amdgcn_sched_barrier(0)
; template <class Epi, bool ALIGN_EPI = true>
; __device__ __forceinline__ void gemm_phase(PG8_LAS unsigned char* lds, const Gemm g, const StaticOrder& S, const Epi& E) {
;     ...
;             PG8_LDB(B0, 0, 0); PG8_LDB(B1, 0, 1); PG8_SCHED; PG8_LDA(At, 0, 0); PG8_STAGE(PG8_SA(1, 1), a1 + hstepA, voffA);
;             PG8_WAIT_V(8); PG8_WAIT_L(0); PG8_BAR; PG8_MMA(0, 0, At, B0); PG8_MMA(0, 1, At, B1); PG8_BAR; PG8_SCHED;
;             PG8_LDA(At, 0, 1); PG8_STAGE(PG8_SB(0, 0), b2, voffB); PG8_STAGE(PG8_SB(0, 1), b2 + hstepB, voffB); PG8_STAGE(PG8_SA(0, 0), a2, voffA);
.Lrot_1004:
	ds_read_b128 v[130:133], v32
	ds_read_b128 v[134:137], v32 offset:1024
	ds_read_b128 v[164:167], v32 offset:2048
	ds_read_b128 v[168:171], v32 offset:3072
	v_add_u32_e32 v32, s52, v143
	ds_read_b128 v[172:175], v32
	ds_read_b128 v[176:179], v32 offset:1024
	ds_read_b128 v[180:183], v32 offset:2048
	ds_read_b128 v[184:187], v32 offset:3072
	v_lshl_add_u64 v[146:147], s[20:21], 0, v[158:159]
	s_add_i32 m0, s35, 0xc000
	ds_read_b128 v[188:191], v163
	ds_read_b128 v[192:195], v163 offset:1024
	ds_read_b128 v[196:199], v163 offset:2048
	ds_read_b128 v[216:219], v163 offset:3072
	ds_read_b128 v[220:223], v163 offset:4096
	ds_read_b128 v[224:227], v163 offset:5120
	ds_read_b128 v[228:231], v163 offset:6144
	ds_read_b128 v[232:235], v163 offset:7168
	global_load_lds_dwordx4 v[146:147], off
	v_lshl_add_u64 v[146:147], s[20:21], 0, v[160:161]
	s_add_i32 m0, s35, 0xe000
	s_nop 0
	global_load_lds_dwordx4 v[146:147], off
	s_waitcnt vmcnt(8)
	s_waitcnt lgkmcnt(0)
	s_barrier
	s_setprio 1
	s_waitcnt lgkmcnt(0)
	v_mfma_f32_16x16x32_bf16 v[126:129], v[188:191], v[130:133], v[126:129]
	v_mfma_f32_16x16x32_bf16 v[122:125], v[188:191], v[164:167], v[122:125]
	v_mfma_f32_16x16x32_bf16 v[110:113], v[196:199], v[130:133], v[110:113]
	v_mfma_f32_16x16x32_bf16 v[106:109], v[196:199], v[164:167], v[106:109]
	v_mfma_f32_16x16x32_bf16 v[94:97], v[220:223], v[130:133], v[94:97]
	v_mfma_f32_16x16x32_bf16 v[90:93], v[220:223], v[164:167], v[90:93]
	v_mfma_f32_16x16x32_bf16 v[78:81], v[228:231], v[130:133], v[78:81]
	v_mfma_f32_16x16x32_bf16 v[74:77], v[228:231], v[164:167], v[74:77]
	v_mfma_f32_16x16x32_bf16 v[126:129], v[192:195], v[134:137], v[126:129]
	v_mfma_f32_16x16x32_bf16 v[122:125], v[192:195], v[168:171], v[122:125]
	v_mfma_f32_16x16x32_bf16 v[110:113], v[216:219], v[134:137], v[110:113]
	v_mfma_f32_16x16x32_bf16 v[106:109], v[216:219], v[168:171], v[106:109]
	v_mfma_f32_16x16x32_bf16 v[94:97], v[224:227], v[134:137], v[94:97]
	v_mfma_f32_16x16x32_bf16 v[90:93], v[224:227], v[168:171], v[90:93]
	v_mfma_f32_16x16x32_bf16 v[78:81], v[232:235], v[134:137], v[78:81]
	v_mfma_f32_16x16x32_bf16 v[74:77], v[232:235], v[168:171], v[74:77]
	v_mfma_f32_16x16x32_bf16 v[118:121], v[188:191], v[172:175], v[118:121]
	v_mfma_f32_16x16x32_bf16 v[114:117], v[188:191], v[180:183], v[114:117]
	v_mfma_f32_16x16x32_bf16 v[102:105], v[196:199], v[172:175], v[102:105]
	v_mfma_f32_16x16x32_bf16 v[98:101], v[196:199], v[180:183], v[98:101]
	v_mfma_f32_16x16x32_bf16 v[86:89], v[220:223], v[172:175], v[86:89]
	v_mfma_f32_16x16x32_bf16 v[82:85], v[220:223], v[180:183], v[82:85]
	v_mfma_f32_16x16x32_bf16 v[70:73], v[228:231], v[172:175], v[70:73]
	v_mfma_f32_16x16x32_bf16 v[66:69], v[228:231], v[180:183], v[66:69]
	v_mfma_f32_16x16x32_bf16 v[118:121], v[192:195], v[176:179], v[118:121]
	v_mfma_f32_16x16x32_bf16 v[114:117], v[192:195], v[184:187], v[114:117]
	v_mfma_f32_16x16x32_bf16 v[102:105], v[216:219], v[176:179], v[102:105]
	v_mfma_f32_16x16x32_bf16 v[98:101], v[216:219], v[184:187], v[98:101]
	v_mfma_f32_16x16x32_bf16 v[86:89], v[224:227], v[176:179], v[86:89]
	v_mfma_f32_16x16x32_bf16 v[82:85], v[224:227], v[184:187], v[82:85]
	v_mfma_f32_16x16x32_bf16 v[70:73], v[232:235], v[176:179], v[70:73]
	v_mfma_f32_16x16x32_bf16 v[66:69], v[232:235], v[184:187], v[66:69]
	s_setprio 0
	s_barrier
	s_add_i32 s50, s50, s34
	v_lshl_add_u64 v[146:147], s[22:23], 0, v[138:139]
	s_mov_b32 m0, s50
	ds_read_b128 v[188:191], v163 offset:16384
	ds_read_b128 v[192:195], v163 offset:17408
	ds_read_b128 v[196:199], v163 offset:18432
	ds_read_b128 v[216:219], v163 offset:19456
	ds_read_b128 v[220:223], v163 offset:20480
	ds_read_b128 v[224:227], v163 offset:21504
	ds_read_b128 v[228:231], v163 offset:22528
	ds_read_b128 v[232:235], v163 offset:23552
	global_load_lds_dwordx4 v[146:147], off
	s_add_i32 m0, s50, 0x2000
	s_add_u32 s50, s22, 0x40000
	v_lshl_add_u64 v[148:149], s[22:23], 0, v[140:141]
	s_addc_u32 s51, s23, 0
	s_add_i32 s52, s52, s34
	global_load_lds_dwordx4 v[148:149], off
	v_lshl_add_u64 v[150:151], s[50:51], 0, v[138:139]
	s_mov_b32 m0, s52
	v_lshl_add_u64 v[200:201], s[24:25], 0, v[140:141]
	global_load_lds_dwordx4 v[150:151], off
	v_lshl_add_u64 v[150:151], s[50:51], 0, v[140:141]
	s_add_i32 m0, s52, 0x2000
	s_nop 0
	global_load_lds_dwordx4 v[150:151], off
	v_lshl_add_u64 v[150:151], s[24:25], 0, v[138:139]
	s_mov_b32 m0, s35
	s_nop 0
	global_load_lds_dwordx4 v[150:151], off
	s_mov_b32 m0, s36
	s_nop 0
	global_load_lds_dwordx4 v[200:201], off
	s_waitcnt vmcnt(8)
	s_waitcnt lgkmcnt(0)
	s_barrier
; #define PG8_STAGE(bufoff, gbase, voff) do { _Pragma("unroll") for (int _i = 0; _i < 2; ++_i) \
;         __builtin_amdgcn_global_load_lds((const unsigned*)((const char*)(gbase) + (voff)[_i]), (PG8_LAS unsigned*)(lds + (bufoff) + ldsw + _i * 8192), 16, 0, 0); } while (0)
; #define PG8_LDA(dst, b, h) do { _Pragma("unroll") for (int m = 0; m < 4; ++m) _Pragma("unroll") for (int k = 0; k < 2; ++k) dst[m][k] = *(const PG8_LAS bf16x8*)(lds + PG8_SA(b, h) + aoff + m * 2048 + k * 1024); } while (0)
; #define PG8_LDB(dst, b, h) do { _Pragma("unroll") for (int n = 0; n < 2; ++n) _Pragma("unroll") for (int k = 0; k < 2; ++k) dst[n][k] = *(const PG8_LAS bf16x8*)(lds + PG8_SB(b, h) + boff + n * 2048 + k * 1024); } while (0)
; #define PG8_WAIT_V(n) asm volatile("s_waitcnt vmcnt(" #n ")" ::: "memory")
; #define PG8_WAIT_L(n) asm volatile("s_waitcnt lgkmcnt(" #n ")" ::: "memory")
; #define PG8_BAR __builtin_amdgcn_s_barrier()
; #define PG8_SCHED __builtin_amdgcn_sched_barrier(0)
; template <class Epi, bool ALIGN_EPI = true>
; __device__ __forceinline__ void gemm_phase(PG8_LAS unsigned char* lds, const Gemm g, const StaticOrder& S, const Epi& E) {
;     ...
;             PG8_WAIT_V(8); PG8_WAIT_L(0); PG8_BAR; PG8_MMA(1, 0, At, B0); PG8_MMA(1, 1, At, B1); PG8_BAR; PG8_SCHED;
;             PG8_LDB(B0, 1, 0); PG8_LDB(B1, 1, 1); PG8_SCHED; PG8_LDA(At, 1, 0); PG8_STAGE(PG8_SA(0, 1), a2 + hstepA, voffA);
;             PG8_WAIT_V(8); PG8_WAIT_L(0); PG8_BAR; PG8_MMA(0, 0, At, B0); PG8_MMA(0, 1, At, B1); PG8_BAR; PG8_SCHED;
	s_setprio 1
	s_waitcnt lgkmcnt(0)
	v_mfma_f32_16x16x32_bf16 v[62:65], v[188:191], v[130:133], v[62:65]
	v_mfma_f32_16x16x32_bf16 v[58:61], v[188:191], v[164:167], v[58:61]
	v_mfma_f32_16x16x32_bf16 v[46:49], v[196:199], v[130:133], v[46:49]
	v_mfma_f32_16x16x32_bf16 v[42:45], v[196:199], v[164:167], v[42:45]
	v_mfma_f32_16x16x32_bf16 v[28:31], v[220:223], v[130:133], v[28:31]
	v_mfma_f32_16x16x32_bf16 v[24:27], v[220:223], v[164:167], v[24:27]
	v_mfma_f32_16x16x32_bf16 v[12:15], v[228:231], v[130:133], v[12:15]
	v_mfma_f32_16x16x32_bf16 v[8:11], v[228:231], v[164:167], v[8:11]
	v_mfma_f32_16x16x32_bf16 v[62:65], v[192:195], v[134:137], v[62:65]
	v_mfma_f32_16x16x32_bf16 v[58:61], v[192:195], v[168:171], v[58:61]
	v_mfma_f32_16x16x32_bf16 v[46:49], v[216:219], v[134:137], v[46:49]
	v_mfma_f32_16x16x32_bf16 v[42:45], v[216:219], v[168:171], v[42:45]
	v_mfma_f32_16x16x32_bf16 v[28:31], v[224:227], v[134:137], v[28:31]
	v_mfma_f32_16x16x32_bf16 v[24:27], v[224:227], v[168:171], v[24:27]
	v_mfma_f32_16x16x32_bf16 v[12:15], v[232:235], v[134:137], v[12:15]
	v_mfma_f32_16x16x32_bf16 v[8:11], v[232:235], v[168:171], v[8:11]
	v_mfma_f32_16x16x32_bf16 v[54:57], v[188:191], v[172:175], v[54:57]
	v_mfma_f32_16x16x32_bf16 v[50:53], v[188:191], v[180:183], v[50:53]
	v_mfma_f32_16x16x32_bf16 v[38:41], v[196:199], v[172:175], v[38:41]
	v_mfma_f32_16x16x32_bf16 v[34:37], v[196:199], v[180:183], v[34:37]
	v_mfma_f32_16x16x32_bf16 v[20:23], v[220:223], v[172:175], v[20:23]
	v_mfma_f32_16x16x32_bf16 v[16:19], v[220:223], v[180:183], v[16:19]
	v_mfma_f32_16x16x32_bf16 v[4:7], v[228:231], v[172:175], v[4:7]
	v_mfma_f32_16x16x32_bf16 v[0:3], v[228:231], v[180:183], v[0:3]
	v_mfma_f32_16x16x32_bf16 v[54:57], v[192:195], v[176:179], v[54:57]
	v_mfma_f32_16x16x32_bf16 v[50:53], v[192:195], v[184:187], v[50:53]
	v_mfma_f32_16x16x32_bf16 v[38:41], v[216:219], v[176:179], v[38:41]
	v_mfma_f32_16x16x32_bf16 v[34:37], v[216:219], v[184:187], v[34:37]
	v_mfma_f32_16x16x32_bf16 v[20:23], v[224:227], v[176:179], v[20:23]
	v_mfma_f32_16x16x32_bf16 v[16:19], v[224:227], v[184:187], v[16:19]
	v_mfma_f32_16x16x32_bf16 v[4:7], v[232:235], v[176:179], v[4:7]
	v_mfma_f32_16x16x32_bf16 v[0:3], v[232:235], v[184:187], v[0:3]
	s_setprio 0
	s_barrier
	s_add_i32 s50, 0, 0x18000
	v_add_u32_e32 v32, s50, v143
	s_add_i32 s51, 0, 0x1c000
	ds_read_b128 v[130:133], v32
	ds_read_b128 v[134:137], v32 offset:1024
	ds_read_b128 v[164:167], v32 offset:2048
	ds_read_b128 v[168:171], v32 offset:3072
	v_add_u32_e32 v32, s51, v143
	ds_read_b128 v[172:175], v32
	ds_read_b128 v[176:179], v32 offset:1024
	ds_read_b128 v[180:183], v32 offset:2048
	ds_read_b128 v[184:187], v32 offset:3072
	s_add_u32 s24, s24, 0x40000
	s_addc_u32 s25, s25, 0
	s_mov_b32 m0, s37
	v_lshl_add_u64 v[204:205], s[24:25], 0, v[138:139]
	ds_read_b128 v[188:191], v163 offset:32768
	ds_read_b128 v[192:195], v163 offset:33792
	ds_read_b128 v[196:199], v163 offset:34816
	ds_read_b128 v[216:219], v163 offset:35840
	ds_read_b128 v[220:223], v163 offset:36864
	ds_read_b128 v[224:227], v163 offset:37888
	ds_read_b128 v[228:231], v163 offset:38912
	ds_read_b128 v[232:235], v163 offset:39936
	global_load_lds_dwordx4 v[204:205], off
	v_lshl_add_u64 v[204:205], s[24:25], 0, v[140:141]
	s_mov_b32 m0, s38
	s_nop 0
	global_load_lds_dwordx4 v[204:205], off
	s_waitcnt vmcnt(8)
	s_waitcnt lgkmcnt(0)
	s_barrier
	s_setprio 1
	s_waitcnt lgkmcnt(0)
	v_mfma_f32_16x16x32_bf16 v[126:129], v[188:191], v[130:133], v[126:129]
	v_mfma_f32_16x16x32_bf16 v[122:125], v[188:191], v[164:167], v[122:125]
	v_mfma_f32_16x16x32_bf16 v[110:113], v[196:199], v[130:133], v[110:113]
	v_mfma_f32_16x16x32_bf16 v[106:109], v[196:199], v[164:167], v[106:109]
	v_mfma_f32_16x16x32_bf16 v[94:97], v[220:223], v[130:133], v[94:97]
	v_mfma_f32_16x16x32_bf16 v[90:93], v[220:223], v[164:167], v[90:93]
	v_mfma_f32_16x16x32_bf16 v[78:81], v[228:231], v[130:133], v[78:81]
	v_mfma_f32_16x16x32_bf16 v[74:77], v[228:231], v[164:167], v[74:77]
	v_mfma_f32_16x16x32_bf16 v[126:129], v[192:195], v[134:137], v[126:129]
	v_mfma_f32_16x16x32_bf16 v[122:125], v[192:195], v[168:171], v[122:125]
	v_mfma_f32_16x16x32_bf16 v[110:113], v[216:219], v[134:137], v[110:113]
	v_mfma_f32_16x16x32_bf16 v[106:109], v[216:219], v[168:171], v[106:109]
	v_mfma_f32_16x16x32_bf16 v[94:97], v[224:227], v[134:137], v[94:97]
	v_mfma_f32_16x16x32_bf16 v[90:93], v[224:227], v[168:171], v[90:93]
	v_mfma_f32_16x16x32_bf16 v[78:81], v[232:235], v[134:137], v[78:81]
	v_mfma_f32_16x16x32_bf16 v[74:77], v[232:235], v[168:171], v[74:77]
	v_mfma_f32_16x16x32_bf16 v[118:121], v[188:191], v[172:175], v[118:121]
	v_mfma_f32_16x16x32_bf16 v[114:117], v[188:191], v[180:183], v[114:117]
	v_mfma_f32_16x16x32_bf16 v[102:105], v[196:199], v[172:175], v[102:105]
	v_mfma_f32_16x16x32_bf16 v[98:101], v[196:199], v[180:183], v[98:101]
	v_mfma_f32_16x16x32_bf16 v[86:89], v[220:223], v[172:175], v[86:89]
	v_mfma_f32_16x16x32_bf16 v[82:85], v[220:223], v[180:183], v[82:85]
	v_mfma_f32_16x16x32_bf16 v[70:73], v[228:231], v[172:175], v[70:73]
	v_mfma_f32_16x16x32_bf16 v[66:69], v[228:231], v[180:183], v[66:69]
	v_mfma_f32_16x16x32_bf16 v[118:121], v[192:195], v[176:179], v[118:121]
	v_mfma_f32_16x16x32_bf16 v[114:117], v[192:195], v[184:187], v[114:117]
	v_mfma_f32_16x16x32_bf16 v[102:105], v[216:219], v[176:179], v[102:105]
	v_mfma_f32_16x16x32_bf16 v[98:101], v[216:219], v[184:187], v[98:101]
	v_mfma_f32_16x16x32_bf16 v[86:89], v[224:227], v[176:179], v[86:89]
	v_mfma_f32_16x16x32_bf16 v[82:85], v[224:227], v[184:187], v[82:85]
	v_mfma_f32_16x16x32_bf16 v[70:73], v[232:235], v[176:179], v[70:73]
	v_mfma_f32_16x16x32_bf16 v[66:69], v[232:235], v[184:187], v[66:69]
	s_setprio 0
	s_barrier
; #define PG8_STAGE(bufoff, gbase, voff) do { _Pragma("unroll") for (int _i = 0; _i < 2; ++_i) \
;         __builtin_amdgcn_global_load_lds((const unsigned*)((const char*)(gbase) + (voff)[_i]), (PG8_LAS unsigned*)(lds + (bufoff) + ldsw + _i * 8192), 16, 0, 0); } while (0)
; #define PG8_LDA(dst, b, h) do { _Pragma("unroll") for (int m = 0; m < 4; ++m) _Pragma("unroll") for (int k = 0; k < 2; ++k) dst[m][k] = *(const PG8_LAS bf16x8*)(lds + PG8_SA(b, h) + aoff + m * 2048 + k * 1024); } while (0)
; #define PG8_WAIT_V(n) asm volatile("s_waitcnt vmcnt(" #n ")" ::: "memory")
; #define PG8_WAIT_L(n) asm volatile("s_waitcnt lgkmcnt(" #n ")" ::: "memory")
; #define PG8_BAR __builtin_amdgcn_s_barrier()
; #define PG8_SCHED __builtin_amdgcn_sched_barrier(0)
; template <class Epi, bool ALIGN_EPI = true>
; __device__ __forceinline__ void gemm_phase(PG8_LAS unsigned char* lds, const Gemm g, const StaticOrder& S, const Epi& E) {
;     ...
;             PG8_LDA(At, 1, 1); PG8_STAGE(PG8_SB(1, 0), b3, voffB); PG8_STAGE(PG8_SB(1, 1), b3 + hstepB, voffB); PG8_STAGE(PG8_SA(1, 0), a3, voffA);
;             PG8_WAIT_V(8); PG8_WAIT_L(0); PG8_BAR; PG8_MMA(1, 0, At, B0); PG8_MMA(1, 1, At, B1); PG8_BAR; PG8_SCHED;
	s_add_i32 s24, s50, s34
	v_lshl_add_u64 v[146:147], v[146:147], 0, s[60:61]
	s_mov_b32 m0, s24
	ds_read_b128 v[188:191], v163 offset:49152
	ds_read_b128 v[192:195], v163 offset:50176
	ds_read_b128 v[196:199], v163 offset:51200
	ds_read_b128 v[216:219], v163 offset:52224
	ds_read_b128 v[220:223], v163 offset:53248
	ds_read_b128 v[224:227], v163 offset:54272
	ds_read_b128 v[228:231], v163 offset:55296
	ds_read_b128 v[232:235], v163 offset:56320
	global_load_lds_dwordx4 v[146:147], off
	s_add_i32 m0, s24, 0x2000
	s_add_u32 s22, s22, 0x40080
	v_lshl_add_u64 v[146:147], v[148:149], 0, s[60:61]
	s_addc_u32 s23, s23, 0
	s_add_i32 s24, s51, s34
	global_load_lds_dwordx4 v[146:147], off
	v_lshl_add_u64 v[146:147], s[22:23], 0, v[138:139]
	s_mov_b32 m0, s24
	s_nop 0
	global_load_lds_dwordx4 v[146:147], off
	v_lshl_add_u64 v[146:147], s[22:23], 0, v[140:141]
	s_add_i32 m0, s24, 0x2000
	s_nop 0
	global_load_lds_dwordx4 v[146:147], off
	v_lshl_add_u64 v[146:147], v[150:151], 0, s[60:61]
	s_mov_b32 m0, s42
	s_nop 0
	global_load_lds_dwordx4 v[146:147], off
	v_lshl_add_u64 v[146:147], v[200:201], 0, s[60:61]
	s_mov_b32 m0, s43
	s_nop 0
	global_load_lds_dwordx4 v[146:147], off
	s_add_i32 s49, s49, 2
	s_add_u32 s20, s20, 0x100
	s_addc_u32 s21, s21, 0
	s_add_u32 s47, s47, 0x100
	s_addc_u32 s48, s48, 0
	s_add_u32 s22, s20, 0xfffc0080
	s_addc_u32 s23, s21, -1
	s_add_i32 s50, 0, 0x10000
	s_cmp_eq_u32 s49, 12
	s_cselect_b32 s25, s11, s23
	s_cselect_b32 s24, s17, s22
	v_add_u32_e32 v32, s50, v143
	s_cselect_b32 s23, s9, s48
	s_cselect_b32 s22, s19, s47
	s_add_i32 s52, 0, 0x14000
	s_cmp_gt_u32 s49, 13
	s_waitcnt vmcnt(8)
	s_waitcnt lgkmcnt(0)
	s_barrier
	s_setprio 1
	s_waitcnt lgkmcnt(0)
	v_mfma_f32_16x16x32_bf16 v[62:65], v[188:191], v[130:133], v[62:65]
	v_mfma_f32_16x16x32_bf16 v[58:61], v[188:191], v[164:167], v[58:61]
	v_mfma_f32_16x16x32_bf16 v[46:49], v[196:199], v[130:133], v[46:49]
	v_mfma_f32_16x16x32_bf16 v[42:45], v[196:199], v[164:167], v[42:45]
	v_mfma_f32_16x16x32_bf16 v[28:31], v[220:223], v[130:133], v[28:31]
	v_mfma_f32_16x16x32_bf16 v[24:27], v[220:223], v[164:167], v[24:27]
	v_mfma_f32_16x16x32_bf16 v[12:15], v[228:231], v[130:133], v[12:15]
	v_mfma_f32_16x16x32_bf16 v[8:11], v[228:231], v[164:167], v[8:11]
	v_mfma_f32_16x16x32_bf16 v[62:65], v[192:195], v[134:137], v[62:65]
	v_mfma_f32_16x16x32_bf16 v[58:61], v[192:195], v[168:171], v[58:61]
	v_mfma_f32_16x16x32_bf16 v[46:49], v[216:219], v[134:137], v[46:49]
	v_mfma_f32_16x16x32_bf16 v[42:45], v[216:219], v[168:171], v[42:45]
	v_mfma_f32_16x16x32_bf16 v[28:31], v[224:227], v[134:137], v[28:31]
	v_mfma_f32_16x16x32_bf16 v[24:27], v[224:227], v[168:171], v[24:27]
	v_mfma_f32_16x16x32_bf16 v[12:15], v[232:235], v[134:137], v[12:15]
	v_mfma_f32_16x16x32_bf16 v[8:11], v[232:235], v[168:171], v[8:11]
	v_mfma_f32_16x16x32_bf16 v[54:57], v[188:191], v[172:175], v[54:57]
	v_mfma_f32_16x16x32_bf16 v[50:53], v[188:191], v[180:183], v[50:53]
	v_mfma_f32_16x16x32_bf16 v[38:41], v[196:199], v[172:175], v[38:41]
	v_mfma_f32_16x16x32_bf16 v[34:37], v[196:199], v[180:183], v[34:37]
	v_mfma_f32_16x16x32_bf16 v[20:23], v[220:223], v[172:175], v[20:23]
	v_mfma_f32_16x16x32_bf16 v[16:19], v[220:223], v[180:183], v[16:19]
	v_mfma_f32_16x16x32_bf16 v[4:7], v[228:231], v[172:175], v[4:7]
	v_mfma_f32_16x16x32_bf16 v[0:3], v[228:231], v[180:183], v[0:3]
	v_mfma_f32_16x16x32_bf16 v[54:57], v[192:195], v[176:179], v[54:57]
	v_mfma_f32_16x16x32_bf16 v[50:53], v[192:195], v[184:187], v[50:53]
	v_mfma_f32_16x16x32_bf16 v[38:41], v[216:219], v[176:179], v[38:41]
	v_mfma_f32_16x16x32_bf16 v[34:37], v[216:219], v[184:187], v[34:37]
	v_mfma_f32_16x16x32_bf16 v[20:23], v[224:227], v[176:179], v[20:23]
	v_mfma_f32_16x16x32_bf16 v[16:19], v[224:227], v[184:187], v[16:19]
	v_mfma_f32_16x16x32_bf16 v[4:7], v[232:235], v[176:179], v[4:7]
	v_mfma_f32_16x16x32_bf16 v[0:3], v[232:235], v[184:187], v[0:3]
	s_setprio 0
	s_barrier
	s_cbranch_scc0 .Lrot_1004
	s_and_b64 vcc, exec, s[6:7]
	s_cbranch_vccz .LBB0_1007
	s_barrier

; #define PG8_STAGE(bufoff, gbase, voff) do { _Pragma("unroll") for (int _i = 0; _i < 2; ++_i) \
;         __builtin_amdgcn_global_load_lds((const unsigned*)((const char*)(gbase) + (voff)[_i]), (PG8_LAS unsigned*)(lds + (bufoff) + ldsw + _i * 8192), 16, 0, 0); } while (0)
; #define PG8_LDA(dst, b, h) do { _Pragma("unroll") for (int m = 0; m < 4; ++m) _Pragma("unroll") for (int k = 0; k < 2; ++k) dst[m][k] = *(const PG8_LAS bf16x8*)(lds + PG8_SA(b, h) + aoff + m * 2048 + k * 1024); } while (0)
; #define PG8_LDB(dst, b, h) do { _Pragma("unroll") for (int n = 0; n < 2; ++n) _Pragma("unroll") for (int k = 0; k < 2; ++k) dst[n][k] = *(const PG8_LAS bf16x8*)(lds + PG8_SB(b, h) + boff + n * 2048 + k * 1024); } while (0)
; #define PG8_WAIT_V(n) asm volatile("s_waitcnt vmcnt(" #n ")" ::: "memory")
; #define PG8_WAIT_L(n) asm volatile("s_waitcnt lgkmcnt(" #n ")" ::: "memory")
; #define PG8_BAR __builtin_amdgcn_s_barrier()
; #define PG8_SCHED __builtin_amdgcn_sched_barrier(0)
; template <class Epi, bool ALIGN_EPI = true>
; __device__ __forceinline__ void gemm_phase(PG8_LAS unsigned char* lds, const Gemm g, const StaticOrder& S, const Epi& E) {
;     ...
;             PG8_LDB(B0, 0, 0); PG8_LDB(B1, 0, 1); PG8_SCHED; PG8_LDA(At, 0, 0); PG8_STAGE(PG8_SA(1, 1), a1 + hstepA, voffA);
;             PG8_WAIT_V(8); PG8_WAIT_L(0); PG8_BAR; PG8_MMA(0, 0, At, B0); PG8_MMA(0, 1, At, B1); PG8_BAR; PG8_SCHED;
;             PG8_LDA(At, 0, 1); PG8_STAGE(PG8_SB(0, 0), b2, voffB); PG8_STAGE(PG8_SB(0, 1), b2 + hstepB, voffB); PG8_STAGE(PG8_SA(0, 0), a2, voffA);
.Lrot_1829:
	ds_read_b128 v[142:145], v32
	ds_read_b128 v[148:151], v32 offset:1024
	ds_read_b128 v[158:161], v32 offset:2048
	ds_read_b128 v[168:171], v32 offset:3072
	v_add_u32_e32 v32, s43, v165
	ds_read_b128 v[172:175], v32
	ds_read_b128 v[176:179], v32 offset:1024
	ds_read_b128 v[180:183], v32 offset:2048
	ds_read_b128 v[184:187], v32 offset:3072
	v_lshl_add_u64 v[146:147], s[6:7], 0, v[138:139]
	s_add_i32 m0, s59, 0xc000
	ds_read_b128 v[188:191], v167
	ds_read_b128 v[192:195], v167 offset:1024
	ds_read_b128 v[196:199], v167 offset:2048
	ds_read_b128 v[208:211], v167 offset:3072
	ds_read_b128 v[216:219], v167 offset:4096
	ds_read_b128 v[220:223], v167 offset:5120
	ds_read_b128 v[224:227], v167 offset:6144
	ds_read_b128 v[228:231], v167 offset:7168
	global_load_lds_dwordx4 v[146:147], off
	v_lshl_add_u64 v[146:147], s[6:7], 0, v[140:141]
	s_add_i32 m0, s59, 0xe000
	s_nop 0
	global_load_lds_dwordx4 v[146:147], off
	s_waitcnt vmcnt(8)
	s_waitcnt lgkmcnt(0)
	s_barrier
	s_setprio 1
	s_waitcnt lgkmcnt(0)
	v_mfma_f32_16x16x32_bf16 v[126:129], v[142:145], v[188:191], v[126:129]
	v_mfma_f32_16x16x32_bf16 v[122:125], v[158:161], v[188:191], v[122:125]
	v_mfma_f32_16x16x32_bf16 v[110:113], v[142:145], v[196:199], v[110:113]
	v_mfma_f32_16x16x32_bf16 v[106:109], v[158:161], v[196:199], v[106:109]
	v_mfma_f32_16x16x32_bf16 v[94:97], v[142:145], v[216:219], v[94:97]
	v_mfma_f32_16x16x32_bf16 v[90:93], v[158:161], v[216:219], v[90:93]
	v_mfma_f32_16x16x32_bf16 v[78:81], v[142:145], v[224:227], v[78:81]
	v_mfma_f32_16x16x32_bf16 v[74:77], v[158:161], v[224:227], v[74:77]
	v_mfma_f32_16x16x32_bf16 v[126:129], v[148:151], v[192:195], v[126:129]
	v_mfma_f32_16x16x32_bf16 v[122:125], v[168:171], v[192:195], v[122:125]
	v_mfma_f32_16x16x32_bf16 v[110:113], v[148:151], v[208:211], v[110:113]
	v_mfma_f32_16x16x32_bf16 v[106:109], v[168:171], v[208:211], v[106:109]
	v_mfma_f32_16x16x32_bf16 v[94:97], v[148:151], v[220:223], v[94:97]
	v_mfma_f32_16x16x32_bf16 v[90:93], v[168:171], v[220:223], v[90:93]
	v_mfma_f32_16x16x32_bf16 v[78:81], v[148:151], v[228:231], v[78:81]
	v_mfma_f32_16x16x32_bf16 v[74:77], v[168:171], v[228:231], v[74:77]
	v_mfma_f32_16x16x32_bf16 v[118:121], v[172:175], v[188:191], v[118:121]
	v_mfma_f32_16x16x32_bf16 v[114:117], v[180:183], v[188:191], v[114:117]
	v_mfma_f32_16x16x32_bf16 v[102:105], v[172:175], v[196:199], v[102:105]
	v_mfma_f32_16x16x32_bf16 v[98:101], v[180:183], v[196:199], v[98:101]
	v_mfma_f32_16x16x32_bf16 v[86:89], v[172:175], v[216:219], v[86:89]
	v_mfma_f32_16x16x32_bf16 v[82:85], v[180:183], v[216:219], v[82:85]
	v_mfma_f32_16x16x32_bf16 v[70:73], v[172:175], v[224:227], v[70:73]
	v_mfma_f32_16x16x32_bf16 v[66:69], v[180:183], v[224:227], v[66:69]
	v_mfma_f32_16x16x32_bf16 v[118:121], v[176:179], v[192:195], v[118:121]
	v_mfma_f32_16x16x32_bf16 v[114:117], v[184:187], v[192:195], v[114:117]
	v_mfma_f32_16x16x32_bf16 v[102:105], v[176:179], v[208:211], v[102:105]
	v_mfma_f32_16x16x32_bf16 v[98:101], v[184:187], v[208:211], v[98:101]
	v_mfma_f32_16x16x32_bf16 v[86:89], v[176:179], v[220:223], v[86:89]
	v_mfma_f32_16x16x32_bf16 v[82:85], v[184:187], v[220:223], v[82:85]
	v_mfma_f32_16x16x32_bf16 v[70:73], v[176:179], v[228:231], v[70:73]
	v_mfma_f32_16x16x32_bf16 v[66:69], v[184:187], v[228:231], v[66:69]
	s_setprio 0
	s_barrier
	s_add_i32 s75, s75, s53
	v_lshl_add_u64 v[146:147], s[44:45], 0, v[132:133]
	s_mov_b32 m0, s75
	ds_read_b128 v[188:191], v167 offset:16384
	ds_read_b128 v[192:195], v167 offset:17408
	ds_read_b128 v[196:199], v167 offset:18432
	ds_read_b128 v[208:211], v167 offset:19456
	ds_read_b128 v[216:219], v167 offset:20480
	ds_read_b128 v[220:223], v167 offset:21504
	ds_read_b128 v[224:227], v167 offset:22528
	ds_read_b128 v[228:231], v167 offset:23552
	global_load_lds_dwordx4 v[146:147], off
	s_add_i32 m0, s75, 0x2000
	s_add_u32 s76, s44, 0x40000
	v_lshl_add_u64 v[162:163], s[44:45], 0, v[136:137]
	s_addc_u32 s77, s45, 0
	s_add_i32 s43, s43, s53
	global_load_lds_dwordx4 v[162:163], off
	v_lshl_add_u64 v[200:201], s[76:77], 0, v[132:133]
	s_mov_b32 m0, s43
	v_lshl_add_u64 v[204:205], s[46:47], 0, v[134:135]
	global_load_lds_dwordx4 v[200:201], off
	v_lshl_add_u64 v[200:201], s[76:77], 0, v[136:137]
	s_add_i32 m0, s43, 0x2000
	s_nop 0
	global_load_lds_dwordx4 v[200:201], off
	v_lshl_add_u64 v[200:201], s[46:47], 0, v[130:131]
	s_mov_b32 m0, s59
	s_nop 0
	global_load_lds_dwordx4 v[200:201], off
	s_mov_b32 m0, s62
	s_nop 0
	global_load_lds_dwordx4 v[204:205], off
	s_waitcnt vmcnt(8)
	s_waitcnt lgkmcnt(0)
	s_barrier
; #define PG8_STAGE(bufoff, gbase, voff) do { _Pragma("unroll") for (int _i = 0; _i < 2; ++_i) \
;         __builtin_amdgcn_global_load_lds((const unsigned*)((const char*)(gbase) + (voff)[_i]), (PG8_LAS unsigned*)(lds + (bufoff) + ldsw + _i * 8192), 16, 0, 0); } while (0)
; #define PG8_LDA(dst, b, h) do { _Pragma("unroll") for (int m = 0; m < 4; ++m) _Pragma("unroll") for (int k = 0; k < 2; ++k) dst[m][k] = *(const PG8_LAS bf16x8*)(lds + PG8_SA(b, h) + aoff + m * 2048 + k * 1024); } while (0)
; #define PG8_LDB(dst, b, h) do { _Pragma("unroll") for (int n = 0; n < 2; ++n) _Pragma("unroll") for (int k = 0; k < 2; ++k) dst[n][k] = *(const PG8_LAS bf16x8*)(lds + PG8_SB(b, h) + boff + n * 2048 + k * 1024); } while (0)
; #define PG8_WAIT_V(n) asm volatile("s_waitcnt vmcnt(" #n ")" ::: "memory")
; #define PG8_WAIT_L(n) asm volatile("s_waitcnt lgkmcnt(" #n ")" ::: "memory")
; #define PG8_BAR __builtin_amdgcn_s_barrier()
; #define PG8_SCHED __builtin_amdgcn_sched_barrier(0)
; template <class Epi, bool ALIGN_EPI = true>
; __device__ __forceinline__ void gemm_phase(PG8_LAS unsigned char* lds, const Gemm g, const StaticOrder& S, const Epi& E) {
;     ...
;             PG8_WAIT_V(8); PG8_WAIT_L(0); PG8_BAR; PG8_MMA(1, 0, At, B0); PG8_MMA(1, 1, At, B1); PG8_BAR; PG8_SCHED;
;             PG8_LDB(B0, 1, 0); PG8_LDB(B1, 1, 1); PG8_SCHED; PG8_LDA(At, 1, 0); PG8_STAGE(PG8_SA(0, 1), a2 + hstepA, voffA);
;             PG8_WAIT_V(8); PG8_WAIT_L(0); PG8_BAR; PG8_MMA(0, 0, At, B0); PG8_MMA(0, 1, At, B1); PG8_BAR; PG8_SCHED;
	s_setprio 1
	s_waitcnt lgkmcnt(0)
	v_mfma_f32_16x16x32_bf16 v[62:65], v[142:145], v[188:191], v[62:65]
	v_mfma_f32_16x16x32_bf16 v[58:61], v[158:161], v[188:191], v[58:61]
	v_mfma_f32_16x16x32_bf16 v[46:49], v[142:145], v[196:199], v[46:49]
	v_mfma_f32_16x16x32_bf16 v[42:45], v[158:161], v[196:199], v[42:45]
	v_mfma_f32_16x16x32_bf16 v[28:31], v[142:145], v[216:219], v[28:31]
	v_mfma_f32_16x16x32_bf16 v[24:27], v[158:161], v[216:219], v[24:27]
	v_mfma_f32_16x16x32_bf16 v[12:15], v[142:145], v[224:227], v[12:15]
	v_mfma_f32_16x16x32_bf16 v[8:11], v[158:161], v[224:227], v[8:11]
	v_mfma_f32_16x16x32_bf16 v[62:65], v[148:151], v[192:195], v[62:65]
	v_mfma_f32_16x16x32_bf16 v[58:61], v[168:171], v[192:195], v[58:61]
	v_mfma_f32_16x16x32_bf16 v[46:49], v[148:151], v[208:211], v[46:49]
	v_mfma_f32_16x16x32_bf16 v[42:45], v[168:171], v[208:211], v[42:45]
	v_mfma_f32_16x16x32_bf16 v[28:31], v[148:151], v[220:223], v[28:31]
	v_mfma_f32_16x16x32_bf16 v[24:27], v[168:171], v[220:223], v[24:27]
	v_mfma_f32_16x16x32_bf16 v[12:15], v[148:151], v[228:231], v[12:15]
	v_mfma_f32_16x16x32_bf16 v[8:11], v[168:171], v[228:231], v[8:11]
	v_mfma_f32_16x16x32_bf16 v[54:57], v[172:175], v[188:191], v[54:57]
	v_mfma_f32_16x16x32_bf16 v[50:53], v[180:183], v[188:191], v[50:53]
	v_mfma_f32_16x16x32_bf16 v[38:41], v[172:175], v[196:199], v[38:41]
	v_mfma_f32_16x16x32_bf16 v[34:37], v[180:183], v[196:199], v[34:37]
	v_mfma_f32_16x16x32_bf16 v[20:23], v[172:175], v[216:219], v[20:23]
	v_mfma_f32_16x16x32_bf16 v[16:19], v[180:183], v[216:219], v[16:19]
	v_mfma_f32_16x16x32_bf16 v[4:7], v[172:175], v[224:227], v[4:7]
	v_mfma_f32_16x16x32_bf16 v[0:3], v[180:183], v[224:227], v[0:3]
	v_mfma_f32_16x16x32_bf16 v[54:57], v[176:179], v[192:195], v[54:57]
	v_mfma_f32_16x16x32_bf16 v[50:53], v[184:187], v[192:195], v[50:53]
	v_mfma_f32_16x16x32_bf16 v[38:41], v[176:179], v[208:211], v[38:41]
	v_mfma_f32_16x16x32_bf16 v[34:37], v[184:187], v[208:211], v[34:37]
	v_mfma_f32_16x16x32_bf16 v[20:23], v[176:179], v[220:223], v[20:23]
	v_mfma_f32_16x16x32_bf16 v[16:19], v[184:187], v[220:223], v[16:19]
	v_mfma_f32_16x16x32_bf16 v[4:7], v[176:179], v[228:231], v[4:7]
	v_mfma_f32_16x16x32_bf16 v[0:3], v[184:187], v[228:231], v[0:3]
	s_setprio 0
	s_barrier
	s_add_i32 s43, 0, 0x18000
	v_add_u32_e32 v32, s43, v165
	s_add_i32 s75, 0, 0x1c000
	ds_read_b128 v[142:145], v32
	ds_read_b128 v[148:151], v32 offset:1024
	ds_read_b128 v[158:161], v32 offset:2048
	ds_read_b128 v[168:171], v32 offset:3072
	v_add_u32_e32 v32, s75, v165
	ds_read_b128 v[172:175], v32
	ds_read_b128 v[176:179], v32 offset:1024
	ds_read_b128 v[180:183], v32 offset:2048
	ds_read_b128 v[184:187], v32 offset:3072
	s_add_u32 s46, s46, 0x40000
	s_addc_u32 s47, s47, 0
	s_mov_b32 m0, s63
	v_lshl_add_u64 v[206:207], s[46:47], 0, v[130:131]
	ds_read_b128 v[188:191], v167 offset:32768
	ds_read_b128 v[192:195], v167 offset:33792
	ds_read_b128 v[196:199], v167 offset:34816
	ds_read_b128 v[208:211], v167 offset:35840
	ds_read_b128 v[216:219], v167 offset:36864
	ds_read_b128 v[220:223], v167 offset:37888
	ds_read_b128 v[224:227], v167 offset:38912
	ds_read_b128 v[228:231], v167 offset:39936
	global_load_lds_dwordx4 v[206:207], off
	v_lshl_add_u64 v[206:207], s[46:47], 0, v[134:135]
	s_mov_b32 m0, s66
	s_nop 0
	global_load_lds_dwordx4 v[206:207], off
	s_waitcnt vmcnt(8)
	s_waitcnt lgkmcnt(0)
	s_barrier
	s_setprio 1
	s_waitcnt lgkmcnt(0)
	v_mfma_f32_16x16x32_bf16 v[126:129], v[142:145], v[188:191], v[126:129]
	v_mfma_f32_16x16x32_bf16 v[122:125], v[158:161], v[188:191], v[122:125]
	v_mfma_f32_16x16x32_bf16 v[110:113], v[142:145], v[196:199], v[110:113]
	v_mfma_f32_16x16x32_bf16 v[106:109], v[158:161], v[196:199], v[106:109]
	v_mfma_f32_16x16x32_bf16 v[94:97], v[142:145], v[216:219], v[94:97]
	v_mfma_f32_16x16x32_bf16 v[90:93], v[158:161], v[216:219], v[90:93]
	v_mfma_f32_16x16x32_bf16 v[78:81], v[142:145], v[224:227], v[78:81]
	v_mfma_f32_16x16x32_bf16 v[74:77], v[158:161], v[224:227], v[74:77]
	v_mfma_f32_16x16x32_bf16 v[126:129], v[148:151], v[192:195], v[126:129]
	v_mfma_f32_16x16x32_bf16 v[122:125], v[168:171], v[192:195], v[122:125]
	v_mfma_f32_16x16x32_bf16 v[110:113], v[148:151], v[208:211], v[110:113]
	v_mfma_f32_16x16x32_bf16 v[106:109], v[168:171], v[208:211], v[106:109]
	v_mfma_f32_16x16x32_bf16 v[94:97], v[148:151], v[220:223], v[94:97]
	v_mfma_f32_16x16x32_bf16 v[90:93], v[168:171], v[220:223], v[90:93]
	v_mfma_f32_16x16x32_bf16 v[78:81], v[148:151], v[228:231], v[78:81]
	v_mfma_f32_16x16x32_bf16 v[74:77], v[168:171], v[228:231], v[74:77]
	v_mfma_f32_16x16x32_bf16 v[118:121], v[172:175], v[188:191], v[118:121]
	v_mfma_f32_16x16x32_bf16 v[114:117], v[180:183], v[188:191], v[114:117]
	v_mfma_f32_16x16x32_bf16 v[102:105], v[172:175], v[196:199], v[102:105]
	v_mfma_f32_16x16x32_bf16 v[98:101], v[180:183], v[196:199], v[98:101]
	v_mfma_f32_16x16x32_bf16 v[86:89], v[172:175], v[216:219], v[86:89]
	v_mfma_f32_16x16x32_bf16 v[82:85], v[180:183], v[216:219], v[82:85]
	v_mfma_f32_16x16x32_bf16 v[70:73], v[172:175], v[224:227], v[70:73]
	v_mfma_f32_16x16x32_bf16 v[66:69], v[180:183], v[224:227], v[66:69]
	v_mfma_f32_16x16x32_bf16 v[118:121], v[176:179], v[192:195], v[118:121]
	v_mfma_f32_16x16x32_bf16 v[114:117], v[184:187], v[192:195], v[114:117]
	v_mfma_f32_16x16x32_bf16 v[102:105], v[176:179], v[208:211], v[102:105]
	v_mfma_f32_16x16x32_bf16 v[98:101], v[184:187], v[208:211], v[98:101]
	v_mfma_f32_16x16x32_bf16 v[86:89], v[176:179], v[220:223], v[86:89]
	v_mfma_f32_16x16x32_bf16 v[82:85], v[184:187], v[220:223], v[82:85]
	v_mfma_f32_16x16x32_bf16 v[70:73], v[176:179], v[228:231], v[70:73]
	v_mfma_f32_16x16x32_bf16 v[66:69], v[184:187], v[228:231], v[66:69]
	s_setprio 0
	s_barrier
; #define PG8_STAGE(bufoff, gbase, voff) do { _Pragma("unroll") for (int _i = 0; _i < 2; ++_i) \
;         __builtin_amdgcn_global_load_lds((const unsigned*)((const char*)(gbase) + (voff)[_i]), (PG8_LAS unsigned*)(lds + (bufoff) + ldsw + _i * 8192), 16, 0, 0); } while (0)
; #define PG8_LDA(dst, b, h) do { _Pragma("unroll") for (int m = 0; m < 4; ++m) _Pragma("unroll") for (int k = 0; k < 2; ++k) dst[m][k] = *(const PG8_LAS bf16x8*)(lds + PG8_SA(b, h) + aoff + m * 2048 + k * 1024); } while (0)
; #define PG8_WAIT_V(n) asm volatile("s_waitcnt vmcnt(" #n ")" ::: "memory")
; #define PG8_WAIT_L(n) asm volatile("s_waitcnt lgkmcnt(" #n ")" ::: "memory")
; #define PG8_BAR __builtin_amdgcn_s_barrier()
; #define PG8_SCHED __builtin_amdgcn_sched_barrier(0)
; template <class Epi, bool ALIGN_EPI = true>
; __device__ __forceinline__ void gemm_phase(PG8_LAS unsigned char* lds, const Gemm g, const StaticOrder& S, const Epi& E) {
;     ...
;             PG8_LDA(At, 1, 1); PG8_STAGE(PG8_SB(1, 0), b3, voffB); PG8_STAGE(PG8_SB(1, 1), b3 + hstepB, voffB); PG8_STAGE(PG8_SA(1, 0), a3, voffA);
;             PG8_WAIT_V(8); PG8_WAIT_L(0); PG8_BAR; PG8_MMA(1, 0, At, B0); PG8_MMA(1, 1, At, B1); PG8_BAR; PG8_SCHED;
	s_add_i32 s43, s43, s53
	v_lshl_add_u64 v[146:147], v[146:147], 0, s[60:61]
	s_mov_b32 m0, s43
	ds_read_b128 v[188:191], v167 offset:49152
	ds_read_b128 v[192:195], v167 offset:50176
	ds_read_b128 v[196:199], v167 offset:51200
	ds_read_b128 v[208:211], v167 offset:52224
	ds_read_b128 v[216:219], v167 offset:53248
	ds_read_b128 v[220:223], v167 offset:54272
	ds_read_b128 v[224:227], v167 offset:55296
	ds_read_b128 v[228:231], v167 offset:56320
	global_load_lds_dwordx4 v[146:147], off
	s_add_i32 m0, s43, 0x2000
	s_add_u32 s44, s44, 0x40080
	v_lshl_add_u64 v[146:147], v[162:163], 0, s[60:61]
	s_addc_u32 s45, s45, 0
	s_add_i32 s43, s75, s53
	global_load_lds_dwordx4 v[146:147], off
	v_lshl_add_u64 v[146:147], s[44:45], 0, v[132:133]
	s_mov_b32 m0, s43
	s_nop 0
	global_load_lds_dwordx4 v[146:147], off
	v_lshl_add_u64 v[146:147], s[44:45], 0, v[136:137]
	s_add_i32 m0, s43, 0x2000
	s_nop 0
	global_load_lds_dwordx4 v[146:147], off
	v_lshl_add_u64 v[146:147], v[200:201], 0, s[60:61]
	s_mov_b32 m0, s70
	s_nop 0
	global_load_lds_dwordx4 v[146:147], off
	v_lshl_add_u64 v[146:147], v[204:205], 0, s[60:61]
	s_mov_b32 m0, s71
	s_nop 0
	global_load_lds_dwordx4 v[146:147], off
	s_add_i32 s37, s37, 2
	s_add_u32 s6, s6, 0x100
	s_addc_u32 s7, s7, 0
	s_add_u32 s9, s9, 0x100
	s_addc_u32 s35, s35, 0
	s_add_u32 s43, s6, 0xfffc0080
	s_addc_u32 s44, s7, -1
	s_add_i32 s75, 0, 0x10000
	s_cmp_eq_u32 s37, 12
	s_cselect_b32 s47, s39, s44
	s_cselect_b32 s46, s38, s43
	v_add_u32_e32 v32, s75, v165
	s_cselect_b32 s45, s41, s35
	s_cselect_b32 s44, s40, s9
	s_add_i32 s43, 0, 0x14000
	s_cmp_gt_u32 s37, 13
	s_waitcnt vmcnt(8)
	s_waitcnt lgkmcnt(0)
	s_barrier
	s_setprio 1
	s_waitcnt lgkmcnt(0)
	v_mfma_f32_16x16x32_bf16 v[62:65], v[142:145], v[188:191], v[62:65]
	v_mfma_f32_16x16x32_bf16 v[58:61], v[158:161], v[188:191], v[58:61]
	v_mfma_f32_16x16x32_bf16 v[46:49], v[142:145], v[196:199], v[46:49]
	v_mfma_f32_16x16x32_bf16 v[42:45], v[158:161], v[196:199], v[42:45]
	v_mfma_f32_16x16x32_bf16 v[28:31], v[142:145], v[216:219], v[28:31]
	v_mfma_f32_16x16x32_bf16 v[24:27], v[158:161], v[216:219], v[24:27]
	v_mfma_f32_16x16x32_bf16 v[12:15], v[142:145], v[224:227], v[12:15]
	v_mfma_f32_16x16x32_bf16 v[8:11], v[158:161], v[224:227], v[8:11]
	v_mfma_f32_16x16x32_bf16 v[62:65], v[148:151], v[192:195], v[62:65]
	v_mfma_f32_16x16x32_bf16 v[58:61], v[168:171], v[192:195], v[58:61]
	v_mfma_f32_16x16x32_bf16 v[46:49], v[148:151], v[208:211], v[46:49]
	v_mfma_f32_16x16x32_bf16 v[42:45], v[168:171], v[208:211], v[42:45]
	v_mfma_f32_16x16x32_bf16 v[28:31], v[148:151], v[220:223], v[28:31]
	v_mfma_f32_16x16x32_bf16 v[24:27], v[168:171], v[220:223], v[24:27]
	v_mfma_f32_16x16x32_bf16 v[12:15], v[148:151], v[228:231], v[12:15]
	v_mfma_f32_16x16x32_bf16 v[8:11], v[168:171], v[228:231], v[8:11]
	v_mfma_f32_16x16x32_bf16 v[54:57], v[172:175], v[188:191], v[54:57]
	v_mfma_f32_16x16x32_bf16 v[50:53], v[180:183], v[188:191], v[50:53]
	v_mfma_f32_16x16x32_bf16 v[38:41], v[172:175], v[196:199], v[38:41]
	v_mfma_f32_16x16x32_bf16 v[34:37], v[180:183], v[196:199], v[34:37]
	v_mfma_f32_16x16x32_bf16 v[20:23], v[172:175], v[216:219], v[20:23]
	v_mfma_f32_16x16x32_bf16 v[16:19], v[180:183], v[216:219], v[16:19]
	v_mfma_f32_16x16x32_bf16 v[4:7], v[172:175], v[224:227], v[4:7]
	v_mfma_f32_16x16x32_bf16 v[0:3], v[180:183], v[224:227], v[0:3]
	v_mfma_f32_16x16x32_bf16 v[54:57], v[176:179], v[192:195], v[54:57]
	v_mfma_f32_16x16x32_bf16 v[50:53], v[184:187], v[192:195], v[50:53]
	v_mfma_f32_16x16x32_bf16 v[38:41], v[176:179], v[208:211], v[38:41]
	v_mfma_f32_16x16x32_bf16 v[34:37], v[184:187], v[208:211], v[34:37]
	v_mfma_f32_16x16x32_bf16 v[20:23], v[176:179], v[220:223], v[20:23]
	v_mfma_f32_16x16x32_bf16 v[16:19], v[184:187], v[220:223], v[16:19]
	v_mfma_f32_16x16x32_bf16 v[4:7], v[176:179], v[228:231], v[4:7]
	v_mfma_f32_16x16x32_bf16 v[0:3], v[184:187], v[228:231], v[0:3]
	s_setprio 0
	s_barrier
	s_cbranch_scc0 .Lrot_1829
	s_and_b64 vcc, exec, s[26:27]
	s_cbranch_vccz .LBB0_1832
	s_barrier

; #define PG8_STAGE(bufoff, gbase, voff) do { _Pragma("unroll") for (int _i = 0; _i < 2; ++_i) \
;         __builtin_amdgcn_global_load_lds((const unsigned*)((const char*)(gbase) + (voff)[_i]), (PG8_LAS unsigned*)(lds + (bufoff) + ldsw + _i * 8192), 16, 0, 0); } while (0)
; #define PG8_LDA(dst, b, h) do { _Pragma("unroll") for (int m = 0; m < 4; ++m) _Pragma("unroll") for (int k = 0; k < 2; ++k) dst[m][k] = *(const PG8_LAS bf16x8*)(lds + PG8_SA(b, h) + aoff + m * 2048 + k * 1024); } while (0)
; #define PG8_LDB(dst, b, h) do { _Pragma("unroll") for (int n = 0; n < 2; ++n) _Pragma("unroll") for (int k = 0; k < 2; ++k) dst[n][k] = *(const PG8_LAS bf16x8*)(lds + PG8_SB(b, h) + boff + n * 2048 + k * 1024); } while (0)
; #define PG8_WAIT_V(n) asm volatile("s_waitcnt vmcnt(" #n ")" ::: "memory")
; #define PG8_WAIT_L(n) asm volatile("s_waitcnt lgkmcnt(" #n ")" ::: "memory")
; #define PG8_BAR __builtin_amdgcn_s_barrier()
; #define PG8_SCHED __builtin_amdgcn_sched_barrier(0)
; template <class Epi, bool ALIGN_EPI = true>
; __device__ __forceinline__ void gemm_phase(PG8_LAS unsigned char* lds, const Gemm g, const StaticOrder& S, const Epi& E) {
;     ...
;             PG8_LDB(B0, 0, 0); PG8_LDB(B1, 0, 1); PG8_SCHED; PG8_LDA(At, 0, 0); PG8_STAGE(PG8_SA(1, 1), a1 + hstepA, voffA);
;             PG8_WAIT_V(8); PG8_WAIT_L(0); PG8_BAR; PG8_MMA(0, 0, At, B0); PG8_MMA(0, 1, At, B1); PG8_BAR; PG8_SCHED;
;             PG8_LDA(At, 0, 1); PG8_STAGE(PG8_SB(0, 0), b2, voffB); PG8_STAGE(PG8_SB(0, 1), b2 + hstepB, voffB); PG8_STAGE(PG8_SA(0, 0), a2, voffA);
.Lrot_2032:
	ds_read_b128 v[140:143], v144
	ds_read_b128 v[148:151], v144 offset:1024
	ds_read_b128 v[162:165], v144 offset:2048
	ds_read_b128 v[166:169], v144 offset:3072
	v_add_u32_e32 v144, s90, v159
	ds_read_b128 v[170:173], v144
	ds_read_b128 v[174:177], v144 offset:1024
	ds_read_b128 v[178:181], v144 offset:2048
	ds_read_b128 v[182:185], v144 offset:3072
	v_lshl_add_u64 v[144:145], s[40:41], 0, v[136:137]
	s_add_i32 m0, s39, 0xc000
	ds_read_b128 v[186:189], v161
	ds_read_b128 v[190:193], v161 offset:1024
	ds_read_b128 v[194:197], v161 offset:2048
	ds_read_b128 v[198:201], v161 offset:3072
	ds_read_b128 v[208:211], v161 offset:4096
	ds_read_b128 v[216:219], v161 offset:5120
	ds_read_b128 v[220:223], v161 offset:6144
	ds_read_b128 v[224:227], v161 offset:7168
	global_load_lds_dwordx4 v[144:145], off
	v_lshl_add_u64 v[144:145], s[40:41], 0, v[138:139]
	s_add_i32 m0, s39, 0xe000
	s_nop 0
	global_load_lds_dwordx4 v[144:145], off
	s_waitcnt vmcnt(8)
	s_waitcnt lgkmcnt(0)
	s_barrier
	s_setprio 1
	s_waitcnt lgkmcnt(0)
	v_mfma_f32_16x16x32_bf16 v[126:129], v[140:143], v[186:189], v[126:129]
	v_mfma_f32_16x16x32_bf16 v[122:125], v[162:165], v[186:189], v[122:125]
	v_mfma_f32_16x16x32_bf16 v[110:113], v[140:143], v[194:197], v[110:113]
	v_mfma_f32_16x16x32_bf16 v[106:109], v[162:165], v[194:197], v[106:109]
	v_mfma_f32_16x16x32_bf16 v[94:97], v[140:143], v[208:211], v[94:97]
	v_mfma_f32_16x16x32_bf16 v[90:93], v[162:165], v[208:211], v[90:93]
	v_mfma_f32_16x16x32_bf16 v[78:81], v[140:143], v[220:223], v[78:81]
	v_mfma_f32_16x16x32_bf16 v[74:77], v[162:165], v[220:223], v[74:77]
	v_mfma_f32_16x16x32_bf16 v[126:129], v[148:151], v[190:193], v[126:129]
	v_mfma_f32_16x16x32_bf16 v[122:125], v[166:169], v[190:193], v[122:125]
	v_mfma_f32_16x16x32_bf16 v[110:113], v[148:151], v[198:201], v[110:113]
	v_mfma_f32_16x16x32_bf16 v[106:109], v[166:169], v[198:201], v[106:109]
	v_mfma_f32_16x16x32_bf16 v[94:97], v[148:151], v[216:219], v[94:97]
	v_mfma_f32_16x16x32_bf16 v[90:93], v[166:169], v[216:219], v[90:93]
	v_mfma_f32_16x16x32_bf16 v[78:81], v[148:151], v[224:227], v[78:81]
	v_mfma_f32_16x16x32_bf16 v[74:77], v[166:169], v[224:227], v[74:77]
	v_mfma_f32_16x16x32_bf16 v[118:121], v[170:173], v[186:189], v[118:121]
	v_mfma_f32_16x16x32_bf16 v[114:117], v[178:181], v[186:189], v[114:117]
	v_mfma_f32_16x16x32_bf16 v[102:105], v[170:173], v[194:197], v[102:105]
	v_mfma_f32_16x16x32_bf16 v[98:101], v[178:181], v[194:197], v[98:101]
	v_mfma_f32_16x16x32_bf16 v[86:89], v[170:173], v[208:211], v[86:89]
	v_mfma_f32_16x16x32_bf16 v[82:85], v[178:181], v[208:211], v[82:85]
	v_mfma_f32_16x16x32_bf16 v[70:73], v[170:173], v[220:223], v[70:73]
	v_mfma_f32_16x16x32_bf16 v[66:69], v[178:181], v[220:223], v[66:69]
	v_mfma_f32_16x16x32_bf16 v[118:121], v[174:177], v[190:193], v[118:121]
	v_mfma_f32_16x16x32_bf16 v[114:117], v[182:185], v[190:193], v[114:117]
	v_mfma_f32_16x16x32_bf16 v[102:105], v[174:177], v[198:201], v[102:105]
	v_mfma_f32_16x16x32_bf16 v[98:101], v[182:185], v[198:201], v[98:101]
	v_mfma_f32_16x16x32_bf16 v[86:89], v[174:177], v[216:219], v[86:89]
	v_mfma_f32_16x16x32_bf16 v[82:85], v[182:185], v[216:219], v[82:85]
	v_mfma_f32_16x16x32_bf16 v[70:73], v[174:177], v[224:227], v[70:73]
	v_mfma_f32_16x16x32_bf16 v[66:69], v[182:185], v[224:227], v[66:69]
	s_setprio 0
	s_barrier
	s_add_i32 s87, s87, s53
	v_lshl_add_u64 v[144:145], s[42:43], 0, v[32:33]
	s_mov_b32 m0, s87
	ds_read_b128 v[186:189], v161 offset:16384
	ds_read_b128 v[190:193], v161 offset:17408
	ds_read_b128 v[194:197], v161 offset:18432
	ds_read_b128 v[198:201], v161 offset:19456
	ds_read_b128 v[208:211], v161 offset:20480
	ds_read_b128 v[216:219], v161 offset:21504
	ds_read_b128 v[220:223], v161 offset:22528
	ds_read_b128 v[224:227], v161 offset:23552
	global_load_lds_dwordx4 v[144:145], off
	s_add_i32 m0, s87, 0x2000
	s_add_u32 s88, s42, 0x40000
	v_lshl_add_u64 v[146:147], s[42:43], 0, v[134:135]
	s_addc_u32 s89, s43, 0
	s_add_i32 s87, s90, s53
	global_load_lds_dwordx4 v[146:147], off
	v_lshl_add_u64 v[204:205], s[88:89], 0, v[32:33]
	s_mov_b32 m0, s87
	v_lshl_add_u64 v[206:207], s[44:45], 0, v[132:133]
	global_load_lds_dwordx4 v[204:205], off
	v_lshl_add_u64 v[204:205], s[88:89], 0, v[134:135]
	s_add_i32 m0, s87, 0x2000
	s_nop 0
	global_load_lds_dwordx4 v[204:205], off
	v_lshl_add_u64 v[204:205], s[44:45], 0, v[130:131]
	s_mov_b32 m0, s39
	s_nop 0
	global_load_lds_dwordx4 v[204:205], off
	s_mov_b32 m0, s67
	s_nop 0
	global_load_lds_dwordx4 v[206:207], off
	s_waitcnt vmcnt(8)
	s_waitcnt lgkmcnt(0)
	s_barrier
; #define PG8_STAGE(bufoff, gbase, voff) do { _Pragma("unroll") for (int _i = 0; _i < 2; ++_i) \
;         __builtin_amdgcn_global_load_lds((const unsigned*)((const char*)(gbase) + (voff)[_i]), (PG8_LAS unsigned*)(lds + (bufoff) + ldsw + _i * 8192), 16, 0, 0); } while (0)
; #define PG8_LDA(dst, b, h) do { _Pragma("unroll") for (int m = 0; m < 4; ++m) _Pragma("unroll") for (int k = 0; k < 2; ++k) dst[m][k] = *(const PG8_LAS bf16x8*)(lds + PG8_SA(b, h) + aoff + m * 2048 + k * 1024); } while (0)
; #define PG8_LDB(dst, b, h) do { _Pragma("unroll") for (int n = 0; n < 2; ++n) _Pragma("unroll") for (int k = 0; k < 2; ++k) dst[n][k] = *(const PG8_LAS bf16x8*)(lds + PG8_SB(b, h) + boff + n * 2048 + k * 1024); } while (0)
; #define PG8_WAIT_V(n) asm volatile("s_waitcnt vmcnt(" #n ")" ::: "memory")
; #define PG8_WAIT_L(n) asm volatile("s_waitcnt lgkmcnt(" #n ")" ::: "memory")
; #define PG8_BAR __builtin_amdgcn_s_barrier()
; #define PG8_SCHED __builtin_amdgcn_sched_barrier(0)
; template <class Epi, bool ALIGN_EPI = true>
; __device__ __forceinline__ void gemm_phase(PG8_LAS unsigned char* lds, const Gemm g, const StaticOrder& S, const Epi& E) {
;     ...
;             PG8_WAIT_V(8); PG8_WAIT_L(0); PG8_BAR; PG8_MMA(1, 0, At, B0); PG8_MMA(1, 1, At, B1); PG8_BAR; PG8_SCHED;
;             PG8_LDB(B0, 1, 0); PG8_LDB(B1, 1, 1); PG8_SCHED; PG8_LDA(At, 1, 0); PG8_STAGE(PG8_SA(0, 1), a2 + hstepA, voffA);
;             PG8_WAIT_V(8); PG8_WAIT_L(0); PG8_BAR; PG8_MMA(0, 0, At, B0); PG8_MMA(0, 1, At, B1); PG8_BAR; PG8_SCHED;
	s_setprio 1
	s_waitcnt lgkmcnt(0)
	v_mfma_f32_16x16x32_bf16 v[62:65], v[140:143], v[186:189], v[62:65]
	v_mfma_f32_16x16x32_bf16 v[58:61], v[162:165], v[186:189], v[58:61]
	v_mfma_f32_16x16x32_bf16 v[46:49], v[140:143], v[194:197], v[46:49]
	v_mfma_f32_16x16x32_bf16 v[42:45], v[162:165], v[194:197], v[42:45]
	v_mfma_f32_16x16x32_bf16 v[28:31], v[140:143], v[208:211], v[28:31]
	v_mfma_f32_16x16x32_bf16 v[24:27], v[162:165], v[208:211], v[24:27]
	v_mfma_f32_16x16x32_bf16 v[12:15], v[140:143], v[220:223], v[12:15]
	v_mfma_f32_16x16x32_bf16 v[8:11], v[162:165], v[220:223], v[8:11]
	v_mfma_f32_16x16x32_bf16 v[62:65], v[148:151], v[190:193], v[62:65]
	v_mfma_f32_16x16x32_bf16 v[58:61], v[166:169], v[190:193], v[58:61]
	v_mfma_f32_16x16x32_bf16 v[46:49], v[148:151], v[198:201], v[46:49]
	v_mfma_f32_16x16x32_bf16 v[42:45], v[166:169], v[198:201], v[42:45]
	v_mfma_f32_16x16x32_bf16 v[28:31], v[148:151], v[216:219], v[28:31]
	v_mfma_f32_16x16x32_bf16 v[24:27], v[166:169], v[216:219], v[24:27]
	v_mfma_f32_16x16x32_bf16 v[12:15], v[148:151], v[224:227], v[12:15]
	v_mfma_f32_16x16x32_bf16 v[8:11], v[166:169], v[224:227], v[8:11]
	v_mfma_f32_16x16x32_bf16 v[54:57], v[170:173], v[186:189], v[54:57]
	v_mfma_f32_16x16x32_bf16 v[50:53], v[178:181], v[186:189], v[50:53]
	v_mfma_f32_16x16x32_bf16 v[38:41], v[170:173], v[194:197], v[38:41]
	v_mfma_f32_16x16x32_bf16 v[34:37], v[178:181], v[194:197], v[34:37]
	v_mfma_f32_16x16x32_bf16 v[20:23], v[170:173], v[208:211], v[20:23]
	v_mfma_f32_16x16x32_bf16 v[16:19], v[178:181], v[208:211], v[16:19]
	v_mfma_f32_16x16x32_bf16 v[4:7], v[170:173], v[220:223], v[4:7]
	v_mfma_f32_16x16x32_bf16 v[0:3], v[178:181], v[220:223], v[0:3]
	v_mfma_f32_16x16x32_bf16 v[54:57], v[174:177], v[190:193], v[54:57]
	v_mfma_f32_16x16x32_bf16 v[50:53], v[182:185], v[190:193], v[50:53]
	v_mfma_f32_16x16x32_bf16 v[38:41], v[174:177], v[198:201], v[38:41]
	v_mfma_f32_16x16x32_bf16 v[34:37], v[182:185], v[198:201], v[34:37]
	v_mfma_f32_16x16x32_bf16 v[20:23], v[174:177], v[216:219], v[20:23]
	v_mfma_f32_16x16x32_bf16 v[16:19], v[182:185], v[216:219], v[16:19]
	v_mfma_f32_16x16x32_bf16 v[4:7], v[174:177], v[224:227], v[4:7]
	v_mfma_f32_16x16x32_bf16 v[0:3], v[182:185], v[224:227], v[0:3]
	s_setprio 0
	s_barrier
	s_add_i32 s87, 0, 0x18000
	v_add_u32_e32 v154, s87, v159
	s_add_i32 s88, 0, 0x1c000
	ds_read_b128 v[140:143], v154
	ds_read_b128 v[148:151], v154 offset:1024
	ds_read_b128 v[162:165], v154 offset:2048
	ds_read_b128 v[166:169], v154 offset:3072
	v_add_u32_e32 v154, s88, v159
	ds_read_b128 v[170:173], v154
	ds_read_b128 v[174:177], v154 offset:1024
	ds_read_b128 v[178:181], v154 offset:2048
	ds_read_b128 v[182:185], v154 offset:3072
	s_add_u32 s44, s44, 0x40000
	s_addc_u32 s45, s45, 0
	s_mov_b32 m0, s70
	v_lshl_add_u64 v[228:229], s[44:45], 0, v[130:131]
	ds_read_b128 v[186:189], v161 offset:32768
	ds_read_b128 v[190:193], v161 offset:33792
	ds_read_b128 v[194:197], v161 offset:34816
	ds_read_b128 v[198:201], v161 offset:35840
	ds_read_b128 v[208:211], v161 offset:36864
	ds_read_b128 v[216:219], v161 offset:37888
	ds_read_b128 v[220:223], v161 offset:38912
	ds_read_b128 v[224:227], v161 offset:39936
	global_load_lds_dwordx4 v[228:229], off
	v_lshl_add_u64 v[228:229], s[44:45], 0, v[132:133]
	s_mov_b32 m0, s71
	s_nop 0
	global_load_lds_dwordx4 v[228:229], off
	s_waitcnt vmcnt(8)
	s_waitcnt lgkmcnt(0)
	s_barrier
	s_setprio 1
	s_waitcnt lgkmcnt(0)
	v_mfma_f32_16x16x32_bf16 v[126:129], v[140:143], v[186:189], v[126:129]
	v_mfma_f32_16x16x32_bf16 v[122:125], v[162:165], v[186:189], v[122:125]
	v_mfma_f32_16x16x32_bf16 v[110:113], v[140:143], v[194:197], v[110:113]
	v_mfma_f32_16x16x32_bf16 v[106:109], v[162:165], v[194:197], v[106:109]
	v_mfma_f32_16x16x32_bf16 v[94:97], v[140:143], v[208:211], v[94:97]
	v_mfma_f32_16x16x32_bf16 v[90:93], v[162:165], v[208:211], v[90:93]
	v_mfma_f32_16x16x32_bf16 v[78:81], v[140:143], v[220:223], v[78:81]
	v_mfma_f32_16x16x32_bf16 v[74:77], v[162:165], v[220:223], v[74:77]
	v_mfma_f32_16x16x32_bf16 v[126:129], v[148:151], v[190:193], v[126:129]
	v_mfma_f32_16x16x32_bf16 v[122:125], v[166:169], v[190:193], v[122:125]
	v_mfma_f32_16x16x32_bf16 v[110:113], v[148:151], v[198:201], v[110:113]
	v_mfma_f32_16x16x32_bf16 v[106:109], v[166:169], v[198:201], v[106:109]
	v_mfma_f32_16x16x32_bf16 v[94:97], v[148:151], v[216:219], v[94:97]
	v_mfma_f32_16x16x32_bf16 v[90:93], v[166:169], v[216:219], v[90:93]
	v_mfma_f32_16x16x32_bf16 v[78:81], v[148:151], v[224:227], v[78:81]
	v_mfma_f32_16x16x32_bf16 v[74:77], v[166:169], v[224:227], v[74:77]
	v_mfma_f32_16x16x32_bf16 v[118:121], v[170:173], v[186:189], v[118:121]
	v_mfma_f32_16x16x32_bf16 v[114:117], v[178:181], v[186:189], v[114:117]
	v_mfma_f32_16x16x32_bf16 v[102:105], v[170:173], v[194:197], v[102:105]
	v_mfma_f32_16x16x32_bf16 v[98:101], v[178:181], v[194:197], v[98:101]
	v_mfma_f32_16x16x32_bf16 v[86:89], v[170:173], v[208:211], v[86:89]
	v_mfma_f32_16x16x32_bf16 v[82:85], v[178:181], v[208:211], v[82:85]
	v_mfma_f32_16x16x32_bf16 v[70:73], v[170:173], v[220:223], v[70:73]
	v_mfma_f32_16x16x32_bf16 v[66:69], v[178:181], v[220:223], v[66:69]
	v_mfma_f32_16x16x32_bf16 v[118:121], v[174:177], v[190:193], v[118:121]
	v_mfma_f32_16x16x32_bf16 v[114:117], v[182:185], v[190:193], v[114:117]
	v_mfma_f32_16x16x32_bf16 v[102:105], v[174:177], v[198:201], v[102:105]
	v_mfma_f32_16x16x32_bf16 v[98:101], v[182:185], v[198:201], v[98:101]
	v_mfma_f32_16x16x32_bf16 v[86:89], v[174:177], v[216:219], v[86:89]
	v_mfma_f32_16x16x32_bf16 v[82:85], v[182:185], v[216:219], v[82:85]
	v_mfma_f32_16x16x32_bf16 v[70:73], v[174:177], v[224:227], v[70:73]
	v_mfma_f32_16x16x32_bf16 v[66:69], v[182:185], v[224:227], v[66:69]
	s_setprio 0
	s_barrier
; #define PG8_STAGE(bufoff, gbase, voff) do { _Pragma("unroll") for (int _i = 0; _i < 2; ++_i) \
;         __builtin_amdgcn_global_load_lds((const unsigned*)((const char*)(gbase) + (voff)[_i]), (PG8_LAS unsigned*)(lds + (bufoff) + ldsw + _i * 8192), 16, 0, 0); } while (0)
; #define PG8_LDA(dst, b, h) do { _Pragma("unroll") for (int m = 0; m < 4; ++m) _Pragma("unroll") for (int k = 0; k < 2; ++k) dst[m][k] = *(const PG8_LAS bf16x8*)(lds + PG8_SA(b, h) + aoff + m * 2048 + k * 1024); } while (0)
; #define PG8_LDB(dst, b, h) do { _Pragma("unroll") for (int n = 0; n < 2; ++n) _Pragma("unroll") for (int k = 0; k < 2; ++k) dst[n][k] = *(const PG8_LAS bf16x8*)(lds + PG8_SB(b, h) + boff + n * 2048 + k * 1024); } while (0)
; #define PG8_BAR __builtin_amdgcn_s_barrier()
; template <class Epi, bool ALIGN_EPI = true>
; __device__ __forceinline__ void gemm_phase(PG8_LAS unsigned char* lds, const Gemm g, const StaticOrder& S, const Epi& E) {
;     ...
;         for (int t = 0; t < nt; t += 2) {
;             const bool last = (t == nt - 2);
;             const char* a1 = cA + (size_t)(t + 1) * kstep;
;             const char* a2 = last ? nA : cA + (size_t)(t + 2) * kstep; const char* b2 = last ? nB : cB + (size_t)(t + 2) * kstep;
;             const char* a3 = a2 + kstep; const char* b3 = b2 + kstep;
;             PG8_LDB(B0, 0, 0); PG8_LDB(B1, 0, 1); PG8_SCHED; PG8_LDA(At, 0, 0); PG8_STAGE(PG8_SA(1, 1), a1 + hstepA, voffA);
;             PG8_WAIT_V(8); PG8_WAIT_L(0); PG8_BAR; PG8_MMA(0, 0, At, B0); PG8_MMA(0, 1, At, B1); PG8_BAR; PG8_SCHED;
;             PG8_LDA(At, 0, 1); PG8_STAGE(PG8_SB(0, 0), b2, voffB); PG8_STAGE(PG8_SB(0, 1), b2 + hstepB, voffB); PG8_STAGE(PG8_SA(0, 0), a2, voffA);
;             PG8_WAIT_V(8); PG8_WAIT_L(0); PG8_BAR; PG8_MMA(1, 0, At, B0); PG8_MMA(1, 1, At, B1); PG8_BAR; PG8_SCHED;
;             PG8_LDB(B0, 1, 0); PG8_LDB(B1, 1, 1); PG8_SCHED; PG8_LDA(At, 1, 0); PG8_STAGE(PG8_SA(0, 1), a2 + hstepA, voffA);
;             PG8_WAIT_V(8); PG8_WAIT_L(0); PG8_BAR; PG8_MMA(0, 0, At, B0); PG8_MMA(0, 1, At, B1); PG8_BAR; PG8_SCHED;
;             PG8_LDA(At, 1, 1); PG8_STAGE(PG8_SB(1, 0), b3, voffB); PG8_STAGE(PG8_SB(1, 1), b3 + hstepB, voffB); PG8_STAGE(PG8_SA(1, 0), a3, voffA);
;             PG8_WAIT_V(8); PG8_WAIT_L(0); PG8_BAR; PG8_MMA(1, 0, At, B0); PG8_MMA(1, 1, At, B1); PG8_BAR; PG8_SCHED;
;         }
;         if constexpr (ALIGN_EPI) { if (wr == 0) PG8_BAR; }
	s_add_i32 s44, s87, s53
	v_lshl_add_u64 v[144:145], v[144:145], 0, s[60:61]
	s_mov_b32 m0, s44
	ds_read_b128 v[186:189], v161 offset:49152
	ds_read_b128 v[190:193], v161 offset:50176
	ds_read_b128 v[194:197], v161 offset:51200
	ds_read_b128 v[198:201], v161 offset:52224
	ds_read_b128 v[208:211], v161 offset:53248
	ds_read_b128 v[216:219], v161 offset:54272
	ds_read_b128 v[220:223], v161 offset:55296
	ds_read_b128 v[224:227], v161 offset:56320
	global_load_lds_dwordx4 v[144:145], off
	s_add_i32 m0, s44, 0x2000
	s_add_u32 s42, s42, 0x40080
	v_lshl_add_u64 v[144:145], v[146:147], 0, s[60:61]
	s_addc_u32 s43, s43, 0
	s_add_i32 s44, s88, s53
	global_load_lds_dwordx4 v[144:145], off
	v_lshl_add_u64 v[144:145], s[42:43], 0, v[32:33]
	s_mov_b32 m0, s44
	s_nop 0
	global_load_lds_dwordx4 v[144:145], off
	v_lshl_add_u64 v[144:145], s[42:43], 0, v[134:135]
	s_add_i32 m0, s44, 0x2000
	s_nop 0
	global_load_lds_dwordx4 v[144:145], off
	v_lshl_add_u64 v[144:145], v[204:205], 0, s[60:61]
	s_mov_b32 m0, s72
	s_nop 0
	global_load_lds_dwordx4 v[144:145], off
	v_lshl_add_u64 v[144:145], v[206:207], 0, s[60:61]
	s_mov_b32 m0, s73
	s_nop 0
	global_load_lds_dwordx4 v[144:145], off
	s_add_i32 s86, s86, 2
	s_add_u32 s40, s40, 0x100
	s_addc_u32 s41, s41, 0
	s_add_u32 s83, s83, 0x100
	s_addc_u32 s85, s85, 0
	s_add_u32 s42, s40, 0xfffc0080
	s_addc_u32 s43, s41, -1
	s_add_i32 s87, 0, 0x10000
	s_cmp_eq_u32 s86, 12
	s_cselect_b32 s45, s29, s43
	s_cselect_b32 s44, s37, s42
	v_add_u32_e32 v144, s87, v159
	s_cselect_b32 s43, s27, s85
	s_cselect_b32 s42, s82, s83
	s_add_i32 s90, 0, 0x14000
	s_cmp_gt_u32 s86, 13
	s_waitcnt vmcnt(8)
	s_waitcnt lgkmcnt(0)
	s_barrier
	s_setprio 1
	s_waitcnt lgkmcnt(0)
	v_mfma_f32_16x16x32_bf16 v[62:65], v[140:143], v[186:189], v[62:65]
	v_mfma_f32_16x16x32_bf16 v[58:61], v[162:165], v[186:189], v[58:61]
	v_mfma_f32_16x16x32_bf16 v[46:49], v[140:143], v[194:197], v[46:49]
	v_mfma_f32_16x16x32_bf16 v[42:45], v[162:165], v[194:197], v[42:45]
	v_mfma_f32_16x16x32_bf16 v[28:31], v[140:143], v[208:211], v[28:31]
	v_mfma_f32_16x16x32_bf16 v[24:27], v[162:165], v[208:211], v[24:27]
	v_mfma_f32_16x16x32_bf16 v[12:15], v[140:143], v[220:223], v[12:15]
	v_mfma_f32_16x16x32_bf16 v[8:11], v[162:165], v[220:223], v[8:11]
	v_mfma_f32_16x16x32_bf16 v[62:65], v[148:151], v[190:193], v[62:65]
	v_mfma_f32_16x16x32_bf16 v[58:61], v[166:169], v[190:193], v[58:61]
	v_mfma_f32_16x16x32_bf16 v[46:49], v[148:151], v[198:201], v[46:49]
	v_mfma_f32_16x16x32_bf16 v[42:45], v[166:169], v[198:201], v[42:45]
	v_mfma_f32_16x16x32_bf16 v[28:31], v[148:151], v[216:219], v[28:31]
	v_mfma_f32_16x16x32_bf16 v[24:27], v[166:169], v[216:219], v[24:27]
	v_mfma_f32_16x16x32_bf16 v[12:15], v[148:151], v[224:227], v[12:15]
	v_mfma_f32_16x16x32_bf16 v[8:11], v[166:169], v[224:227], v[8:11]
	v_mfma_f32_16x16x32_bf16 v[54:57], v[170:173], v[186:189], v[54:57]
	v_mfma_f32_16x16x32_bf16 v[50:53], v[178:181], v[186:189], v[50:53]
	v_mfma_f32_16x16x32_bf16 v[38:41], v[170:173], v[194:197], v[38:41]
	v_mfma_f32_16x16x32_bf16 v[34:37], v[178:181], v[194:197], v[34:37]
	v_mfma_f32_16x16x32_bf16 v[20:23], v[170:173], v[208:211], v[20:23]
	v_mfma_f32_16x16x32_bf16 v[16:19], v[178:181], v[208:211], v[16:19]
	v_mfma_f32_16x16x32_bf16 v[4:7], v[170:173], v[220:223], v[4:7]
	v_mfma_f32_16x16x32_bf16 v[0:3], v[178:181], v[220:223], v[0:3]
	v_mfma_f32_16x16x32_bf16 v[54:57], v[174:177], v[190:193], v[54:57]
	v_mfma_f32_16x16x32_bf16 v[50:53], v[182:185], v[190:193], v[50:53]
	v_mfma_f32_16x16x32_bf16 v[38:41], v[174:177], v[198:201], v[38:41]
	v_mfma_f32_16x16x32_bf16 v[34:37], v[182:185], v[198:201], v[34:37]
	v_mfma_f32_16x16x32_bf16 v[20:23], v[174:177], v[216:219], v[20:23]
	v_mfma_f32_16x16x32_bf16 v[16:19], v[182:185], v[216:219], v[16:19]
	v_mfma_f32_16x16x32_bf16 v[4:7], v[174:177], v[224:227], v[4:7]
	v_mfma_f32_16x16x32_bf16 v[0:3], v[182:185], v[224:227], v[0:3]
	s_setprio 0
	s_barrier
	s_cbranch_scc0 .Lrot_2032
	s_and_b64 vcc, exec, s[14:15]
	s_cbranch_vccz .LBB0_2035
	s_barrier

; #define PG8_STAGE(bufoff, gbase, voff) do { _Pragma("unroll") for (int _i = 0; _i < 2; ++_i) \
;         __builtin_amdgcn_global_load_lds((const unsigned*)((const char*)(gbase) + (voff)[_i]), (PG8_LAS unsigned*)(lds + (bufoff) + ldsw + _i * 8192), 16, 0, 0); } while (0)
; #define PG8_LDA(dst, b, h) do { _Pragma("unroll") for (int m = 0; m < 4; ++m) _Pragma("unroll") for (int k = 0; k < 2; ++k) dst[m][k] = *(const PG8_LAS bf16x8*)(lds + PG8_SA(b, h) + aoff + m * 2048 + k * 1024); } while (0)
; #define PG8_LDB(dst, b, h) do { _Pragma("unroll") for (int n = 0; n < 2; ++n) _Pragma("unroll") for (int k = 0; k < 2; ++k) dst[n][k] = *(const PG8_LAS bf16x8*)(lds + PG8_SB(b, h) + boff + n * 2048 + k * 1024); } while (0)
; #define PG8_WAIT_V(n) asm volatile("s_waitcnt vmcnt(" #n ")" ::: "memory")
; #define PG8_WAIT_L(n) asm volatile("s_waitcnt lgkmcnt(" #n ")" ::: "memory")
; #define PG8_BAR __builtin_amdgcn_s_barrier()
; #define PG8_SCHED __builtin_amdgcn_sched_barrier(0)
; template <class Epi, bool ALIGN_EPI = true>
; __device__ __forceinline__ void gemm_phase(PG8_LAS unsigned char* lds, const Gemm g, const StaticOrder& S, const Epi& E) {
;     ...
;         const bool has_next = S.next(ui + 1, nxt);
;         const char* nA = has_next ? (const char*)g.A + (size_t)nxt.pm * tstepA + (size_t)nxt.ks * ksA : cA; const char* nB = has_next ? (const char*)g.Bt + (size_t)nxt.pn * tstepB + (size_t)nxt.ks * ksA : cB;
;         for (int t = 0; t < nt; t += 2) {
;             const bool last = (t == nt - 2);
;             const char* a1 = cA + (size_t)(t + 1) * kstep;
;             const char* a2 = last ? nA : cA + (size_t)(t + 2) * kstep; const char* b2 = last ? nB : cB + (size_t)(t + 2) * kstep;
;             const char* a3 = a2 + kstep; const char* b3 = b2 + kstep;
;             PG8_LDB(B0, 0, 0); PG8_LDB(B1, 0, 1); PG8_SCHED; PG8_LDA(At, 0, 0); PG8_STAGE(PG8_SA(1, 1), a1 + hstepA, voffA);
;             PG8_WAIT_V(8); PG8_WAIT_L(0); PG8_BAR; PG8_MMA(0, 0, At, B0); PG8_MMA(0, 1, At, B1); PG8_BAR; PG8_SCHED;
;             PG8_LDA(At, 0, 1); PG8_STAGE(PG8_SB(0, 0), b2, voffB); PG8_STAGE(PG8_SB(0, 1), b2 + hstepB, voffB); PG8_STAGE(PG8_SA(0, 0), a2, voffA);
;             PG8_WAIT_V(8); PG8_WAIT_L(0); PG8_BAR; PG8_MMA(1, 0, At, B0); PG8_MMA(1, 1, At, B1); PG8_BAR; PG8_SCHED;
.LBB0_2118:
	s_ashr_i32 s35, s34, 31
	s_lshl_b64 s[38:39], s[34:35], 21
	s_add_u32 s7, s51, s38
	s_addc_u32 s35, s52, s39
	s_ashr_i32 s31, s30, 31
	s_lshl_b64 s[40:41], s[30:31], 9
	s_add_u32 s38, s7, s40
	s_addc_u32 s39, s35, s41
	s_and_b64 s[42:43], s[2:3], exec
	s_cselect_b32 s47, s39, s45
	s_cselect_b32 s46, s38, s44
	s_ashr_i32 s37, s36, 31
	s_lshl_b64 s[42:43], s[36:37], 21
	s_add_u32 s7, s53, s42
	s_addc_u32 s31, s66, s43
	s_add_u32 s40, s7, s40
	s_addc_u32 s41, s31, s41
	s_and_b64 s[42:43], s[2:3], exec
	s_cselect_b32 s43, s41, s49
	s_cselect_b32 s42, s40, s48
	s_add_i32 s77, 0, 0x10000
	s_add_i32 s35, 0, 0x14000
	v_add_u32_e32 v154, s77, v139
	v_add_u32_e32 v155, s35, v139
	ds_read_b128 v[0:3], v154
	ds_read_b128 v[4:7], v154 offset:1024
	ds_read_b128 v[8:11], v154 offset:2048
	ds_read_b128 v[12:15], v154 offset:3072
	ds_read_b128 v[16:19], v155
	ds_read_b128 v[20:23], v155 offset:1024
	ds_read_b128 v[24:27], v155 offset:2048
	ds_read_b128 v[28:31], v155 offset:3072
	s_add_u32 s86, s44, 0x100080
	s_addc_u32 s87, s45, 0
	s_add_i32 s83, s9, 0xc000
	v_lshl_add_u64 v[66:67], s[86:87], 0, v[136:137]
	s_mov_b32 m0, s83
	s_add_i32 s7, s9, 0xe000
	ds_read_b128 v[34:37], v143
	ds_read_b128 v[38:41], v143 offset:1024
	ds_read_b128 v[42:45], v143 offset:2048
	ds_read_b128 v[46:49], v143 offset:3072
	ds_read_b128 v[50:53], v143 offset:4096
	ds_read_b128 v[54:57], v143 offset:5120
	ds_read_b128 v[58:61], v143 offset:6144
	ds_read_b128 v[62:65], v143 offset:7168
	global_load_lds_dwordx4 v[66:67], off
	v_lshl_add_u64 v[66:67], s[86:87], 0, v[132:133]
	s_mov_b32 m0, s7
	s_nop 0
	global_load_lds_dwordx4 v[66:67], off
	s_waitcnt vmcnt(8)
	s_waitcnt lgkmcnt(0)
	s_barrier
	s_setprio 1
	s_waitcnt lgkmcnt(0)
	v_mfma_f32_16x16x32_bf16 v[66:69], v[0:3], v[34:37], 0
	v_mfma_f32_16x16x32_bf16 v[70:73], v[8:11], v[34:37], 0
	v_mfma_f32_16x16x32_bf16 v[74:77], v[0:3], v[42:45], 0
	v_mfma_f32_16x16x32_bf16 v[78:81], v[8:11], v[42:45], 0
	v_mfma_f32_16x16x32_bf16 v[82:85], v[0:3], v[50:53], 0
	v_mfma_f32_16x16x32_bf16 v[86:89], v[8:11], v[50:53], 0
	v_mfma_f32_16x16x32_bf16 v[90:93], v[0:3], v[58:61], 0
	v_mfma_f32_16x16x32_bf16 v[94:97], v[8:11], v[58:61], 0
	v_mfma_f32_16x16x32_bf16 v[66:69], v[4:7], v[38:41], v[66:69]
	v_mfma_f32_16x16x32_bf16 v[70:73], v[12:15], v[38:41], v[70:73]
	v_mfma_f32_16x16x32_bf16 v[74:77], v[4:7], v[46:49], v[74:77]
	v_mfma_f32_16x16x32_bf16 v[78:81], v[12:15], v[46:49], v[78:81]
	v_mfma_f32_16x16x32_bf16 v[82:85], v[4:7], v[54:57], v[82:85]
	v_mfma_f32_16x16x32_bf16 v[86:89], v[12:15], v[54:57], v[86:89]
	v_mfma_f32_16x16x32_bf16 v[90:93], v[4:7], v[62:65], v[90:93]
	v_mfma_f32_16x16x32_bf16 v[94:97], v[12:15], v[62:65], v[94:97]
	v_mfma_f32_16x16x32_bf16 v[98:101], v[16:19], v[34:37], 0
	v_mfma_f32_16x16x32_bf16 v[34:37], v[24:27], v[34:37], 0
	v_mfma_f32_16x16x32_bf16 v[98:101], v[20:23], v[38:41], v[98:101]
	v_mfma_f32_16x16x32_bf16 v[34:37], v[28:31], v[38:41], v[34:37]
	v_mfma_f32_16x16x32_bf16 v[38:41], v[16:19], v[42:45], 0
	v_mfma_f32_16x16x32_bf16 v[42:45], v[24:27], v[42:45], 0
	v_mfma_f32_16x16x32_bf16 v[38:41], v[20:23], v[46:49], v[38:41]
	v_mfma_f32_16x16x32_bf16 v[42:45], v[28:31], v[46:49], v[42:45]
	v_mfma_f32_16x16x32_bf16 v[46:49], v[16:19], v[50:53], 0
	v_mfma_f32_16x16x32_bf16 v[50:53], v[24:27], v[50:53], 0
	v_mfma_f32_16x16x32_bf16 v[46:49], v[20:23], v[54:57], v[46:49]
	v_mfma_f32_16x16x32_bf16 v[50:53], v[28:31], v[54:57], v[50:53]
	v_mfma_f32_16x16x32_bf16 v[54:57], v[16:19], v[58:61], 0
	v_mfma_f32_16x16x32_bf16 v[58:61], v[24:27], v[58:61], 0
	v_mfma_f32_16x16x32_bf16 v[54:57], v[20:23], v[62:65], v[54:57]
	v_mfma_f32_16x16x32_bf16 v[58:61], v[28:31], v[62:65], v[58:61]
	s_setprio 0
	s_barrier
	v_lshl_add_u64 v[144:145], s[48:49], 0, v[134:135]
	s_add_i32 s77, s77, s67
	v_lshl_add_u64 v[146:147], v[144:145], 0, s[64:65]
	s_mov_b32 m0, s77
	s_add_i32 s31, s77, 0x2000
	ds_read_b128 v[62:65], v143 offset:16384
	ds_read_b128 v[102:105], v143 offset:17408
	ds_read_b128 v[106:109], v143 offset:18432
	ds_read_b128 v[110:113], v143 offset:19456
	ds_read_b128 v[114:117], v143 offset:20480
	ds_read_b128 v[118:121], v143 offset:21504
	ds_read_b128 v[122:125], v143 offset:22528
	ds_read_b128 v[126:129], v143 offset:23552
	global_load_lds_dwordx4 v[146:147], off
	v_lshl_add_u64 v[146:147], s[48:49], 0, v[130:131]
	s_add_u32 s86, s48, 0x100100
	v_lshl_add_u64 v[148:149], v[146:147], 0, s[64:65]
	s_mov_b32 m0, s31
	s_addc_u32 s87, s49, 0
	s_add_i32 s35, s35, s67
	global_load_lds_dwordx4 v[148:149], off
	v_lshl_add_u64 v[148:149], s[86:87], 0, v[134:135]
	s_mov_b32 m0, s35
	s_add_i32 s37, s35, 0x2000
	global_load_lds_dwordx4 v[148:149], off
	v_lshl_add_u64 v[148:149], s[86:87], 0, v[130:131]
	s_mov_b32 m0, s37
	v_lshl_add_u64 v[204:205], s[44:45], 0, v[136:137]
	global_load_lds_dwordx4 v[148:149], off
	v_lshl_add_u64 v[148:149], v[204:205], 0, s[64:65]
	s_mov_b32 m0, s9
	v_lshl_add_u64 v[206:207], s[44:45], 0, v[132:133]
	global_load_lds_dwordx4 v[148:149], off
	v_lshl_add_u64 v[148:149], v[206:207], 0, s[64:65]
	s_mov_b32 m0, s29
	s_nop 0
	global_load_lds_dwordx4 v[148:149], off
	s_waitcnt vmcnt(8)
	s_waitcnt lgkmcnt(0)
	s_barrier
; #define PG8_STAGE(bufoff, gbase, voff) do { _Pragma("unroll") for (int _i = 0; _i < 2; ++_i) \
;         __builtin_amdgcn_global_load_lds((const unsigned*)((const char*)(gbase) + (voff)[_i]), (PG8_LAS unsigned*)(lds + (bufoff) + ldsw + _i * 8192), 16, 0, 0); } while (0)
; #define PG8_LDA(dst, b, h) do { _Pragma("unroll") for (int m = 0; m < 4; ++m) _Pragma("unroll") for (int k = 0; k < 2; ++k) dst[m][k] = *(const PG8_LAS bf16x8*)(lds + PG8_SA(b, h) + aoff + m * 2048 + k * 1024); } while (0)
; #define PG8_LDB(dst, b, h) do { _Pragma("unroll") for (int n = 0; n < 2; ++n) _Pragma("unroll") for (int k = 0; k < 2; ++k) dst[n][k] = *(const PG8_LAS bf16x8*)(lds + PG8_SB(b, h) + boff + n * 2048 + k * 1024); } while (0)
; #define PG8_WAIT_V(n) asm volatile("s_waitcnt vmcnt(" #n ")" ::: "memory")
; #define PG8_WAIT_L(n) asm volatile("s_waitcnt lgkmcnt(" #n ")" ::: "memory")
; #define PG8_BAR __builtin_amdgcn_s_barrier()
; #define PG8_SCHED __builtin_amdgcn_sched_barrier(0)
; template <class Epi, bool ALIGN_EPI = true>
; __device__ __forceinline__ void gemm_phase(PG8_LAS unsigned char* lds, const Gemm g, const StaticOrder& S, const Epi& E) {
;     ...
;             PG8_WAIT_V(8); PG8_WAIT_L(0); PG8_BAR; PG8_MMA(1, 0, At, B0); PG8_MMA(1, 1, At, B1); PG8_BAR; PG8_SCHED;
;             PG8_LDB(B0, 1, 0); PG8_LDB(B1, 1, 1); PG8_SCHED; PG8_LDA(At, 1, 0); PG8_STAGE(PG8_SA(0, 1), a2 + hstepA, voffA);
;             PG8_WAIT_V(8); PG8_WAIT_L(0); PG8_BAR; PG8_MMA(0, 0, At, B0); PG8_MMA(0, 1, At, B1); PG8_BAR; PG8_SCHED;
	s_setprio 1
	s_waitcnt lgkmcnt(0)
	v_mfma_f32_16x16x32_bf16 v[148:151], v[0:3], v[62:65], 0
	v_mfma_f32_16x16x32_bf16 v[162:165], v[0:3], v[106:109], 0
	v_mfma_f32_16x16x32_bf16 v[170:173], v[0:3], v[114:117], 0
	v_mfma_f32_16x16x32_bf16 v[0:3], v[0:3], v[122:125], 0
	v_mfma_f32_16x16x32_bf16 v[148:151], v[4:7], v[102:105], v[148:151]
	v_mfma_f32_16x16x32_bf16 v[162:165], v[4:7], v[110:113], v[162:165]
	v_mfma_f32_16x16x32_bf16 v[170:173], v[4:7], v[118:121], v[170:173]
	v_mfma_f32_16x16x32_bf16 v[0:3], v[4:7], v[126:129], v[0:3]
	v_mfma_f32_16x16x32_bf16 v[4:7], v[8:11], v[122:125], 0
	v_mfma_f32_16x16x32_bf16 v[158:161], v[8:11], v[62:65], 0
	v_mfma_f32_16x16x32_bf16 v[166:169], v[8:11], v[106:109], 0
	v_mfma_f32_16x16x32_bf16 v[174:177], v[8:11], v[114:117], 0
	v_mfma_f32_16x16x32_bf16 v[4:7], v[12:15], v[126:129], v[4:7]
	v_mfma_f32_16x16x32_bf16 v[158:161], v[12:15], v[102:105], v[158:161]
	v_mfma_f32_16x16x32_bf16 v[166:169], v[12:15], v[110:113], v[166:169]
	v_mfma_f32_16x16x32_bf16 v[174:177], v[12:15], v[118:121], v[174:177]
	v_mfma_f32_16x16x32_bf16 v[8:11], v[16:19], v[62:65], 0
	v_mfma_f32_16x16x32_bf16 v[12:15], v[24:27], v[62:65], 0
	v_mfma_f32_16x16x32_bf16 v[8:11], v[20:23], v[102:105], v[8:11]
	v_mfma_f32_16x16x32_bf16 v[12:15], v[28:31], v[102:105], v[12:15]
	v_mfma_f32_16x16x32_bf16 v[62:65], v[16:19], v[106:109], 0
	v_mfma_f32_16x16x32_bf16 v[102:105], v[24:27], v[106:109], 0
	v_mfma_f32_16x16x32_bf16 v[106:109], v[16:19], v[114:117], 0
	v_mfma_f32_16x16x32_bf16 v[16:19], v[16:19], v[122:125], 0
	v_mfma_f32_16x16x32_bf16 v[62:65], v[20:23], v[110:113], v[62:65]
	v_mfma_f32_16x16x32_bf16 v[102:105], v[28:31], v[110:113], v[102:105]
	v_mfma_f32_16x16x32_bf16 v[106:109], v[20:23], v[118:121], v[106:109]
	v_mfma_f32_16x16x32_bf16 v[110:113], v[24:27], v[114:117], 0
	v_mfma_f32_16x16x32_bf16 v[16:19], v[20:23], v[126:129], v[16:19]
	v_mfma_f32_16x16x32_bf16 v[20:23], v[24:27], v[122:125], 0
	v_mfma_f32_16x16x32_bf16 v[110:113], v[28:31], v[118:121], v[110:113]
	v_mfma_f32_16x16x32_bf16 v[20:23], v[28:31], v[126:129], v[20:23]
	s_setprio 0
	s_barrier
	s_add_i32 s85, 0, 0x18000
	s_add_i32 s88, 0, 0x1c000
	v_add_u32_e32 v240, s85, v139
	v_add_u32_e32 v244, s88, v139
	ds_read_b128 v[24:27], v240
	ds_read_b128 v[28:31], v240 offset:1024
	ds_read_b128 v[114:117], v240 offset:2048
	ds_read_b128 v[118:121], v240 offset:3072
	ds_read_b128 v[122:125], v244
	ds_read_b128 v[126:129], v244 offset:1024
	ds_read_b128 v[178:181], v244 offset:2048
	ds_read_b128 v[182:185], v244 offset:3072
	s_add_u32 s86, s44, 0x100100
	s_addc_u32 s87, s45, 0
	s_mov_b32 m0, s70
	v_lshl_add_u64 v[228:229], s[86:87], 0, v[136:137]
	ds_read_b128 v[186:189], v143 offset:32768
	ds_read_b128 v[190:193], v143 offset:33792
	ds_read_b128 v[194:197], v143 offset:34816
	ds_read_b128 v[198:201], v143 offset:35840
	ds_read_b128 v[208:211], v143 offset:36864
	ds_read_b128 v[216:219], v143 offset:37888
	ds_read_b128 v[220:223], v143 offset:38912
	ds_read_b128 v[224:227], v143 offset:39936
	global_load_lds_dwordx4 v[228:229], off
	v_lshl_add_u64 v[228:229], s[86:87], 0, v[132:133]
	s_mov_b32 m0, s71
	s_nop 0
	global_load_lds_dwordx4 v[228:229], off
	s_waitcnt vmcnt(8)
	s_waitcnt lgkmcnt(0)
	s_barrier
	s_setprio 1
	s_waitcnt lgkmcnt(0)
	v_mfma_f32_16x16x32_bf16 v[66:69], v[24:27], v[186:189], v[66:69]
	v_mfma_f32_16x16x32_bf16 v[70:73], v[114:117], v[186:189], v[70:73]
	v_mfma_f32_16x16x32_bf16 v[74:77], v[24:27], v[194:197], v[74:77]
	v_mfma_f32_16x16x32_bf16 v[78:81], v[114:117], v[194:197], v[78:81]
	v_mfma_f32_16x16x32_bf16 v[82:85], v[24:27], v[208:211], v[82:85]
	v_mfma_f32_16x16x32_bf16 v[86:89], v[114:117], v[208:211], v[86:89]
	v_mfma_f32_16x16x32_bf16 v[90:93], v[24:27], v[220:223], v[90:93]
	v_mfma_f32_16x16x32_bf16 v[94:97], v[114:117], v[220:223], v[94:97]
	v_mfma_f32_16x16x32_bf16 v[66:69], v[28:31], v[190:193], v[66:69]
	v_mfma_f32_16x16x32_bf16 v[70:73], v[118:121], v[190:193], v[70:73]
	v_mfma_f32_16x16x32_bf16 v[74:77], v[28:31], v[198:201], v[74:77]
	v_mfma_f32_16x16x32_bf16 v[78:81], v[118:121], v[198:201], v[78:81]
	v_mfma_f32_16x16x32_bf16 v[82:85], v[28:31], v[216:219], v[82:85]
	v_mfma_f32_16x16x32_bf16 v[86:89], v[118:121], v[216:219], v[86:89]
	v_mfma_f32_16x16x32_bf16 v[90:93], v[28:31], v[224:227], v[90:93]
	v_mfma_f32_16x16x32_bf16 v[94:97], v[118:121], v[224:227], v[94:97]
	v_mfma_f32_16x16x32_bf16 v[98:101], v[122:125], v[186:189], v[98:101]
	v_mfma_f32_16x16x32_bf16 v[34:37], v[178:181], v[186:189], v[34:37]
	v_mfma_f32_16x16x32_bf16 v[38:41], v[122:125], v[194:197], v[38:41]
	v_mfma_f32_16x16x32_bf16 v[42:45], v[178:181], v[194:197], v[42:45]
	v_mfma_f32_16x16x32_bf16 v[46:49], v[122:125], v[208:211], v[46:49]
	v_mfma_f32_16x16x32_bf16 v[50:53], v[178:181], v[208:211], v[50:53]
	v_mfma_f32_16x16x32_bf16 v[54:57], v[122:125], v[220:223], v[54:57]
	v_mfma_f32_16x16x32_bf16 v[58:61], v[178:181], v[220:223], v[58:61]
	v_mfma_f32_16x16x32_bf16 v[98:101], v[126:129], v[190:193], v[98:101]
	v_mfma_f32_16x16x32_bf16 v[34:37], v[182:185], v[190:193], v[34:37]
	v_mfma_f32_16x16x32_bf16 v[38:41], v[126:129], v[198:201], v[38:41]
	v_mfma_f32_16x16x32_bf16 v[42:45], v[182:185], v[198:201], v[42:45]
	v_mfma_f32_16x16x32_bf16 v[46:49], v[126:129], v[216:219], v[46:49]
	v_mfma_f32_16x16x32_bf16 v[50:53], v[182:185], v[216:219], v[50:53]
	v_mfma_f32_16x16x32_bf16 v[54:57], v[126:129], v[224:227], v[54:57]
	v_mfma_f32_16x16x32_bf16 v[58:61], v[182:185], v[224:227], v[58:61]
	s_setprio 0
	s_barrier
; #define PG8_STAGE(bufoff, gbase, voff) do { _Pragma("unroll") for (int _i = 0; _i < 2; ++_i) \
;         __builtin_amdgcn_global_load_lds((const unsigned*)((const char*)(gbase) + (voff)[_i]), (PG8_LAS unsigned*)(lds + (bufoff) + ldsw + _i * 8192), 16, 0, 0); } while (0)
; #define PG8_LDA(dst, b, h) do { _Pragma("unroll") for (int m = 0; m < 4; ++m) _Pragma("unroll") for (int k = 0; k < 2; ++k) dst[m][k] = *(const PG8_LAS bf16x8*)(lds + PG8_SA(b, h) + aoff + m * 2048 + k * 1024); } while (0)
; #define PG8_LDB(dst, b, h) do { _Pragma("unroll") for (int n = 0; n < 2; ++n) _Pragma("unroll") for (int k = 0; k < 2; ++k) dst[n][k] = *(const PG8_LAS bf16x8*)(lds + PG8_SB(b, h) + boff + n * 2048 + k * 1024); } while (0)
; #define PG8_WAIT_V(n) asm volatile("s_waitcnt vmcnt(" #n ")" ::: "memory")
; #define PG8_WAIT_L(n) asm volatile("s_waitcnt lgkmcnt(" #n ")" ::: "memory")
; #define PG8_BAR __builtin_amdgcn_s_barrier()
; #define PG8_SCHED __builtin_amdgcn_sched_barrier(0)
; template <class Epi, bool ALIGN_EPI = true>
; __device__ __forceinline__ void gemm_phase(PG8_LAS unsigned char* lds, const Gemm g, const StaticOrder& S, const Epi& E) {
;     ...
;             PG8_LDB(B0, 0, 0); PG8_LDB(B1, 0, 1); PG8_SCHED; PG8_LDA(At, 0, 0); PG8_STAGE(PG8_SA(1, 1), a1 + hstepA, voffA);
;             PG8_WAIT_V(8); PG8_WAIT_L(0); PG8_BAR; PG8_MMA(0, 0, At, B0); PG8_MMA(0, 1, At, B1); PG8_BAR; PG8_SCHED;
;             PG8_LDA(At, 0, 1); PG8_STAGE(PG8_SB(0, 0), b2, voffB); PG8_STAGE(PG8_SB(0, 1), b2 + hstepB, voffB); PG8_STAGE(PG8_SA(0, 0), a2, voffA);
;             PG8_WAIT_V(8); PG8_WAIT_L(0); PG8_BAR; PG8_MMA(1, 0, At, B0); PG8_MMA(1, 1, At, B1); PG8_BAR; PG8_SCHED;
;             PG8_LDB(B0, 1, 0); PG8_LDB(B1, 1, 1); PG8_SCHED; PG8_LDA(At, 1, 0); PG8_STAGE(PG8_SA(0, 1), a2 + hstepA, voffA);
;             PG8_WAIT_V(8); PG8_WAIT_L(0); PG8_BAR; PG8_MMA(0, 0, At, B0); PG8_MMA(0, 1, At, B1); PG8_BAR; PG8_SCHED;
;             PG8_LDA(At, 1, 1); PG8_STAGE(PG8_SB(1, 0), b3, voffB); PG8_STAGE(PG8_SB(1, 1), b3 + hstepB, voffB); PG8_STAGE(PG8_SA(1, 0), a3, voffA);
;             PG8_WAIT_V(8); PG8_WAIT_L(0); PG8_BAR; PG8_MMA(1, 0, At, B0); PG8_MMA(1, 1, At, B1); PG8_BAR; PG8_SCHED;
	s_add_i32 s85, s85, s67
	s_add_i32 s82, s85, 0x2000
	v_lshl_add_u64 v[144:145], v[144:145], 0, s[68:69]
	s_mov_b32 m0, s85
	s_add_u32 s86, s48, 0x100180
	ds_read_b128 v[186:189], v143 offset:49152
	ds_read_b128 v[190:193], v143 offset:50176
	ds_read_b128 v[194:197], v143 offset:51200
	ds_read_b128 v[198:201], v143 offset:52224
	ds_read_b128 v[208:211], v143 offset:53248
	ds_read_b128 v[216:219], v143 offset:54272
	ds_read_b128 v[220:223], v143 offset:55296
	ds_read_b128 v[224:227], v143 offset:56320
	global_load_lds_dwordx4 v[144:145], off
	v_lshl_add_u64 v[144:145], v[146:147], 0, s[68:69]
	s_mov_b32 m0, s82
	s_addc_u32 s87, s49, 0
	s_add_i32 s48, s88, s67
	global_load_lds_dwordx4 v[144:145], off
	v_lshl_add_u64 v[144:145], s[86:87], 0, v[134:135]
	s_mov_b32 m0, s48
	s_add_i32 s49, s48, 0x2000
	global_load_lds_dwordx4 v[144:145], off
	v_lshl_add_u64 v[144:145], s[86:87], 0, v[130:131]
	s_mov_b32 m0, s49
	s_nop 0
	global_load_lds_dwordx4 v[144:145], off
	v_lshl_add_u64 v[144:145], v[204:205], 0, s[68:69]
	s_mov_b32 m0, s74
	s_nop 0
	global_load_lds_dwordx4 v[144:145], off
	v_lshl_add_u64 v[144:145], v[206:207], 0, s[68:69]
	s_mov_b32 m0, s75
	s_nop 0
	global_load_lds_dwordx4 v[144:145], off
	s_waitcnt vmcnt(8)
	s_waitcnt lgkmcnt(0)
	s_barrier
	s_setprio 1
	s_waitcnt lgkmcnt(0)
	v_mfma_f32_16x16x32_bf16 v[0:3], v[24:27], v[220:223], v[0:3]
	v_mfma_f32_16x16x32_bf16 v[4:7], v[114:117], v[220:223], v[4:7]
	v_mfma_f32_16x16x32_bf16 v[148:151], v[24:27], v[186:189], v[148:151]
	v_mfma_f32_16x16x32_bf16 v[158:161], v[114:117], v[186:189], v[158:161]
	v_mfma_f32_16x16x32_bf16 v[162:165], v[24:27], v[194:197], v[162:165]
	v_mfma_f32_16x16x32_bf16 v[166:169], v[114:117], v[194:197], v[166:169]
	v_mfma_f32_16x16x32_bf16 v[170:173], v[24:27], v[208:211], v[170:173]
	v_mfma_f32_16x16x32_bf16 v[174:177], v[114:117], v[208:211], v[174:177]
	v_mfma_f32_16x16x32_bf16 v[0:3], v[28:31], v[224:227], v[0:3]
	v_mfma_f32_16x16x32_bf16 v[4:7], v[118:121], v[224:227], v[4:7]
	v_mfma_f32_16x16x32_bf16 v[148:151], v[28:31], v[190:193], v[148:151]
	v_mfma_f32_16x16x32_bf16 v[158:161], v[118:121], v[190:193], v[158:161]
	v_mfma_f32_16x16x32_bf16 v[162:165], v[28:31], v[198:201], v[162:165]
	v_mfma_f32_16x16x32_bf16 v[166:169], v[118:121], v[198:201], v[166:169]
	v_mfma_f32_16x16x32_bf16 v[170:173], v[28:31], v[216:219], v[170:173]
	v_mfma_f32_16x16x32_bf16 v[174:177], v[118:121], v[216:219], v[174:177]
	v_mfma_f32_16x16x32_bf16 v[8:11], v[122:125], v[186:189], v[8:11]
	v_mfma_f32_16x16x32_bf16 v[12:15], v[178:181], v[186:189], v[12:15]
	v_mfma_f32_16x16x32_bf16 v[24:27], v[122:125], v[194:197], v[62:65]
	v_mfma_f32_16x16x32_bf16 v[28:31], v[178:181], v[194:197], v[102:105]
	v_mfma_f32_16x16x32_bf16 v[62:65], v[122:125], v[208:211], v[106:109]
	v_mfma_f32_16x16x32_bf16 v[102:105], v[178:181], v[208:211], v[110:113]
	v_mfma_f32_16x16x32_bf16 v[16:19], v[122:125], v[220:223], v[16:19]
	v_mfma_f32_16x16x32_bf16 v[20:23], v[178:181], v[220:223], v[20:23]
	v_mfma_f32_16x16x32_bf16 v[8:11], v[126:129], v[190:193], v[8:11]
	v_mfma_f32_16x16x32_bf16 v[12:15], v[182:185], v[190:193], v[12:15]
	v_mfma_f32_16x16x32_bf16 v[24:27], v[126:129], v[198:201], v[24:27]
	v_mfma_f32_16x16x32_bf16 v[28:31], v[182:185], v[198:201], v[28:31]
	v_mfma_f32_16x16x32_bf16 v[62:65], v[126:129], v[216:219], v[62:65]
	v_mfma_f32_16x16x32_bf16 v[102:105], v[182:185], v[216:219], v[102:105]
	v_mfma_f32_16x16x32_bf16 v[16:19], v[126:129], v[224:227], v[16:19]
	v_mfma_f32_16x16x32_bf16 v[20:23], v[182:185], v[224:227], v[20:23]
	s_setprio 0
	s_barrier
	ds_read_b128 v[106:109], v154
	ds_read_b128 v[110:113], v154 offset:1024
	ds_read_b128 v[114:117], v154 offset:2048
	ds_read_b128 v[118:121], v154 offset:3072
	ds_read_b128 v[122:125], v155
	ds_read_b128 v[126:129], v155 offset:1024
	ds_read_b128 v[178:181], v155 offset:2048
	ds_read_b128 v[182:185], v155 offset:3072
	s_add_u32 s44, s44, 0x100180
	s_addc_u32 s45, s45, 0
	s_mov_b32 m0, s83
	v_lshl_add_u64 v[144:145], s[44:45], 0, v[136:137]
	ds_read_b128 v[186:189], v143
	ds_read_b128 v[190:193], v143 offset:1024
	ds_read_b128 v[194:197], v143 offset:2048
	ds_read_b128 v[198:201], v143 offset:3072
	ds_read_b128 v[208:211], v143 offset:4096
	ds_read_b128 v[216:219], v143 offset:5120
	ds_read_b128 v[220:223], v143 offset:6144
	ds_read_b128 v[224:227], v143 offset:7168
	global_load_lds_dwordx4 v[144:145], off
	v_lshl_add_u64 v[144:145], s[44:45], 0, v[132:133]
	s_mov_b32 m0, s7
	s_nop 0
	global_load_lds_dwordx4 v[144:145], off
	s_waitcnt vmcnt(8)
	s_waitcnt lgkmcnt(0)
	s_barrier
; #define PG8_STAGE(bufoff, gbase, voff) do { _Pragma("unroll") for (int _i = 0; _i < 2; ++_i) \
;         __builtin_amdgcn_global_load_lds((const unsigned*)((const char*)(gbase) + (voff)[_i]), (PG8_LAS unsigned*)(lds + (bufoff) + ldsw + _i * 8192), 16, 0, 0); } while (0)
; #define PG8_LDA(dst, b, h) do { _Pragma("unroll") for (int m = 0; m < 4; ++m) _Pragma("unroll") for (int k = 0; k < 2; ++k) dst[m][k] = *(const PG8_LAS bf16x8*)(lds + PG8_SA(b, h) + aoff + m * 2048 + k * 1024); } while (0)
; #define PG8_LDB(dst, b, h) do { _Pragma("unroll") for (int n = 0; n < 2; ++n) _Pragma("unroll") for (int k = 0; k < 2; ++k) dst[n][k] = *(const PG8_LAS bf16x8*)(lds + PG8_SB(b, h) + boff + n * 2048 + k * 1024); } while (0)
; #define PG8_WAIT_V(n) asm volatile("s_waitcnt vmcnt(" #n ")" ::: "memory")
; #define PG8_WAIT_L(n) asm volatile("s_waitcnt lgkmcnt(" #n ")" ::: "memory")
; #define PG8_BAR __builtin_amdgcn_s_barrier()
; #define PG8_SCHED __builtin_amdgcn_sched_barrier(0)
; template <class Epi, bool ALIGN_EPI = true>
; __device__ __forceinline__ void gemm_phase(PG8_LAS unsigned char* lds, const Gemm g, const StaticOrder& S, const Epi& E) {
;     ...
;             PG8_LDB(B0, 0, 0); PG8_LDB(B1, 0, 1); PG8_SCHED; PG8_LDA(At, 0, 0); PG8_STAGE(PG8_SA(1, 1), a1 + hstepA, voffA);
;             PG8_WAIT_V(8); PG8_WAIT_L(0); PG8_BAR; PG8_MMA(0, 0, At, B0); PG8_MMA(0, 1, At, B1); PG8_BAR; PG8_SCHED;
;             PG8_LDA(At, 0, 1); PG8_STAGE(PG8_SB(0, 0), b2, voffB); PG8_STAGE(PG8_SB(0, 1), b2 + hstepB, voffB); PG8_STAGE(PG8_SA(0, 0), a2, voffA);
;             PG8_WAIT_V(8); PG8_WAIT_L(0); PG8_BAR; PG8_MMA(1, 0, At, B0); PG8_MMA(1, 1, At, B1); PG8_BAR; PG8_SCHED;
	s_setprio 1
	s_waitcnt lgkmcnt(0)
	v_mfma_f32_16x16x32_bf16 v[66:69], v[106:109], v[186:189], v[66:69]
	v_mfma_f32_16x16x32_bf16 v[70:73], v[114:117], v[186:189], v[70:73]
	v_mfma_f32_16x16x32_bf16 v[74:77], v[106:109], v[194:197], v[74:77]
	v_mfma_f32_16x16x32_bf16 v[78:81], v[114:117], v[194:197], v[78:81]
	v_mfma_f32_16x16x32_bf16 v[82:85], v[106:109], v[208:211], v[82:85]
	v_mfma_f32_16x16x32_bf16 v[86:89], v[114:117], v[208:211], v[86:89]
	v_mfma_f32_16x16x32_bf16 v[90:93], v[106:109], v[220:223], v[90:93]
	v_mfma_f32_16x16x32_bf16 v[94:97], v[114:117], v[220:223], v[94:97]
	v_mfma_f32_16x16x32_bf16 v[66:69], v[110:113], v[190:193], v[66:69]
	v_mfma_f32_16x16x32_bf16 v[70:73], v[118:121], v[190:193], v[70:73]
	v_mfma_f32_16x16x32_bf16 v[74:77], v[110:113], v[198:201], v[74:77]
	v_mfma_f32_16x16x32_bf16 v[78:81], v[118:121], v[198:201], v[78:81]
	v_mfma_f32_16x16x32_bf16 v[82:85], v[110:113], v[216:219], v[82:85]
	v_mfma_f32_16x16x32_bf16 v[86:89], v[118:121], v[216:219], v[86:89]
	v_mfma_f32_16x16x32_bf16 v[90:93], v[110:113], v[224:227], v[90:93]
	v_mfma_f32_16x16x32_bf16 v[94:97], v[118:121], v[224:227], v[94:97]
	v_mfma_f32_16x16x32_bf16 v[50:53], v[178:181], v[208:211], v[50:53]
	v_mfma_f32_16x16x32_bf16 v[98:101], v[122:125], v[186:189], v[98:101]
	v_mfma_f32_16x16x32_bf16 v[34:37], v[178:181], v[186:189], v[34:37]
	v_mfma_f32_16x16x32_bf16 v[186:189], v[182:185], v[216:219], v[50:53]
	v_mfma_f32_16x16x32_bf16 v[50:53], v[122:125], v[220:223], v[54:57]
	v_mfma_f32_16x16x32_bf16 v[98:101], v[126:129], v[190:193], v[98:101]
	v_mfma_f32_16x16x32_bf16 v[34:37], v[182:185], v[190:193], v[34:37]
	v_mfma_f32_16x16x32_bf16 v[38:41], v[122:125], v[194:197], v[38:41]
	v_mfma_f32_16x16x32_bf16 v[42:45], v[178:181], v[194:197], v[42:45]
	v_mfma_f32_16x16x32_bf16 v[46:49], v[122:125], v[208:211], v[46:49]
	v_mfma_f32_16x16x32_bf16 v[190:193], v[126:129], v[224:227], v[50:53]
	v_mfma_f32_16x16x32_bf16 v[50:53], v[178:181], v[220:223], v[58:61]
	v_mfma_f32_16x16x32_bf16 v[38:41], v[126:129], v[198:201], v[38:41]
	v_mfma_f32_16x16x32_bf16 v[42:45], v[182:185], v[198:201], v[42:45]
	v_mfma_f32_16x16x32_bf16 v[46:49], v[126:129], v[216:219], v[46:49]
	v_mfma_f32_16x16x32_bf16 v[58:61], v[182:185], v[224:227], v[50:53]
	s_setprio 0
	s_barrier
	s_mov_b32 m0, s77
	v_lshl_add_u64 v[214:215], s[42:43], 0, v[134:135]
	s_add_u32 s44, s42, 0x100000
	ds_read_b128 v[50:53], v143 offset:16384
	ds_read_b128 v[54:57], v143 offset:17408
	ds_read_b128 v[194:197], v143 offset:18432
	ds_read_b128 v[198:201], v143 offset:19456
	ds_read_b128 v[208:211], v143 offset:20480
	ds_read_b128 v[216:219], v143 offset:21504
	ds_read_b128 v[220:223], v143 offset:22528
	ds_read_b128 v[224:227], v143 offset:23552
	global_load_lds_dwordx4 v[214:215], off
	v_lshl_add_u64 v[252:253], s[42:43], 0, v[130:131]
	s_mov_b32 m0, s31
	s_addc_u32 s45, s43, 0
	global_load_lds_dwordx4 v[252:253], off
	v_lshl_add_u64 v[144:145], s[44:45], 0, v[134:135]
	s_mov_b32 m0, s35
	v_lshl_add_u64 v[154:155], s[46:47], 0, v[136:137]
	global_load_lds_dwordx4 v[144:145], off
	v_lshl_add_u64 v[144:145], s[44:45], 0, v[130:131]
	s_mov_b32 m0, s37
	v_lshl_add_u64 v[156:157], s[46:47], 0, v[132:133]
	global_load_lds_dwordx4 v[144:145], off
	s_mov_b32 m0, s9
	s_nop 0
	global_load_lds_dwordx4 v[154:155], off
	s_mov_b32 m0, s29
	s_nop 0
	global_load_lds_dwordx4 v[156:157], off
	s_waitcnt vmcnt(8)
	s_waitcnt lgkmcnt(0)
	s_barrier
	s_setprio 1
	s_waitcnt lgkmcnt(0)
	v_mfma_f32_16x16x32_bf16 v[0:3], v[106:109], v[220:223], v[0:3]
	v_mfma_f32_16x16x32_bf16 v[228:231], v[110:113], v[224:227], v[0:3]
	v_mfma_f32_16x16x32_bf16 v[0:3], v[114:117], v[220:223], v[4:7]
	v_mfma_f32_16x16x32_bf16 v[148:151], v[106:109], v[50:53], v[148:151]
	v_mfma_f32_16x16x32_bf16 v[158:161], v[114:117], v[50:53], v[158:161]
	v_mfma_f32_16x16x32_bf16 v[162:165], v[106:109], v[194:197], v[162:165]
	v_mfma_f32_16x16x32_bf16 v[166:169], v[114:117], v[194:197], v[166:169]
	v_mfma_f32_16x16x32_bf16 v[170:173], v[106:109], v[208:211], v[170:173]
	v_mfma_f32_16x16x32_bf16 v[174:177], v[114:117], v[208:211], v[174:177]
	v_mfma_f32_16x16x32_bf16 v[114:117], v[118:121], v[224:227], v[0:3]
	v_mfma_f32_16x16x32_bf16 v[148:151], v[110:113], v[54:57], v[148:151]
	v_mfma_f32_16x16x32_bf16 v[158:161], v[118:121], v[54:57], v[158:161]
	v_mfma_f32_16x16x32_bf16 v[162:165], v[110:113], v[198:201], v[162:165]
	v_mfma_f32_16x16x32_bf16 v[166:169], v[118:121], v[198:201], v[166:169]
	v_mfma_f32_16x16x32_bf16 v[170:173], v[110:113], v[216:219], v[170:173]
	v_mfma_f32_16x16x32_bf16 v[174:177], v[118:121], v[216:219], v[174:177]
	v_mfma_f32_16x16x32_bf16 v[0:3], v[122:125], v[50:53], v[8:11]
	v_mfma_f32_16x16x32_bf16 v[118:121], v[126:129], v[54:57], v[0:3]
	v_mfma_f32_16x16x32_bf16 v[0:3], v[178:181], v[50:53], v[12:15]
	v_mfma_f32_16x16x32_bf16 v[232:235], v[182:185], v[54:57], v[0:3]
	v_mfma_f32_16x16x32_bf16 v[0:3], v[122:125], v[194:197], v[24:27]
	v_mfma_f32_16x16x32_bf16 v[236:239], v[126:129], v[198:201], v[0:3]
	v_mfma_f32_16x16x32_bf16 v[0:3], v[178:181], v[194:197], v[28:31]
	v_mfma_f32_16x16x32_bf16 v[194:197], v[182:185], v[198:201], v[0:3]
	v_mfma_f32_16x16x32_bf16 v[0:3], v[122:125], v[208:211], v[62:65]
	v_mfma_f32_16x16x32_bf16 v[198:201], v[126:129], v[216:219], v[0:3]
	v_mfma_f32_16x16x32_bf16 v[0:3], v[178:181], v[208:211], v[102:105]
	v_mfma_f32_16x16x32_bf16 v[102:105], v[182:185], v[216:219], v[0:3]
	v_mfma_f32_16x16x32_bf16 v[0:3], v[122:125], v[220:223], v[16:19]
	v_mfma_f32_16x16x32_bf16 v[208:211], v[126:129], v[224:227], v[0:3]
	v_mfma_f32_16x16x32_bf16 v[0:3], v[178:181], v[220:223], v[20:23]
	v_mfma_f32_16x16x32_bf16 v[178:181], v[182:185], v[224:227], v[0:3]
	s_setprio 0
	s_barrier
; #define PG8_STAGE(bufoff, gbase, voff) do { _Pragma("unroll") for (int _i = 0; _i < 2; ++_i) \
;         __builtin_amdgcn_global_load_lds((const unsigned*)((const char*)(gbase) + (voff)[_i]), (PG8_LAS unsigned*)(lds + (bufoff) + ldsw + _i * 8192), 16, 0, 0); } while (0)
; #define PG8_LDA(dst, b, h) do { _Pragma("unroll") for (int m = 0; m < 4; ++m) _Pragma("unroll") for (int k = 0; k < 2; ++k) dst[m][k] = *(const PG8_LAS bf16x8*)(lds + PG8_SA(b, h) + aoff + m * 2048 + k * 1024); } while (0)
; #define PG8_LDB(dst, b, h) do { _Pragma("unroll") for (int n = 0; n < 2; ++n) _Pragma("unroll") for (int k = 0; k < 2; ++k) dst[n][k] = *(const PG8_LAS bf16x8*)(lds + PG8_SB(b, h) + boff + n * 2048 + k * 1024); } while (0)
; #define PG8_WAIT_V(n) asm volatile("s_waitcnt vmcnt(" #n ")" ::: "memory")
; #define PG8_WAIT_L(n) asm volatile("s_waitcnt lgkmcnt(" #n ")" ::: "memory")
; #define PG8_BAR __builtin_amdgcn_s_barrier()
; #define PG8_SCHED __builtin_amdgcn_sched_barrier(0)
; template <class Epi, bool ALIGN_EPI = true>
; __device__ __forceinline__ void gemm_phase(PG8_LAS unsigned char* lds, const Gemm g, const StaticOrder& S, const Epi& E) {
;     ...
;             PG8_LDB(B0, 1, 0); PG8_LDB(B1, 1, 1); PG8_SCHED; PG8_LDA(At, 1, 0); PG8_STAGE(PG8_SA(0, 1), a2 + hstepA, voffA);
;             PG8_WAIT_V(8); PG8_WAIT_L(0); PG8_BAR; PG8_MMA(0, 0, At, B0); PG8_MMA(0, 1, At, B1); PG8_BAR; PG8_SCHED;
;             PG8_LDA(At, 1, 1); PG8_STAGE(PG8_SB(1, 0), b3, voffB); PG8_STAGE(PG8_SB(1, 1), b3 + hstepB, voffB); PG8_STAGE(PG8_SA(1, 0), a3, voffA);
;             PG8_WAIT_V(8); PG8_WAIT_L(0); PG8_BAR; PG8_MMA(1, 0, At, B0); PG8_MMA(1, 1, At, B1); PG8_BAR; PG8_SCHED;
;         }
;         if constexpr (ALIGN_EPI) { if (wr == 0) PG8_BAR; }
	ds_read_b128 v[122:125], v240
	ds_read_b128 v[126:129], v240 offset:1024
	ds_read_b128 v[182:185], v240 offset:2048
	ds_read_b128 v[216:219], v240 offset:3072
	ds_read_b128 v[220:223], v244
	ds_read_b128 v[224:227], v244 offset:1024
	ds_read_b128 v[240:243], v244 offset:2048
	ds_read_b128 v[244:247], v244 offset:3072
	s_add_u32 s44, s46, 0x100000
	s_addc_u32 s45, s47, 0
	s_mov_b32 m0, s70
	v_lshl_add_u64 v[0:1], s[44:45], 0, v[136:137]
	ds_read_b128 v[16:19], v143 offset:32768
	ds_read_b128 v[20:23], v143 offset:33792
	ds_read_b128 v[62:65], v143 offset:34816
	ds_read_b128 v[106:109], v143 offset:35840
	ds_read_b128 v[110:113], v143 offset:36864
	ds_read_b128 v[248:251], v143 offset:37888
	ds_read_b128 v[144:147], v143 offset:38912
	ds_read_b128 v[204:207], v143 offset:39936
	global_load_lds_dwordx4 v[0:1], off
	v_lshl_add_u64 v[0:1], s[44:45], 0, v[132:133]
	s_mov_b32 m0, s71
	s_nop 0
	global_load_lds_dwordx4 v[0:1], off
	s_waitcnt vmcnt(8)
	s_waitcnt lgkmcnt(0)
	s_barrier
	s_setprio 1
	s_waitcnt lgkmcnt(0)
	v_mfma_f32_16x16x32_bf16 v[0:3], v[122:125], v[16:19], v[66:69]
	v_mfma_f32_16x16x32_bf16 v[50:53], v[126:129], v[20:23], v[0:3]
	v_mfma_f32_16x16x32_bf16 v[0:3], v[182:185], v[16:19], v[70:73]
	v_mfma_f32_16x16x32_bf16 v[54:57], v[216:219], v[20:23], v[0:3]
	v_mfma_f32_16x16x32_bf16 v[0:3], v[122:125], v[62:65], v[74:77]
	v_mfma_f32_16x16x32_bf16 v[24:27], v[126:129], v[106:109], v[0:3]
	v_mfma_f32_16x16x32_bf16 v[0:3], v[182:185], v[62:65], v[78:81]
	v_mfma_f32_16x16x32_bf16 v[28:31], v[216:219], v[106:109], v[0:3]
	v_mfma_f32_16x16x32_bf16 v[0:3], v[122:125], v[110:113], v[82:85]
	v_mfma_f32_16x16x32_bf16 v[8:11], v[126:129], v[248:251], v[0:3]
	v_mfma_f32_16x16x32_bf16 v[0:3], v[182:185], v[110:113], v[86:89]
	v_mfma_f32_16x16x32_bf16 v[12:15], v[216:219], v[248:251], v[0:3]
	v_mfma_f32_16x16x32_bf16 v[0:3], v[122:125], v[144:147], v[90:93]
	v_mfma_f32_16x16x32_bf16 v[4:7], v[182:185], v[144:147], v[94:97]
	v_mfma_f32_16x16x32_bf16 v[0:3], v[126:129], v[204:207], v[0:3]
	v_mfma_f32_16x16x32_bf16 v[4:7], v[216:219], v[204:207], v[4:7]
	v_mfma_f32_16x16x32_bf16 v[66:69], v[220:223], v[16:19], v[98:101]
	v_mfma_f32_16x16x32_bf16 v[16:19], v[240:243], v[16:19], v[34:37]
	v_mfma_f32_16x16x32_bf16 v[94:97], v[244:247], v[20:23], v[16:19]
	v_mfma_f32_16x16x32_bf16 v[16:19], v[220:223], v[62:65], v[38:41]
	v_mfma_f32_16x16x32_bf16 v[90:93], v[224:227], v[20:23], v[66:69]
	v_mfma_f32_16x16x32_bf16 v[66:69], v[224:227], v[106:109], v[16:19]
	v_mfma_f32_16x16x32_bf16 v[16:19], v[240:243], v[62:65], v[42:45]
	v_mfma_f32_16x16x32_bf16 v[70:73], v[244:247], v[106:109], v[16:19]
	v_mfma_f32_16x16x32_bf16 v[16:19], v[220:223], v[110:113], v[46:49]
	v_mfma_f32_16x16x32_bf16 v[42:45], v[224:227], v[248:251], v[16:19]
	v_mfma_f32_16x16x32_bf16 v[16:19], v[240:243], v[110:113], v[186:189]
	v_mfma_f32_16x16x32_bf16 v[46:49], v[244:247], v[248:251], v[16:19]
	v_mfma_f32_16x16x32_bf16 v[16:19], v[220:223], v[144:147], v[190:193]
	v_mfma_f32_16x16x32_bf16 v[20:23], v[240:243], v[144:147], v[58:61]
	v_mfma_f32_16x16x32_bf16 v[16:19], v[224:227], v[204:207], v[16:19]
	v_mfma_f32_16x16x32_bf16 v[20:23], v[244:247], v[204:207], v[20:23]
	s_setprio 0
	s_barrier
	s_mov_b32 m0, s85
	v_lshl_add_u64 v[34:35], v[214:215], 0, s[60:61]
	s_add_u32 s42, s42, 0x100080
	ds_read_b128 v[74:77], v143 offset:49152
	ds_read_b128 v[78:81], v143 offset:50176
	ds_read_b128 v[98:101], v143 offset:51200
	ds_read_b128 v[144:147], v143 offset:52224
	ds_read_b128 v[186:189], v143 offset:53248
	ds_read_b128 v[190:193], v143 offset:54272
	ds_read_b128 v[204:207], v143 offset:55296
	ds_read_b128 v[248:251], v143 offset:56320
	global_load_lds_dwordx4 v[34:35], off
	v_lshl_add_u64 v[34:35], v[252:253], 0, s[60:61]
	s_mov_b32 m0, s82
	s_addc_u32 s43, s43, 0
	global_load_lds_dwordx4 v[34:35], off
	v_lshl_add_u64 v[34:35], s[42:43], 0, v[134:135]
	s_mov_b32 m0, s48
	s_nop 0
	global_load_lds_dwordx4 v[34:35], off
	v_lshl_add_u64 v[34:35], s[42:43], 0, v[130:131]
	s_mov_b32 m0, s49
	s_nop 0
	global_load_lds_dwordx4 v[34:35], off
	v_lshl_add_u64 v[34:35], v[154:155], 0, s[60:61]
	s_mov_b32 m0, s74
	s_nop 0
	global_load_lds_dwordx4 v[34:35], off
	v_lshl_add_u64 v[34:35], v[156:157], 0, s[60:61]
	s_mov_b32 m0, s75
	s_nop 0
	global_load_lds_dwordx4 v[34:35], off
	s_waitcnt vmcnt(8)
	s_waitcnt lgkmcnt(0)
	s_barrier
	s_setprio 1
	s_waitcnt lgkmcnt(0)
	v_mfma_f32_16x16x32_bf16 v[34:37], v[122:125], v[74:77], v[148:151]
	v_mfma_f32_16x16x32_bf16 v[106:109], v[126:129], v[78:81], v[34:37]
	v_mfma_f32_16x16x32_bf16 v[34:37], v[182:185], v[74:77], v[158:161]
	v_mfma_f32_16x16x32_bf16 v[110:113], v[216:219], v[78:81], v[34:37]
	v_mfma_f32_16x16x32_bf16 v[34:37], v[122:125], v[98:101], v[162:165]
	v_mfma_f32_16x16x32_bf16 v[82:85], v[126:129], v[144:147], v[34:37]
	v_mfma_f32_16x16x32_bf16 v[34:37], v[182:185], v[98:101], v[166:169]
	v_mfma_f32_16x16x32_bf16 v[86:89], v[216:219], v[144:147], v[34:37]
	v_mfma_f32_16x16x32_bf16 v[34:37], v[122:125], v[186:189], v[170:173]
	v_mfma_f32_16x16x32_bf16 v[58:61], v[126:129], v[190:193], v[34:37]
	v_mfma_f32_16x16x32_bf16 v[34:37], v[182:185], v[186:189], v[174:177]
	v_mfma_f32_16x16x32_bf16 v[62:65], v[216:219], v[190:193], v[34:37]
	v_mfma_f32_16x16x32_bf16 v[34:37], v[122:125], v[204:207], v[228:231]
	v_mfma_f32_16x16x32_bf16 v[38:41], v[182:185], v[204:207], v[114:117]
	v_mfma_f32_16x16x32_bf16 v[34:37], v[126:129], v[248:251], v[34:37]
	v_mfma_f32_16x16x32_bf16 v[38:41], v[216:219], v[248:251], v[38:41]
	v_mfma_f32_16x16x32_bf16 v[114:117], v[220:223], v[74:77], v[118:121]
	v_mfma_f32_16x16x32_bf16 v[74:77], v[240:243], v[74:77], v[232:235]
	v_mfma_f32_16x16x32_bf16 v[126:129], v[244:247], v[78:81], v[74:77]
	v_mfma_f32_16x16x32_bf16 v[74:77], v[220:223], v[98:101], v[236:239]
	v_mfma_f32_16x16x32_bf16 v[122:125], v[224:227], v[78:81], v[114:117]
	v_mfma_f32_16x16x32_bf16 v[114:117], v[224:227], v[144:147], v[74:77]
	v_mfma_f32_16x16x32_bf16 v[74:77], v[240:243], v[98:101], v[194:197]
	v_mfma_f32_16x16x32_bf16 v[118:121], v[244:247], v[144:147], v[74:77]
	v_mfma_f32_16x16x32_bf16 v[74:77], v[220:223], v[186:189], v[198:201]
	v_mfma_f32_16x16x32_bf16 v[98:101], v[224:227], v[190:193], v[74:77]
	v_mfma_f32_16x16x32_bf16 v[74:77], v[240:243], v[186:189], v[102:105]
	v_mfma_f32_16x16x32_bf16 v[102:105], v[244:247], v[190:193], v[74:77]
	v_mfma_f32_16x16x32_bf16 v[74:77], v[220:223], v[204:207], v[208:211]
	v_mfma_f32_16x16x32_bf16 v[78:81], v[240:243], v[204:207], v[178:181]
	v_mfma_f32_16x16x32_bf16 v[74:77], v[224:227], v[248:251], v[74:77]
	v_mfma_f32_16x16x32_bf16 v[78:81], v[244:247], v[248:251], v[78:81]
	s_setprio 0
	s_barrier
	s_andn2_b64 vcc, exec, s[12:13]
	s_cbranch_vccnz .LBB0_2120
	s_barrier

; #define PG8_STAGE(bufoff, gbase, voff) do { _Pragma("unroll") for (int _i = 0; _i < 2; ++_i) \
;         __builtin_amdgcn_global_load_lds((const unsigned*)((const char*)(gbase) + (voff)[_i]), (PG8_LAS unsigned*)(lds + (bufoff) + ldsw + _i * 8192), 16, 0, 0); } while (0)
; #define PG8_LDA(dst, b, h) do { _Pragma("unroll") for (int m = 0; m < 4; ++m) _Pragma("unroll") for (int k = 0; k < 2; ++k) dst[m][k] = *(const PG8_LAS bf16x8*)(lds + PG8_SA(b, h) + aoff + m * 2048 + k * 1024); } while (0)
; #define PG8_LDB(dst, b, h) do { _Pragma("unroll") for (int n = 0; n < 2; ++n) _Pragma("unroll") for (int k = 0; k < 2; ++k) dst[n][k] = *(const PG8_LAS bf16x8*)(lds + PG8_SB(b, h) + boff + n * 2048 + k * 1024); } while (0)
; #define PG8_WAIT_V(n) asm volatile("s_waitcnt vmcnt(" #n ")" ::: "memory")
; #define PG8_WAIT_L(n) asm volatile("s_waitcnt lgkmcnt(" #n ")" ::: "memory")
; #define PG8_BAR __builtin_amdgcn_s_barrier()
; #define PG8_SCHED __builtin_amdgcn_sched_barrier(0)
; template <class Epi, bool ALIGN_EPI = true>
; __device__ __forceinline__ void gemm_phase(PG8_LAS unsigned char* lds, const Gemm g, const StaticOrder& S, const Epi& E) {
;     ...
;             PG8_LDB(B0, 0, 0); PG8_LDB(B1, 0, 1); PG8_SCHED; PG8_LDA(At, 0, 0); PG8_STAGE(PG8_SA(1, 1), a1 + hstepA, voffA);
;             PG8_WAIT_V(8); PG8_WAIT_L(0); PG8_BAR; PG8_MMA(0, 0, At, B0); PG8_MMA(0, 1, At, B1); PG8_BAR; PG8_SCHED;
;             PG8_LDA(At, 0, 1); PG8_STAGE(PG8_SB(0, 0), b2, voffB); PG8_STAGE(PG8_SB(0, 1), b2 + hstepB, voffB); PG8_STAGE(PG8_SA(0, 0), a2, voffA);
.Lrot_2132:
	ds_read_b128 v[142:145], v32
	ds_read_b128 v[148:151], v32 offset:1024
	ds_read_b128 v[158:161], v32 offset:2048
	ds_read_b128 v[168:171], v32 offset:3072
	v_add_u32_e32 v32, s43, v165
	ds_read_b128 v[172:175], v32
	ds_read_b128 v[176:179], v32 offset:1024
	ds_read_b128 v[180:183], v32 offset:2048
	ds_read_b128 v[184:187], v32 offset:3072
	v_lshl_add_u64 v[146:147], s[48:49], 0, v[138:139]
	s_add_i32 m0, s75, 0xc000
	ds_read_b128 v[188:191], v167
	ds_read_b128 v[192:195], v167 offset:1024
	ds_read_b128 v[196:199], v167 offset:2048
	ds_read_b128 v[208:211], v167 offset:3072
	ds_read_b128 v[216:219], v167 offset:4096
	ds_read_b128 v[220:223], v167 offset:5120
	ds_read_b128 v[224:227], v167 offset:6144
	ds_read_b128 v[228:231], v167 offset:7168
	global_load_lds_dwordx4 v[146:147], off
	v_lshl_add_u64 v[146:147], s[48:49], 0, v[140:141]
	s_add_i32 m0, s75, 0xe000
	s_nop 0
	global_load_lds_dwordx4 v[146:147], off
	s_waitcnt vmcnt(8)
	s_waitcnt lgkmcnt(0)
	s_barrier
	s_setprio 1
	s_waitcnt lgkmcnt(0)
	v_mfma_f32_16x16x32_bf16 v[126:129], v[142:145], v[188:191], v[126:129]
	v_mfma_f32_16x16x32_bf16 v[122:125], v[158:161], v[188:191], v[122:125]
	v_mfma_f32_16x16x32_bf16 v[110:113], v[142:145], v[196:199], v[110:113]
	v_mfma_f32_16x16x32_bf16 v[106:109], v[158:161], v[196:199], v[106:109]
	v_mfma_f32_16x16x32_bf16 v[94:97], v[142:145], v[216:219], v[94:97]
	v_mfma_f32_16x16x32_bf16 v[90:93], v[158:161], v[216:219], v[90:93]
	v_mfma_f32_16x16x32_bf16 v[78:81], v[142:145], v[224:227], v[78:81]
	v_mfma_f32_16x16x32_bf16 v[74:77], v[158:161], v[224:227], v[74:77]
	v_mfma_f32_16x16x32_bf16 v[126:129], v[148:151], v[192:195], v[126:129]
	v_mfma_f32_16x16x32_bf16 v[122:125], v[168:171], v[192:195], v[122:125]
	v_mfma_f32_16x16x32_bf16 v[110:113], v[148:151], v[208:211], v[110:113]
	v_mfma_f32_16x16x32_bf16 v[106:109], v[168:171], v[208:211], v[106:109]
	v_mfma_f32_16x16x32_bf16 v[94:97], v[148:151], v[220:223], v[94:97]
	v_mfma_f32_16x16x32_bf16 v[90:93], v[168:171], v[220:223], v[90:93]
	v_mfma_f32_16x16x32_bf16 v[78:81], v[148:151], v[228:231], v[78:81]
	v_mfma_f32_16x16x32_bf16 v[74:77], v[168:171], v[228:231], v[74:77]
	v_mfma_f32_16x16x32_bf16 v[118:121], v[172:175], v[188:191], v[118:121]
	v_mfma_f32_16x16x32_bf16 v[114:117], v[180:183], v[188:191], v[114:117]
	v_mfma_f32_16x16x32_bf16 v[102:105], v[172:175], v[196:199], v[102:105]
	v_mfma_f32_16x16x32_bf16 v[98:101], v[180:183], v[196:199], v[98:101]
	v_mfma_f32_16x16x32_bf16 v[86:89], v[172:175], v[216:219], v[86:89]
	v_mfma_f32_16x16x32_bf16 v[82:85], v[180:183], v[216:219], v[82:85]
	v_mfma_f32_16x16x32_bf16 v[70:73], v[172:175], v[224:227], v[70:73]
	v_mfma_f32_16x16x32_bf16 v[66:69], v[180:183], v[224:227], v[66:69]
	v_mfma_f32_16x16x32_bf16 v[118:121], v[176:179], v[192:195], v[118:121]
	v_mfma_f32_16x16x32_bf16 v[114:117], v[184:187], v[192:195], v[114:117]
	v_mfma_f32_16x16x32_bf16 v[102:105], v[176:179], v[208:211], v[102:105]
	v_mfma_f32_16x16x32_bf16 v[98:101], v[184:187], v[208:211], v[98:101]
	v_mfma_f32_16x16x32_bf16 v[86:89], v[176:179], v[220:223], v[86:89]
	v_mfma_f32_16x16x32_bf16 v[82:85], v[184:187], v[220:223], v[82:85]
	v_mfma_f32_16x16x32_bf16 v[70:73], v[176:179], v[228:231], v[70:73]
	v_mfma_f32_16x16x32_bf16 v[66:69], v[184:187], v[228:231], v[66:69]
	s_setprio 0
	s_barrier
	s_add_i32 s93, s93, s74
	v_lshl_add_u64 v[146:147], s[50:51], 0, v[132:133]
	s_mov_b32 m0, s93
	ds_read_b128 v[188:191], v167 offset:16384
	ds_read_b128 v[192:195], v167 offset:17408
	ds_read_b128 v[196:199], v167 offset:18432
	ds_read_b128 v[208:211], v167 offset:19456
	ds_read_b128 v[216:219], v167 offset:20480
	ds_read_b128 v[220:223], v167 offset:21504
	ds_read_b128 v[224:227], v167 offset:22528
	ds_read_b128 v[228:231], v167 offset:23552
	global_load_lds_dwordx4 v[146:147], off
	s_add_i32 m0, s93, 0x2000
	s_add_u32 s94, s50, 0x100000
	v_lshl_add_u64 v[162:163], s[50:51], 0, v[136:137]
	s_addc_u32 s95, s51, 0
	s_add_i32 s43, s43, s74
	global_load_lds_dwordx4 v[162:163], off
	v_lshl_add_u64 v[200:201], s[94:95], 0, v[132:133]
	s_mov_b32 m0, s43
	v_lshl_add_u64 v[204:205], s[52:53], 0, v[134:135]
	global_load_lds_dwordx4 v[200:201], off
	v_lshl_add_u64 v[200:201], s[94:95], 0, v[136:137]
	s_add_i32 m0, s43, 0x2000
	s_nop 0
	global_load_lds_dwordx4 v[200:201], off
	v_lshl_add_u64 v[200:201], s[52:53], 0, v[130:131]
	s_mov_b32 m0, s75
	s_nop 0
	global_load_lds_dwordx4 v[200:201], off
	s_mov_b32 m0, s76
	s_nop 0
	global_load_lds_dwordx4 v[204:205], off
	s_waitcnt vmcnt(8)
	s_waitcnt lgkmcnt(0)
	s_barrier
; #define PG8_STAGE(bufoff, gbase, voff) do { _Pragma("unroll") for (int _i = 0; _i < 2; ++_i) \
;         __builtin_amdgcn_global_load_lds((const unsigned*)((const char*)(gbase) + (voff)[_i]), (PG8_LAS unsigned*)(lds + (bufoff) + ldsw + _i * 8192), 16, 0, 0); } while (0)
; #define PG8_LDA(dst, b, h) do { _Pragma("unroll") for (int m = 0; m < 4; ++m) _Pragma("unroll") for (int k = 0; k < 2; ++k) dst[m][k] = *(const PG8_LAS bf16x8*)(lds + PG8_SA(b, h) + aoff + m * 2048 + k * 1024); } while (0)
; #define PG8_LDB(dst, b, h) do { _Pragma("unroll") for (int n = 0; n < 2; ++n) _Pragma("unroll") for (int k = 0; k < 2; ++k) dst[n][k] = *(const PG8_LAS bf16x8*)(lds + PG8_SB(b, h) + boff + n * 2048 + k * 1024); } while (0)
; #define PG8_WAIT_V(n) asm volatile("s_waitcnt vmcnt(" #n ")" ::: "memory")
; #define PG8_WAIT_L(n) asm volatile("s_waitcnt lgkmcnt(" #n ")" ::: "memory")
; #define PG8_BAR __builtin_amdgcn_s_barrier()
; #define PG8_SCHED __builtin_amdgcn_sched_barrier(0)
; template <class Epi, bool ALIGN_EPI = true>
; __device__ __forceinline__ void gemm_phase(PG8_LAS unsigned char* lds, const Gemm g, const StaticOrder& S, const Epi& E) {
;     ...
;             PG8_WAIT_V(8); PG8_WAIT_L(0); PG8_BAR; PG8_MMA(1, 0, At, B0); PG8_MMA(1, 1, At, B1); PG8_BAR; PG8_SCHED;
;             PG8_LDB(B0, 1, 0); PG8_LDB(B1, 1, 1); PG8_SCHED; PG8_LDA(At, 1, 0); PG8_STAGE(PG8_SA(0, 1), a2 + hstepA, voffA);
;             PG8_WAIT_V(8); PG8_WAIT_L(0); PG8_BAR; PG8_MMA(0, 0, At, B0); PG8_MMA(0, 1, At, B1); PG8_BAR; PG8_SCHED;
	s_setprio 1
	s_waitcnt lgkmcnt(0)
	v_mfma_f32_16x16x32_bf16 v[62:65], v[142:145], v[188:191], v[62:65]
	v_mfma_f32_16x16x32_bf16 v[58:61], v[158:161], v[188:191], v[58:61]
	v_mfma_f32_16x16x32_bf16 v[46:49], v[142:145], v[196:199], v[46:49]
	v_mfma_f32_16x16x32_bf16 v[42:45], v[158:161], v[196:199], v[42:45]
	v_mfma_f32_16x16x32_bf16 v[28:31], v[142:145], v[216:219], v[28:31]
	v_mfma_f32_16x16x32_bf16 v[24:27], v[158:161], v[216:219], v[24:27]
	v_mfma_f32_16x16x32_bf16 v[12:15], v[142:145], v[224:227], v[12:15]
	v_mfma_f32_16x16x32_bf16 v[8:11], v[158:161], v[224:227], v[8:11]
	v_mfma_f32_16x16x32_bf16 v[62:65], v[148:151], v[192:195], v[62:65]
	v_mfma_f32_16x16x32_bf16 v[58:61], v[168:171], v[192:195], v[58:61]
	v_mfma_f32_16x16x32_bf16 v[46:49], v[148:151], v[208:211], v[46:49]
	v_mfma_f32_16x16x32_bf16 v[42:45], v[168:171], v[208:211], v[42:45]
	v_mfma_f32_16x16x32_bf16 v[28:31], v[148:151], v[220:223], v[28:31]
	v_mfma_f32_16x16x32_bf16 v[24:27], v[168:171], v[220:223], v[24:27]
	v_mfma_f32_16x16x32_bf16 v[12:15], v[148:151], v[228:231], v[12:15]
	v_mfma_f32_16x16x32_bf16 v[8:11], v[168:171], v[228:231], v[8:11]
	v_mfma_f32_16x16x32_bf16 v[54:57], v[172:175], v[188:191], v[54:57]
	v_mfma_f32_16x16x32_bf16 v[50:53], v[180:183], v[188:191], v[50:53]
	v_mfma_f32_16x16x32_bf16 v[38:41], v[172:175], v[196:199], v[38:41]
	v_mfma_f32_16x16x32_bf16 v[34:37], v[180:183], v[196:199], v[34:37]
	v_mfma_f32_16x16x32_bf16 v[20:23], v[172:175], v[216:219], v[20:23]
	v_mfma_f32_16x16x32_bf16 v[16:19], v[180:183], v[216:219], v[16:19]
	v_mfma_f32_16x16x32_bf16 v[4:7], v[172:175], v[224:227], v[4:7]
	v_mfma_f32_16x16x32_bf16 v[0:3], v[180:183], v[224:227], v[0:3]
	v_mfma_f32_16x16x32_bf16 v[54:57], v[176:179], v[192:195], v[54:57]
	v_mfma_f32_16x16x32_bf16 v[50:53], v[184:187], v[192:195], v[50:53]
	v_mfma_f32_16x16x32_bf16 v[38:41], v[176:179], v[208:211], v[38:41]
	v_mfma_f32_16x16x32_bf16 v[34:37], v[184:187], v[208:211], v[34:37]
	v_mfma_f32_16x16x32_bf16 v[20:23], v[176:179], v[220:223], v[20:23]
	v_mfma_f32_16x16x32_bf16 v[16:19], v[184:187], v[220:223], v[16:19]
	v_mfma_f32_16x16x32_bf16 v[4:7], v[176:179], v[228:231], v[4:7]
	v_mfma_f32_16x16x32_bf16 v[0:3], v[184:187], v[228:231], v[0:3]
	s_setprio 0
	s_barrier
	s_add_i32 s43, 0, 0x18000
	v_add_u32_e32 v32, s43, v165
	s_add_i32 s93, 0, 0x1c000
	ds_read_b128 v[142:145], v32
	ds_read_b128 v[148:151], v32 offset:1024
	ds_read_b128 v[158:161], v32 offset:2048
	ds_read_b128 v[168:171], v32 offset:3072
	v_add_u32_e32 v32, s93, v165
	ds_read_b128 v[172:175], v32
	ds_read_b128 v[176:179], v32 offset:1024
	ds_read_b128 v[180:183], v32 offset:2048
	ds_read_b128 v[184:187], v32 offset:3072
	s_add_u32 s52, s52, 0x100000
	s_addc_u32 s53, s53, 0
	s_mov_b32 m0, s77
	v_lshl_add_u64 v[206:207], s[52:53], 0, v[130:131]
	ds_read_b128 v[188:191], v167 offset:32768
	ds_read_b128 v[192:195], v167 offset:33792
	ds_read_b128 v[196:199], v167 offset:34816
	ds_read_b128 v[208:211], v167 offset:35840
	ds_read_b128 v[216:219], v167 offset:36864
	ds_read_b128 v[220:223], v167 offset:37888
	ds_read_b128 v[224:227], v167 offset:38912
	ds_read_b128 v[228:231], v167 offset:39936
	global_load_lds_dwordx4 v[206:207], off
	v_lshl_add_u64 v[206:207], s[52:53], 0, v[134:135]
	s_mov_b32 m0, s82
	s_nop 0
	global_load_lds_dwordx4 v[206:207], off
	s_waitcnt vmcnt(8)
	s_waitcnt lgkmcnt(0)
	s_barrier
	s_setprio 1
	s_waitcnt lgkmcnt(0)
	v_mfma_f32_16x16x32_bf16 v[126:129], v[142:145], v[188:191], v[126:129]
	v_mfma_f32_16x16x32_bf16 v[122:125], v[158:161], v[188:191], v[122:125]
	v_mfma_f32_16x16x32_bf16 v[110:113], v[142:145], v[196:199], v[110:113]
	v_mfma_f32_16x16x32_bf16 v[106:109], v[158:161], v[196:199], v[106:109]
	v_mfma_f32_16x16x32_bf16 v[94:97], v[142:145], v[216:219], v[94:97]
	v_mfma_f32_16x16x32_bf16 v[90:93], v[158:161], v[216:219], v[90:93]
	v_mfma_f32_16x16x32_bf16 v[78:81], v[142:145], v[224:227], v[78:81]
	v_mfma_f32_16x16x32_bf16 v[74:77], v[158:161], v[224:227], v[74:77]
	v_mfma_f32_16x16x32_bf16 v[126:129], v[148:151], v[192:195], v[126:129]
	v_mfma_f32_16x16x32_bf16 v[122:125], v[168:171], v[192:195], v[122:125]
	v_mfma_f32_16x16x32_bf16 v[110:113], v[148:151], v[208:211], v[110:113]
	v_mfma_f32_16x16x32_bf16 v[106:109], v[168:171], v[208:211], v[106:109]
	v_mfma_f32_16x16x32_bf16 v[94:97], v[148:151], v[220:223], v[94:97]
	v_mfma_f32_16x16x32_bf16 v[90:93], v[168:171], v[220:223], v[90:93]
	v_mfma_f32_16x16x32_bf16 v[78:81], v[148:151], v[228:231], v[78:81]
	v_mfma_f32_16x16x32_bf16 v[74:77], v[168:171], v[228:231], v[74:77]
	v_mfma_f32_16x16x32_bf16 v[118:121], v[172:175], v[188:191], v[118:121]
	v_mfma_f32_16x16x32_bf16 v[114:117], v[180:183], v[188:191], v[114:117]
	v_mfma_f32_16x16x32_bf16 v[102:105], v[172:175], v[196:199], v[102:105]
	v_mfma_f32_16x16x32_bf16 v[98:101], v[180:183], v[196:199], v[98:101]
	v_mfma_f32_16x16x32_bf16 v[86:89], v[172:175], v[216:219], v[86:89]
	v_mfma_f32_16x16x32_bf16 v[82:85], v[180:183], v[216:219], v[82:85]
	v_mfma_f32_16x16x32_bf16 v[70:73], v[172:175], v[224:227], v[70:73]
	v_mfma_f32_16x16x32_bf16 v[66:69], v[180:183], v[224:227], v[66:69]
	v_mfma_f32_16x16x32_bf16 v[118:121], v[176:179], v[192:195], v[118:121]
	v_mfma_f32_16x16x32_bf16 v[114:117], v[184:187], v[192:195], v[114:117]
	v_mfma_f32_16x16x32_bf16 v[102:105], v[176:179], v[208:211], v[102:105]
	v_mfma_f32_16x16x32_bf16 v[98:101], v[184:187], v[208:211], v[98:101]
	v_mfma_f32_16x16x32_bf16 v[86:89], v[176:179], v[220:223], v[86:89]
	v_mfma_f32_16x16x32_bf16 v[82:85], v[184:187], v[220:223], v[82:85]
	v_mfma_f32_16x16x32_bf16 v[70:73], v[176:179], v[228:231], v[70:73]
	v_mfma_f32_16x16x32_bf16 v[66:69], v[184:187], v[228:231], v[66:69]
	s_setprio 0
	s_barrier
; #define PG8_STAGE(bufoff, gbase, voff) do { _Pragma("unroll") for (int _i = 0; _i < 2; ++_i) \
;         __builtin_amdgcn_global_load_lds((const unsigned*)((const char*)(gbase) + (voff)[_i]), (PG8_LAS unsigned*)(lds + (bufoff) + ldsw + _i * 8192), 16, 0, 0); } while (0)
; #define PG8_LDA(dst, b, h) do { _Pragma("unroll") for (int m = 0; m < 4; ++m) _Pragma("unroll") for (int k = 0; k < 2; ++k) dst[m][k] = *(const PG8_LAS bf16x8*)(lds + PG8_SA(b, h) + aoff + m * 2048 + k * 1024); } while (0)
; #define PG8_LDB(dst, b, h) do { _Pragma("unroll") for (int n = 0; n < 2; ++n) _Pragma("unroll") for (int k = 0; k < 2; ++k) dst[n][k] = *(const PG8_LAS bf16x8*)(lds + PG8_SB(b, h) + boff + n * 2048 + k * 1024); } while (0)
; #define PG8_BAR __builtin_amdgcn_s_barrier()
; template <class Epi, bool ALIGN_EPI = true>
; __device__ __forceinline__ void gemm_phase(PG8_LAS unsigned char* lds, const Gemm g, const StaticOrder& S, const Epi& E) {
;     ...
;         for (int t = 0; t < nt; t += 2) {
;             const bool last = (t == nt - 2);
;             const char* a1 = cA + (size_t)(t + 1) * kstep;
;             const char* a2 = last ? nA : cA + (size_t)(t + 2) * kstep; const char* b2 = last ? nB : cB + (size_t)(t + 2) * kstep;
;             const char* a3 = a2 + kstep; const char* b3 = b2 + kstep;
;             PG8_LDB(B0, 0, 0); PG8_LDB(B1, 0, 1); PG8_SCHED; PG8_LDA(At, 0, 0); PG8_STAGE(PG8_SA(1, 1), a1 + hstepA, voffA);
;             PG8_WAIT_V(8); PG8_WAIT_L(0); PG8_BAR; PG8_MMA(0, 0, At, B0); PG8_MMA(0, 1, At, B1); PG8_BAR; PG8_SCHED;
;             PG8_LDA(At, 0, 1); PG8_STAGE(PG8_SB(0, 0), b2, voffB); PG8_STAGE(PG8_SB(0, 1), b2 + hstepB, voffB); PG8_STAGE(PG8_SA(0, 0), a2, voffA);
;             PG8_WAIT_V(8); PG8_WAIT_L(0); PG8_BAR; PG8_MMA(1, 0, At, B0); PG8_MMA(1, 1, At, B1); PG8_BAR; PG8_SCHED;
;             PG8_LDB(B0, 1, 0); PG8_LDB(B1, 1, 1); PG8_SCHED; PG8_LDA(At, 1, 0); PG8_STAGE(PG8_SA(0, 1), a2 + hstepA, voffA);
;             PG8_WAIT_V(8); PG8_WAIT_L(0); PG8_BAR; PG8_MMA(0, 0, At, B0); PG8_MMA(0, 1, At, B1); PG8_BAR; PG8_SCHED;
;             PG8_LDA(At, 1, 1); PG8_STAGE(PG8_SB(1, 0), b3, voffB); PG8_STAGE(PG8_SB(1, 1), b3 + hstepB, voffB); PG8_STAGE(PG8_SA(1, 0), a3, voffA);
;             PG8_WAIT_V(8); PG8_WAIT_L(0); PG8_BAR; PG8_MMA(1, 0, At, B0); PG8_MMA(1, 1, At, B1); PG8_BAR; PG8_SCHED;
;         }
;         if constexpr (ALIGN_EPI) { if (wr == 0) PG8_BAR; }
	s_add_i32 s43, s43, s74
	v_lshl_add_u64 v[146:147], v[146:147], 0, s[60:61]
	s_mov_b32 m0, s43
	ds_read_b128 v[188:191], v167 offset:49152
	ds_read_b128 v[192:195], v167 offset:50176
	ds_read_b128 v[196:199], v167 offset:51200
	ds_read_b128 v[208:211], v167 offset:52224
	ds_read_b128 v[216:219], v167 offset:53248
	ds_read_b128 v[220:223], v167 offset:54272
	ds_read_b128 v[224:227], v167 offset:55296
	ds_read_b128 v[228:231], v167 offset:56320
	global_load_lds_dwordx4 v[146:147], off
	s_add_i32 m0, s43, 0x2000
	s_add_u32 s50, s50, 0x100080
	v_lshl_add_u64 v[146:147], v[162:163], 0, s[60:61]
	s_addc_u32 s51, s51, 0
	s_add_i32 s43, s93, s74
	global_load_lds_dwordx4 v[146:147], off
	v_lshl_add_u64 v[146:147], s[50:51], 0, v[132:133]
	s_mov_b32 m0, s43
	s_nop 0
	global_load_lds_dwordx4 v[146:147], off
	v_lshl_add_u64 v[146:147], s[50:51], 0, v[136:137]
	s_add_i32 m0, s43, 0x2000
	s_nop 0
	global_load_lds_dwordx4 v[146:147], off
	v_lshl_add_u64 v[146:147], v[200:201], 0, s[60:61]
	s_mov_b32 m0, s83
	s_nop 0
	global_load_lds_dwordx4 v[146:147], off
	v_lshl_add_u64 v[146:147], v[204:205], 0, s[60:61]
	s_mov_b32 m0, s85
	s_nop 0
	global_load_lds_dwordx4 v[146:147], off
	s_add_i32 s41, s41, 2
	s_add_u32 s48, s48, 0x100
	s_addc_u32 s49, s49, 0
	s_add_u32 s7, s7, 0x100
	s_addc_u32 s9, s9, 0
	s_add_u32 s43, s48, 0xfff00080
	s_addc_u32 s50, s49, -1
	s_add_i32 s93, 0, 0x10000
	s_cmp_eq_u32 s41, 60
	s_cselect_b32 s53, s45, s50
	s_cselect_b32 s52, s44, s43
	v_add_u32_e32 v32, s93, v165
	s_cselect_b32 s51, s47, s9
	s_cselect_b32 s50, s46, s7
	s_add_i32 s43, 0, 0x14000
	s_cmp_gt_u32 s41, 61
	s_waitcnt vmcnt(8)
	s_waitcnt lgkmcnt(0)
	s_barrier
	s_setprio 1
	s_waitcnt lgkmcnt(0)
	v_mfma_f32_16x16x32_bf16 v[62:65], v[142:145], v[188:191], v[62:65]
	v_mfma_f32_16x16x32_bf16 v[58:61], v[158:161], v[188:191], v[58:61]
	v_mfma_f32_16x16x32_bf16 v[46:49], v[142:145], v[196:199], v[46:49]
	v_mfma_f32_16x16x32_bf16 v[42:45], v[158:161], v[196:199], v[42:45]
	v_mfma_f32_16x16x32_bf16 v[28:31], v[142:145], v[216:219], v[28:31]
	v_mfma_f32_16x16x32_bf16 v[24:27], v[158:161], v[216:219], v[24:27]
	v_mfma_f32_16x16x32_bf16 v[12:15], v[142:145], v[224:227], v[12:15]
	v_mfma_f32_16x16x32_bf16 v[8:11], v[158:161], v[224:227], v[8:11]
	v_mfma_f32_16x16x32_bf16 v[62:65], v[148:151], v[192:195], v[62:65]
	v_mfma_f32_16x16x32_bf16 v[58:61], v[168:171], v[192:195], v[58:61]
	v_mfma_f32_16x16x32_bf16 v[46:49], v[148:151], v[208:211], v[46:49]
	v_mfma_f32_16x16x32_bf16 v[42:45], v[168:171], v[208:211], v[42:45]
	v_mfma_f32_16x16x32_bf16 v[28:31], v[148:151], v[220:223], v[28:31]
	v_mfma_f32_16x16x32_bf16 v[24:27], v[168:171], v[220:223], v[24:27]
	v_mfma_f32_16x16x32_bf16 v[12:15], v[148:151], v[228:231], v[12:15]
	v_mfma_f32_16x16x32_bf16 v[8:11], v[168:171], v[228:231], v[8:11]
	v_mfma_f32_16x16x32_bf16 v[54:57], v[172:175], v[188:191], v[54:57]
	v_mfma_f32_16x16x32_bf16 v[50:53], v[180:183], v[188:191], v[50:53]
	v_mfma_f32_16x16x32_bf16 v[38:41], v[172:175], v[196:199], v[38:41]
	v_mfma_f32_16x16x32_bf16 v[34:37], v[180:183], v[196:199], v[34:37]
	v_mfma_f32_16x16x32_bf16 v[20:23], v[172:175], v[216:219], v[20:23]
	v_mfma_f32_16x16x32_bf16 v[16:19], v[180:183], v[216:219], v[16:19]
	v_mfma_f32_16x16x32_bf16 v[4:7], v[172:175], v[224:227], v[4:7]
	v_mfma_f32_16x16x32_bf16 v[0:3], v[180:183], v[224:227], v[0:3]
	v_mfma_f32_16x16x32_bf16 v[54:57], v[176:179], v[192:195], v[54:57]
	v_mfma_f32_16x16x32_bf16 v[50:53], v[184:187], v[192:195], v[50:53]
	v_mfma_f32_16x16x32_bf16 v[38:41], v[176:179], v[208:211], v[38:41]
	v_mfma_f32_16x16x32_bf16 v[34:37], v[184:187], v[208:211], v[34:37]
	v_mfma_f32_16x16x32_bf16 v[20:23], v[176:179], v[220:223], v[20:23]
	v_mfma_f32_16x16x32_bf16 v[16:19], v[184:187], v[220:223], v[16:19]
	v_mfma_f32_16x16x32_bf16 v[4:7], v[176:179], v[228:231], v[4:7]
	v_mfma_f32_16x16x32_bf16 v[0:3], v[184:187], v[228:231], v[0:3]
	s_setprio 0
	s_barrier
	s_cbranch_scc0 .Lrot_2132
	s_and_b64 vcc, exec, s[38:39]
	s_cbranch_vccz .LBB0_2135
	s_barrier
